# LDS-DMA persistent K-loops + LDS-staged coalesced epilogues for FF1, P1a (sigmoid/silu/identity), P1b; silu uses v_rcp_f32 like the baseline sigmoid
# speedup vs baseline: 1.0909x; 1.0462x over previous
; DEV void phase_p1(const Params& p, int g, char* smem) {
;   const int L = g ? 8192 : 4096;
;   const u16* H = (const u16*)(p.out + (size_t)g * NTOK * D);
;   const u16* WinT = (const u16*)(p.ws + OFF_WIN);
;   u16* PHG = (u16*)(p.ws + OFF_PHG);
;   u16* GT = (u16*)(p.ws + OFF_GT);
;   u16* UHY = (u16*)(p.ws + OFF_UHY);
;   {
;     GemmPipe gp;
;     gp.primed = false;
;     for (int iter = 0;; ++iter) {
;       int mt, nt, mtn, ntn;
;       if (!tile_map(iter, 128, 18, mt, nt)) break;
;       const bool more = tile_map(iter + 1, 128, 18, mtn, ntn);
;       if (!more) { mtn = mt; ntn = nt; }
;       Acc acc;
;       acc_zero(acc);
;       const int m0 = mt * 256, n0 = nt * 256;
;       RowLoader al{H, 1024}, bl{WinT + (size_t)1536 * 1024, 1024};
;       gemm_mainloop_p(acc, al, bl, m0, n0, mtn * 256, ntn * 256, 1024, smem, gp);
;       gp.primed = more;
.LBB0_259:
	s_xor_b64 s[0:1], s[0:1], -1
	v_writelane_b32 v252, s0, 8
	s_ashr_i32 s39, s38, 31
	s_mov_b64 s[2:3], 0
	v_writelane_b32 v252, s1, 9
	s_lshl_b64 s[0:1], s[38:39], 27
	s_add_u32 s64, s78, s0
	v_writelane_b32 v252, s0, 10
	s_addc_u32 s65, s79, s1
	s_mov_b32 s6, s85
	v_writelane_b32 v252, s1, 11
	v_readlane_b32 s19, v249, 52
	v_readlane_b32 s22, v249, 53
	s_branch .LBB0_263
.LBB0_261:
	s_mov_b64 s[4:5], 0

; template <class AL, class BL>
; DEV void gemm_mainloop_p(Acc& acc, const AL& al, const BL& bl, int m0, int n0, int m0n, int n0n, int K, char* lds,
;                          GemmPipe& gp) {
;   const int tid = tidx_full();
;   const int wave = tid >> 6, lane = tid & 63;
;   const int wm = (wave >> 2) * 128, wn = (wave & 3) * 64;
;   const int lr = lane & 31, lh = lane >> 5;
;   const int nk = K / BK;
;   if (!gp.primed) {
;     gp.ra = al.load(tid, m0, 0);
;     gp.rb = bl.load(tid, n0, 0);
;     __syncthreads();
;     al.store(tid, lds, gp.ra);
;     bl.store(tid, lds + TILE_BYTES, gp.rb);
;     gp.ra = al.load(tid, m0, BK);
;     gp.rb = bl.load(tid, n0, BK);
;     __syncthreads();
;   }
; DEV void phase_p1(const Params& p, int g, char* smem) {
;     ...
;       Acc acc;
;       acc_zero(acc);
;       const int m0 = mt * 256, n0 = nt * 256;
;       RowLoader al{H, 1024}, bl{WinT + (size_t)1536 * 1024, 1024};
;       gemm_mainloop_p(acc, al, bl, m0, n0, mtn * 256, ntn * 256, 1024, smem, gp);
.LBB0_278:
	s_and_b64 vcc, exec, s[2:3]
	s_lshl_b32 s5, s7, 8
	s_lshl_b32 s4, s8, 8
	v_lshrrev_b32_e32 v149, 6, v202
	v_and_b32_e32 v148, 63, v202
	s_nop 0
	v_readfirstlane_b32 s13, v149
	v_lshrrev_b32_e32 v150, 3, v148
	v_lshl_add_u32 v150, v149, 5, v150
	v_and_b32_e32 v151, 7, v148
	v_lshrrev_b32_e32 v128, 4, v148
	v_xor_b32_e32 v151, v128, v151
	v_lshlrev_b32_e32 v151, 4, v151
	s_lshl_b32 s13, s13, 12
	v_add_u32_e32 v128, s5, v150
	v_lshlrev_b32_e32 v128, 11, v128
	v_add_u32_e32 v128, v128, v151
	v_add_u32_e32 v129, 0x4000, v128
	v_add_u32_e32 v130, 0x8000, v128
	v_add_u32_e32 v131, 0xc000, v128
	v_xor_b32_e32 v129, 0x40, v129
	v_xor_b32_e32 v131, 0x40, v131
	v_add_u32_e32 v132, s4, v150
	v_lshlrev_b32_e32 v132, 11, v132
	v_add_u32_e32 v132, v132, v151
	v_add_u32_e32 v133, 0x4000, v132
	v_add_u32_e32 v134, 0x8000, v132
	v_add_u32_e32 v135, 0xc000, v132
	v_xor_b32_e32 v133, 0x40, v133
	v_xor_b32_e32 v135, 0x40, v135
	v_lshrrev_b32_e32 v144, 1, v148
	v_and_b32_e32 v144, 7, v144
	v_lshrrev_b32_e32 v145, 5, v148
	v_xor_b32_e32 v144, v144, v145
	v_lshlrev_b32_e32 v144, 4, v144
	v_and_b32_e32 v145, 31, v148
	v_lshlrev_b32_e32 v145, 7, v145
	v_lshrrev_b32_e32 v136, 2, v149
	v_lshl_add_u32 v136, v136, 14, v145
	v_and_b32_e32 v140, 3, v149
	v_lshl_add_u32 v140, v140, 13, v145
	v_add_u32_e32 v140, 0x10000, v140
	v_xor_b32_e32 v139, 0x60, v144
	v_add_u32_e32 v139, v136, v139
	v_xor_b32_e32 v138, 0x40, v144
	v_add_u32_e32 v138, v136, v138
	v_xor_b32_e32 v137, 0x20, v144
	v_add_u32_e32 v137, v136, v137
	v_add_u32_e32 v136, v136, v144
	v_xor_b32_e32 v143, 0x60, v144
	v_add_u32_e32 v143, v140, v143
	v_xor_b32_e32 v142, 0x40, v144
	v_add_u32_e32 v142, v140, v142
	v_xor_b32_e32 v141, 0x20, v144
	v_add_u32_e32 v141, v140, v141
	v_add_u32_e32 v140, v140, v144
	s_mov_b64 s[14:15], s[64:65]
	s_mov_b64 s[16:17], s[24:25]
	s_cbranch_vccnz .Lp1a_primed
	s_add_u32 m0, s13, 0x0
	s_nop 0
	global_load_lds_dwordx4 v128, s[14:15]
	s_add_u32 m0, m0, 0x400
	s_nop 0
	global_load_lds_dwordx4 v129, s[14:15]
	s_add_u32 m0, m0, 0x400
	s_nop 0
	global_load_lds_dwordx4 v130, s[14:15]
	s_add_u32 m0, m0, 0x400
	s_nop 0
	global_load_lds_dwordx4 v131, s[14:15]
	s_add_u32 m0, s13, 0x10000
	s_nop 0
	global_load_lds_dwordx4 v132, s[16:17]
	s_add_u32 m0, m0, 0x400
	s_nop 0
	global_load_lds_dwordx4 v133, s[16:17]
	s_add_u32 m0, m0, 0x400
	s_nop 0
	global_load_lds_dwordx4 v134, s[16:17]
	s_add_u32 m0, m0, 0x400
	s_nop 0
	global_load_lds_dwordx4 v135, s[16:17]
.Lp1a_primed:
	s_add_u32 s14, s14, 0x80
	s_addc_u32 s15, s15, 0
	s_add_u32 s16, s16, 0x80
	s_addc_u32 s17, s17, 0
	v_mov_b32_e32 v0, 0
	v_mov_b32_e32 v1, 0
	v_mov_b64_e32 v[2:3], v[0:1]
	v_mov_b64_e32 v[4:5], v[0:1]
	v_mov_b64_e32 v[6:7], v[0:1]
	v_mov_b64_e32 v[8:9], v[0:1]
	v_mov_b64_e32 v[10:11], v[0:1]
	v_mov_b64_e32 v[12:13], v[0:1]
	v_mov_b64_e32 v[14:15], v[0:1]
	v_mov_b64_e32 v[16:17], v[0:1]
	v_mov_b64_e32 v[18:19], v[0:1]
	v_mov_b64_e32 v[20:21], v[0:1]
	v_mov_b64_e32 v[22:23], v[0:1]
	v_mov_b64_e32 v[24:25], v[0:1]
	v_mov_b64_e32 v[26:27], v[0:1]
	v_mov_b64_e32 v[28:29], v[0:1]
	v_mov_b64_e32 v[30:31], v[0:1]
	v_mov_b64_e32 v[32:33], v[0:1]
	v_mov_b64_e32 v[34:35], v[0:1]
	v_mov_b64_e32 v[36:37], v[0:1]
	v_mov_b64_e32 v[38:39], v[0:1]
	v_mov_b64_e32 v[40:41], v[0:1]
	v_mov_b64_e32 v[42:43], v[0:1]
	v_mov_b64_e32 v[44:45], v[0:1]
	v_mov_b64_e32 v[46:47], v[0:1]
	v_mov_b64_e32 v[48:49], v[0:1]
	v_mov_b64_e32 v[50:51], v[0:1]
	v_mov_b64_e32 v[52:53], v[0:1]
	v_mov_b64_e32 v[54:55], v[0:1]
	v_mov_b64_e32 v[56:57], v[0:1]
	v_mov_b64_e32 v[58:59], v[0:1]
	v_mov_b64_e32 v[60:61], v[0:1]
	v_mov_b64_e32 v[62:63], v[0:1]
	v_mov_b64_e32 v[64:65], v[0:1]
	v_mov_b64_e32 v[66:67], v[0:1]
	v_mov_b64_e32 v[68:69], v[0:1]
	v_mov_b64_e32 v[70:71], v[0:1]
	v_mov_b64_e32 v[72:73], v[0:1]
	v_mov_b64_e32 v[74:75], v[0:1]
	v_mov_b64_e32 v[76:77], v[0:1]
	v_mov_b64_e32 v[78:79], v[0:1]
	v_mov_b64_e32 v[80:81], v[0:1]
	v_mov_b64_e32 v[82:83], v[0:1]
	v_mov_b64_e32 v[84:85], v[0:1]
	v_mov_b64_e32 v[86:87], v[0:1]
	v_mov_b64_e32 v[88:89], v[0:1]
	v_mov_b64_e32 v[90:91], v[0:1]
	v_mov_b64_e32 v[92:93], v[0:1]
	v_mov_b64_e32 v[94:95], v[0:1]
	v_mov_b64_e32 v[96:97], v[0:1]
	v_mov_b64_e32 v[98:99], v[0:1]
	v_mov_b64_e32 v[100:101], v[0:1]
	v_mov_b64_e32 v[102:103], v[0:1]
	v_mov_b64_e32 v[104:105], v[0:1]
	v_mov_b64_e32 v[106:107], v[0:1]
	v_mov_b64_e32 v[108:109], v[0:1]
	v_mov_b64_e32 v[110:111], v[0:1]
	v_mov_b64_e32 v[112:113], v[0:1]
	v_mov_b64_e32 v[114:115], v[0:1]
	v_mov_b64_e32 v[116:117], v[0:1]
	v_mov_b64_e32 v[118:119], v[0:1]
	v_mov_b64_e32 v[120:121], v[0:1]
	v_mov_b64_e32 v[122:123], v[0:1]
	v_mov_b64_e32 v[124:125], v[0:1]
	v_mov_b64_e32 v[126:127], v[0:1]
	s_mov_b32 s18, 0
	s_waitcnt vmcnt(0)
	s_barrier
; template <class AL, class BL>
; DEV void gemm_ktile(Acc& acc, const char* A, const char* B, int wm, int wn, int lr, int lh, const AL& al, const BL& bl,
;                     int tid, int m0, int n0, int knext, char* nxt, R4& ra, R4& rb) {
;     ...
; #pragma unroll
;   for (int i = 0; i < 4; ++i) a[0][i] = *(const bf16x8*)(pa + 32 * i * LDSROW);
; #pragma unroll
;   for (int j = 0; j < 2; ++j) b[0][j] = *(const bf16x8*)(pb + 32 * j * LDSROW);
; #pragma unroll
;   for (int ks = 0; ks < 4; ++ks) {
;     const int cur = ks & 1, nx = cur ^ 1;
;     if (ks < 3) {
; #pragma unroll
;       for (int i = 0; i < 4; ++i) a[nx][i] = *(const bf16x8*)(pa + 32 * i * LDSROW + (ks + 1) * 32);
; #pragma unroll
;       for (int j = 0; j < 2; ++j) b[nx][j] = *(const bf16x8*)(pb + 32 * j * LDSROW + (ks + 1) * 32);
;     }
;     __builtin_amdgcn_sched_barrier(0);
; #pragma unroll
;     for (int i = 0; i < 4; ++i)
; #pragma unroll
;       for (int j = 0; j < 2; ++j)
;         acc[i][j] = __builtin_amdgcn_mfma_f32_32x32x16_bf16(a[cur][i], b[cur][j], acc[i][j], 0, 0, 0);
;     __builtin_amdgcn_sched_barrier(0);
;     if (ks == 1) {
;       al.store(tid, nxt, ra);
;       bl.store(tid, nxt + TILE_BYTES, rb);
;       __builtin_amdgcn_sched_barrier(0);
;       ra = al.load(tid, m0, knext);
;       rb = bl.load(tid, n0, knext);
;       __builtin_amdgcn_sched_barrier(0);
;     }
; template <class AL, class BL>
; DEV void gemm_mainloop_p(Acc& acc, const AL& al, const BL& bl, int m0, int n0, int m0n, int n0n, int K, char* lds,
;                          GemmPipe& gp) {
;     ...
;   for (int kt = 0; kt < nk; ++kt) {
;     const char* cur = lds + (kt & 1) * 2 * TILE_BYTES;
;     char* nxt = lds + ((kt + 1) & 1) * 2 * TILE_BYTES;
;     const bool wrap = (kt + 2 >= nk);
;     const int kk = (wrap ? kt + 2 - nk : kt + 2) * BK;
;     const int mr = wrap ? m0n : m0, nr = wrap ? n0n : n0;
;     __builtin_amdgcn_sched_barrier(0);
;     gemm_ktile(acc, cur, cur + TILE_BYTES, wm, wn, lr, lh, al, bl, tid, mr, nr, kk, nxt, gp.ra, gp.rb);
;     __builtin_amdgcn_sched_barrier(0);
;     __syncthreads();
;   }
.Lp1a_kloop:
	s_add_u32 m0, s13, 0x8000
	s_nop 0
	global_load_lds_dwordx4 v128, s[14:15]
	s_add_u32 m0, m0, 0x400
	s_nop 0
	global_load_lds_dwordx4 v129, s[14:15]
	s_add_u32 m0, m0, 0x400
	s_nop 0
	global_load_lds_dwordx4 v130, s[14:15]
	s_add_u32 m0, m0, 0x400
	s_nop 0
	global_load_lds_dwordx4 v131, s[14:15]
	s_add_u32 m0, s13, 0x18000
	s_nop 0
	global_load_lds_dwordx4 v132, s[16:17]
	s_add_u32 m0, m0, 0x400
	s_nop 0
	global_load_lds_dwordx4 v133, s[16:17]
	s_add_u32 m0, m0, 0x400
	s_nop 0
	global_load_lds_dwordx4 v134, s[16:17]
	s_add_u32 m0, m0, 0x400
	s_nop 0
	global_load_lds_dwordx4 v135, s[16:17]
	s_add_u32 s14, s14, 0x80
	s_addc_u32 s15, s15, 0
	s_add_u32 s16, s16, 0x80
	s_addc_u32 s17, s17, 0
	ds_read_b128 v[174:177], v136
	ds_read_b128 v[178:181], v137
	ds_read_b128 v[182:185], v136 offset:4096
	ds_read_b128 v[186:189], v137 offset:4096
	ds_read_b128 v[190:193], v136 offset:8192
	ds_read_b128 v[194:197], v137 offset:8192
	ds_read_b128 v[198:201], v136 offset:12288
	ds_read_b128 v[222:225], v137 offset:12288
	ds_read_b128 v[226:229], v140
	ds_read_b128 v[230:233], v141
	ds_read_b128 v[234:237], v140 offset:4096
	ds_read_b128 v[238:241], v141 offset:4096
	s_waitcnt lgkmcnt(3)
	v_mfma_f32_32x32x16_bf16 v[112:127], v[226:229], v[174:177], v[112:127]
	s_waitcnt lgkmcnt(1)
	v_mfma_f32_32x32x16_bf16 v[96:111], v[234:237], v[174:177], v[96:111]
	v_mfma_f32_32x32x16_bf16 v[80:95], v[226:229], v[182:185], v[80:95]
	v_mfma_f32_32x32x16_bf16 v[64:79], v[234:237], v[182:185], v[64:79]
	v_mfma_f32_32x32x16_bf16 v[48:63], v[226:229], v[190:193], v[48:63]
	v_mfma_f32_32x32x16_bf16 v[32:47], v[234:237], v[190:193], v[32:47]
	v_mfma_f32_32x32x16_bf16 v[16:31], v[226:229], v[198:201], v[16:31]
	v_mfma_f32_32x32x16_bf16 v[0:15], v[234:237], v[198:201], v[0:15]
	ds_read_b128 v[174:177], v138
	ds_read_b128 v[182:185], v138 offset:4096
	ds_read_b128 v[190:193], v138 offset:8192
	ds_read_b128 v[198:201], v138 offset:12288
	ds_read_b128 v[226:229], v142
	ds_read_b128 v[234:237], v142 offset:4096
	v_mfma_f32_32x32x16_bf16 v[112:127], v[230:233], v[178:181], v[112:127]
	s_waitcnt lgkmcnt(6)
	v_mfma_f32_32x32x16_bf16 v[96:111], v[238:241], v[178:181], v[96:111]
	v_mfma_f32_32x32x16_bf16 v[80:95], v[230:233], v[186:189], v[80:95]
	v_mfma_f32_32x32x16_bf16 v[64:79], v[238:241], v[186:189], v[64:79]
	v_mfma_f32_32x32x16_bf16 v[48:63], v[230:233], v[194:197], v[48:63]
	v_mfma_f32_32x32x16_bf16 v[32:47], v[238:241], v[194:197], v[32:47]
	v_mfma_f32_32x32x16_bf16 v[16:31], v[230:233], v[222:225], v[16:31]
	v_mfma_f32_32x32x16_bf16 v[0:15], v[238:241], v[222:225], v[0:15]
	ds_read_b128 v[178:181], v139
	ds_read_b128 v[186:189], v139 offset:4096
	ds_read_b128 v[194:197], v139 offset:8192
	ds_read_b128 v[222:225], v139 offset:12288
	ds_read_b128 v[230:233], v143
	ds_read_b128 v[238:241], v143 offset:4096
	s_waitcnt lgkmcnt(6)
	v_mfma_f32_32x32x16_bf16 v[112:127], v[226:229], v[174:177], v[112:127]
	v_mfma_f32_32x32x16_bf16 v[96:111], v[234:237], v[174:177], v[96:111]
	v_mfma_f32_32x32x16_bf16 v[80:95], v[226:229], v[182:185], v[80:95]
	v_mfma_f32_32x32x16_bf16 v[64:79], v[234:237], v[182:185], v[64:79]
	v_mfma_f32_32x32x16_bf16 v[48:63], v[226:229], v[190:193], v[48:63]
	v_mfma_f32_32x32x16_bf16 v[32:47], v[234:237], v[190:193], v[32:47]
	v_mfma_f32_32x32x16_bf16 v[16:31], v[226:229], v[198:201], v[16:31]
	v_mfma_f32_32x32x16_bf16 v[0:15], v[234:237], v[198:201], v[0:15]
	s_waitcnt lgkmcnt(1)
	v_mfma_f32_32x32x16_bf16 v[112:127], v[230:233], v[178:181], v[112:127]
	s_waitcnt lgkmcnt(0)
	v_mfma_f32_32x32x16_bf16 v[96:111], v[238:241], v[178:181], v[96:111]
	v_mfma_f32_32x32x16_bf16 v[80:95], v[230:233], v[186:189], v[80:95]
	v_mfma_f32_32x32x16_bf16 v[64:79], v[238:241], v[186:189], v[64:79]
	v_mfma_f32_32x32x16_bf16 v[48:63], v[230:233], v[194:197], v[48:63]
	v_mfma_f32_32x32x16_bf16 v[32:47], v[238:241], v[194:197], v[32:47]
	v_mfma_f32_32x32x16_bf16 v[16:31], v[230:233], v[222:225], v[16:31]
	v_mfma_f32_32x32x16_bf16 v[0:15], v[238:241], v[222:225], v[0:15]
	s_waitcnt vmcnt(0)
	s_barrier
	s_cmp_eq_u32 s18, 7
	s_cbranch_scc1 .Lp1a_skipdma
	s_add_u32 m0, s13, 0x0
	s_nop 0
	global_load_lds_dwordx4 v128, s[14:15]
	s_add_u32 m0, m0, 0x400
	s_nop 0
	global_load_lds_dwordx4 v129, s[14:15]
	s_add_u32 m0, m0, 0x400
	s_nop 0
	global_load_lds_dwordx4 v130, s[14:15]
	s_add_u32 m0, m0, 0x400
	s_nop 0
	global_load_lds_dwordx4 v131, s[14:15]
	s_add_u32 m0, s13, 0x10000
	s_nop 0
	global_load_lds_dwordx4 v132, s[16:17]
	s_add_u32 m0, m0, 0x400
	s_nop 0
	global_load_lds_dwordx4 v133, s[16:17]
	s_add_u32 m0, m0, 0x400
	s_nop 0
	global_load_lds_dwordx4 v134, s[16:17]
	s_add_u32 m0, m0, 0x400
	s_nop 0
	global_load_lds_dwordx4 v135, s[16:17]
	s_add_u32 s14, s14, 0x80
	s_addc_u32 s15, s15, 0
	s_add_u32 s16, s16, 0x80
	s_addc_u32 s17, s17, 0
; template <class AL, class BL>
; DEV void gemm_mainloop_p(Acc& acc, const AL& al, const BL& bl, int m0, int n0, int m0n, int n0n, int K, char* lds,
;                          GemmPipe& gp) {
;     ...
;   for (int kt = 0; kt < nk; ++kt) {
;     const char* cur = lds + (kt & 1) * 2 * TILE_BYTES;
;     char* nxt = lds + ((kt + 1) & 1) * 2 * TILE_BYTES;
;     const bool wrap = (kt + 2 >= nk);
;     const int kk = (wrap ? kt + 2 - nk : kt + 2) * BK;
;     const int mr = wrap ? m0n : m0, nr = wrap ? n0n : n0;
;     __builtin_amdgcn_sched_barrier(0);
;     gemm_ktile(acc, cur, cur + TILE_BYTES, wm, wn, lr, lh, al, bl, tid, mr, nr, kk, nxt, gp.ra, gp.rb);
;     __builtin_amdgcn_sched_barrier(0);
;     __syncthreads();
;   }
; DEV void phase_p1(const Params& p, int g, char* smem) {
;     ...
;       int mt, nt, mtn, ntn;
;       if (!tile_map(iter, 128, 18, mt, nt)) break;
;       const bool more = tile_map(iter + 1, 128, 18, mtn, ntn);
;       if (!more) { mtn = mt; ntn = nt; }
;       Acc acc;
;       acc_zero(acc);
;       const int m0 = mt * 256, n0 = nt * 256;
;       RowLoader al{H, 1024}, bl{WinT + (size_t)1536 * 1024, 1024};
;       gemm_mainloop_p(acc, al, bl, m0, n0, mtn * 256, ntn * 256, 1024, smem, gp);
;       gp.primed = more;
.Lp1a_skipdma:
	ds_read_b128 v[174:177], v136 offset:32768
	ds_read_b128 v[178:181], v137 offset:32768
	ds_read_b128 v[182:185], v136 offset:36864
	ds_read_b128 v[186:189], v137 offset:36864
	ds_read_b128 v[190:193], v136 offset:40960
	ds_read_b128 v[194:197], v137 offset:40960
	ds_read_b128 v[198:201], v136 offset:45056
	ds_read_b128 v[222:225], v137 offset:45056
	ds_read_b128 v[226:229], v140 offset:32768
	ds_read_b128 v[230:233], v141 offset:32768
	ds_read_b128 v[234:237], v140 offset:36864
	ds_read_b128 v[238:241], v141 offset:36864
	s_waitcnt lgkmcnt(3)
	v_mfma_f32_32x32x16_bf16 v[112:127], v[226:229], v[174:177], v[112:127]
	s_waitcnt lgkmcnt(1)
	v_mfma_f32_32x32x16_bf16 v[96:111], v[234:237], v[174:177], v[96:111]
	v_mfma_f32_32x32x16_bf16 v[80:95], v[226:229], v[182:185], v[80:95]
	v_mfma_f32_32x32x16_bf16 v[64:79], v[234:237], v[182:185], v[64:79]
	v_mfma_f32_32x32x16_bf16 v[48:63], v[226:229], v[190:193], v[48:63]
	v_mfma_f32_32x32x16_bf16 v[32:47], v[234:237], v[190:193], v[32:47]
	v_mfma_f32_32x32x16_bf16 v[16:31], v[226:229], v[198:201], v[16:31]
	v_mfma_f32_32x32x16_bf16 v[0:15], v[234:237], v[198:201], v[0:15]
	ds_read_b128 v[174:177], v138 offset:32768
	ds_read_b128 v[182:185], v138 offset:36864
	ds_read_b128 v[190:193], v138 offset:40960
	ds_read_b128 v[198:201], v138 offset:45056
	ds_read_b128 v[226:229], v142 offset:32768
	ds_read_b128 v[234:237], v142 offset:36864
	v_mfma_f32_32x32x16_bf16 v[112:127], v[230:233], v[178:181], v[112:127]
	s_waitcnt lgkmcnt(6)
	v_mfma_f32_32x32x16_bf16 v[96:111], v[238:241], v[178:181], v[96:111]
	v_mfma_f32_32x32x16_bf16 v[80:95], v[230:233], v[186:189], v[80:95]
	v_mfma_f32_32x32x16_bf16 v[64:79], v[238:241], v[186:189], v[64:79]
	v_mfma_f32_32x32x16_bf16 v[48:63], v[230:233], v[194:197], v[48:63]
	v_mfma_f32_32x32x16_bf16 v[32:47], v[238:241], v[194:197], v[32:47]
	v_mfma_f32_32x32x16_bf16 v[16:31], v[230:233], v[222:225], v[16:31]
	v_mfma_f32_32x32x16_bf16 v[0:15], v[238:241], v[222:225], v[0:15]
	ds_read_b128 v[178:181], v139 offset:32768
	ds_read_b128 v[186:189], v139 offset:36864
	ds_read_b128 v[194:197], v139 offset:40960
	ds_read_b128 v[222:225], v139 offset:45056
	ds_read_b128 v[230:233], v143 offset:32768
	ds_read_b128 v[238:241], v143 offset:36864
	s_waitcnt lgkmcnt(6)
	v_mfma_f32_32x32x16_bf16 v[112:127], v[226:229], v[174:177], v[112:127]
	v_mfma_f32_32x32x16_bf16 v[96:111], v[234:237], v[174:177], v[96:111]
	v_mfma_f32_32x32x16_bf16 v[80:95], v[226:229], v[182:185], v[80:95]
	v_mfma_f32_32x32x16_bf16 v[64:79], v[234:237], v[182:185], v[64:79]
	v_mfma_f32_32x32x16_bf16 v[48:63], v[226:229], v[190:193], v[48:63]
	v_mfma_f32_32x32x16_bf16 v[32:47], v[234:237], v[190:193], v[32:47]
	v_mfma_f32_32x32x16_bf16 v[16:31], v[226:229], v[198:201], v[16:31]
	v_mfma_f32_32x32x16_bf16 v[0:15], v[234:237], v[198:201], v[0:15]
	s_waitcnt lgkmcnt(1)
	v_mfma_f32_32x32x16_bf16 v[112:127], v[230:233], v[178:181], v[112:127]
	s_waitcnt lgkmcnt(0)
	v_mfma_f32_32x32x16_bf16 v[96:111], v[238:241], v[178:181], v[96:111]
	v_mfma_f32_32x32x16_bf16 v[80:95], v[230:233], v[186:189], v[80:95]
	v_mfma_f32_32x32x16_bf16 v[64:79], v[238:241], v[186:189], v[64:79]
	v_mfma_f32_32x32x16_bf16 v[48:63], v[230:233], v[194:197], v[48:63]
	v_mfma_f32_32x32x16_bf16 v[32:47], v[238:241], v[194:197], v[32:47]
	v_mfma_f32_32x32x16_bf16 v[16:31], v[230:233], v[222:225], v[16:31]
	v_mfma_f32_32x32x16_bf16 v[0:15], v[238:241], v[222:225], v[0:15]
	s_add_i32 s18, s18, 1
	s_waitcnt vmcnt(0)
	s_cmp_lg_u32 s18, 8
	s_barrier
	s_cbranch_scc1 .Lp1a_kloop
	s_and_b64 vcc, exec, s[0:1]
	s_cbranch_vccz .Lp1a_nomore
	s_lshl_b32 s9, s11, 8
	s_lshl_b32 s10, s12, 8
	v_add_u32_e32 v128, s9, v150
	v_lshlrev_b32_e32 v128, 11, v128
	v_add_u32_e32 v128, v128, v151
	v_add_u32_e32 v129, 0x4000, v128
	v_add_u32_e32 v130, 0x8000, v128
	v_add_u32_e32 v131, 0xc000, v128
	v_xor_b32_e32 v129, 0x40, v129
	v_xor_b32_e32 v131, 0x40, v131
	v_add_u32_e32 v132, s10, v150
	v_lshlrev_b32_e32 v132, 11, v132
	v_add_u32_e32 v132, v132, v151
	v_add_u32_e32 v133, 0x4000, v132
	v_add_u32_e32 v134, 0x8000, v132
	v_add_u32_e32 v135, 0xc000, v132
	v_xor_b32_e32 v133, 0x40, v133
	v_xor_b32_e32 v135, 0x40, v135
	s_mov_b64 s[14:15], s[64:65]
	s_mov_b64 s[16:17], s[24:25]
	s_add_u32 m0, s13, 0x0
	s_nop 0
	global_load_lds_dwordx4 v128, s[14:15]
	s_add_u32 m0, m0, 0x400
	s_nop 0
	global_load_lds_dwordx4 v129, s[14:15]
	s_add_u32 m0, m0, 0x400
	s_nop 0
	global_load_lds_dwordx4 v130, s[14:15]
	s_add_u32 m0, m0, 0x400
	s_nop 0
	global_load_lds_dwordx4 v131, s[14:15]
	s_add_u32 m0, s13, 0x10000
	s_nop 0
	global_load_lds_dwordx4 v132, s[16:17]
	s_add_u32 m0, m0, 0x400
	s_nop 0
	global_load_lds_dwordx4 v133, s[16:17]
	s_add_u32 m0, m0, 0x400
	s_nop 0
	global_load_lds_dwordx4 v134, s[16:17]
	s_add_u32 m0, m0, 0x400
	s_nop 0
	global_load_lds_dwordx4 v135, s[16:17]
; DEV u16 f2bf(float f) { return (u16)(pack2(f, f) & 0xffffu); }
; DEV float silu_f(float x) { return x / (1.f + __expf(-x)); }
; template <class F>
; DEV void acc_foreach(Acc& acc, int m0, int n0, F f) {
;   asm volatile("s_nop 7\n\ts_nop 7\n\ts_nop 3" ::: "memory");
;   const int tid = tidx_full();
;   const int wave = tid >> 6, lane = tid & 63;
;   const int wm = (wave >> 2) * 128, wn = (wave & 3) * 64;
;   const int lr = lane & 31, lh = lane >> 5;
; #pragma unroll
;   for (int i = 0; i < 4; ++i)
; #pragma unroll
;     for (int j = 0; j < 2; ++j)
; #pragma unroll
;       for (int r = 0; r < 16; ++r) {
;         const int m = m0 + wm + 32 * i + (r & 3) + 8 * (r >> 2) + 4 * lh;
;         const int n = n0 + wn + 32 * j + lr;
;         float v = acc[i][j][r];
;         f(m, n, v);
;         acc[i][j][r] = v;
;       }
; }
; DEV void phase_p1(const Params& p, int g, char* smem) {
;     ...
;       if (n0 < 2560) {
;         const bool dosilu = (n0 < 512) || (n0 >= 2048);
;         acc_foreach(acc, m0, n0, [&](int m, int n, float& v) {
;           const float o = dosilu ? silu_f(v) : v;
;           PHG[(size_t)m * 2560 + n] = f2bf(o);
;         });
.Lp1a_nomore:
	s_cmp_gt_i32 s8, 9
	s_cbranch_scc1 .Lp1a_gt
	s_cmp_lt_u32 s8, 2
	s_cbranch_scc1 .Lp1a_silu
	s_cmp_gt_u32 s8, 7
	s_cbranch_scc1 .Lp1a_silu
	s_nop 7
	s_nop 7
	s_nop 3
	v_and_b32_e32 v160, 63, v202
	v_lshrrev_b32_e32 v161, 6, v202
	v_and_b32_e32 v164, 3, v161
	v_lshlrev_b32_e32 v164, 13, v164
	v_add_u32_e32 v164, 0x8000, v164
	v_lshrrev_b32_e32 v160, 2, v161
	v_lshl_add_u32 v164, v160, 16, v164
	v_and_b32_e32 v160, 63, v202
	v_and_b32_e32 v166, 31, v160
	v_lshrrev_b32_e32 v167, 5, v160
	v_lshlrev_b32_e32 v168, 7, v166
	v_lshl_add_u32 v168, v167, 3, v168
	v_add_u32_e32 v168, v164, v168
	v_and_b32_e32 v166, 7, v166
	v_lshlrev_b32_e32 v166, 4, v166
	v_add_u32_e32 v170, v168, v166
	v_xor_b32_e32 v167, 0x10, v166
	v_add_u32_e32 v171, v168, v167
	v_xor_b32_e32 v167, 0x20, v166
	v_add_u32_e32 v172, v168, v167
	v_xor_b32_e32 v167, 0x30, v166
	v_add_u32_e32 v173, v168, v167
	v_xor_b32_e32 v167, 0x40, v166
	v_add_u32_e32 v174, v168, v167
	v_xor_b32_e32 v167, 0x50, v166
	v_add_u32_e32 v175, v168, v167
	v_xor_b32_e32 v167, 0x60, v166
	v_add_u32_e32 v176, v168, v167
	v_xor_b32_e32 v167, 0x70, v166
	v_add_u32_e32 v177, v168, v167
	v_lshrrev_b32_e32 v166, 3, v160
	v_and_b32_e32 v167, 7, v160
	v_lshrrev_b32_e32 v169, 2, v161
	v_lshl_add_u32 v169, v169, 7, v166
	v_add_u32_e32 v169, s5, v169
	v_mul_u32_u24_e32 v169, 0x1400, v169
	v_and_b32_e32 v168, 3, v161
	v_lshlrev_b32_e32 v168, 3, v168
	v_add_u32_e32 v168, v168, v167
	v_lshl_add_u32 v169, v168, 4, v169
	s_lshl_b32 s100, s4, 1
	v_add_u32_e32 v169, s100, v169
	v_xor_b32_e32 v167, v166, v167
	v_lshlrev_b32_e32 v167, 4, v167
	v_lshl_add_u32 v168, v166, 7, v167
	v_add_u32_e32 v168, v164, v168
	v_cvt_pk_bf16_f32 v112, v112, v113
	v_cvt_pk_bf16_f32 v113, v114, v115
	ds_write_b64 v170, v[112:113]
	v_cvt_pk_bf16_f32 v116, v116, v117
	v_cvt_pk_bf16_f32 v117, v118, v119
	ds_write_b64 v171, v[116:117]
	v_cvt_pk_bf16_f32 v120, v120, v121
	v_cvt_pk_bf16_f32 v121, v122, v123
	ds_write_b64 v172, v[120:121]
	v_cvt_pk_bf16_f32 v124, v124, v125
	v_cvt_pk_bf16_f32 v125, v126, v127
	ds_write_b64 v173, v[124:125]
	v_cvt_pk_bf16_f32 v96, v96, v97
	v_cvt_pk_bf16_f32 v97, v98, v99
	ds_write_b64 v174, v[96:97]
	v_cvt_pk_bf16_f32 v100, v100, v101
	v_cvt_pk_bf16_f32 v101, v102, v103
	ds_write_b64 v175, v[100:101]
	v_cvt_pk_bf16_f32 v104, v104, v105
	v_cvt_pk_bf16_f32 v105, v106, v107
	ds_write_b64 v176, v[104:105]
	v_cvt_pk_bf16_f32 v108, v108, v109
	v_cvt_pk_bf16_f32 v109, v110, v111
	ds_write_b64 v177, v[108:109]
	v_cvt_pk_bf16_f32 v80, v80, v81
	v_cvt_pk_bf16_f32 v81, v82, v83
	ds_write_b64 v170, v[80:81] offset:4096
	v_cvt_pk_bf16_f32 v84, v84, v85
	v_cvt_pk_bf16_f32 v85, v86, v87
	ds_write_b64 v171, v[84:85] offset:4096
	v_cvt_pk_bf16_f32 v88, v88, v89
	v_cvt_pk_bf16_f32 v89, v90, v91
	ds_write_b64 v172, v[88:89] offset:4096
	v_cvt_pk_bf16_f32 v92, v92, v93
	v_cvt_pk_bf16_f32 v93, v94, v95
	ds_write_b64 v173, v[92:93] offset:4096
	v_cvt_pk_bf16_f32 v64, v64, v65
	v_cvt_pk_bf16_f32 v65, v66, v67
	ds_write_b64 v174, v[64:65] offset:4096
	v_cvt_pk_bf16_f32 v68, v68, v69
	v_cvt_pk_bf16_f32 v69, v70, v71
	ds_write_b64 v175, v[68:69] offset:4096
	v_cvt_pk_bf16_f32 v72, v72, v73
	v_cvt_pk_bf16_f32 v73, v74, v75
	ds_write_b64 v176, v[72:73] offset:4096
	v_cvt_pk_bf16_f32 v76, v76, v77
	v_cvt_pk_bf16_f32 v77, v78, v79
	ds_write_b64 v177, v[76:77] offset:4096
	s_waitcnt lgkmcnt(0)
	ds_read_b128 v[96:99], v168
	ds_read_b128 v[100:103], v168 offset:1024
	ds_read_b128 v[104:107], v168 offset:2048
	ds_read_b128 v[108:111], v168 offset:3072
	ds_read_b128 v[112:115], v168 offset:4096
	ds_read_b128 v[116:119], v168 offset:5120
	ds_read_b128 v[120:123], v168 offset:6144
	ds_read_b128 v[124:127], v168 offset:7168
	s_waitcnt lgkmcnt(7)
	global_store_dwordx4 v169, v[96:99], s[56:57]
	v_add_u32_e32 v169, 0xa000, v169
	s_waitcnt lgkmcnt(6)
	global_store_dwordx4 v169, v[100:103], s[56:57]
	v_add_u32_e32 v169, 0xa000, v169
	s_waitcnt lgkmcnt(5)
	global_store_dwordx4 v169, v[104:107], s[56:57]
	v_add_u32_e32 v169, 0xa000, v169
	s_waitcnt lgkmcnt(4)
	global_store_dwordx4 v169, v[108:111], s[56:57]
	v_add_u32_e32 v169, 0xa000, v169
	s_waitcnt lgkmcnt(3)
	global_store_dwordx4 v169, v[112:115], s[56:57]
	v_add_u32_e32 v169, 0xa000, v169
	s_waitcnt lgkmcnt(2)
	global_store_dwordx4 v169, v[116:119], s[56:57]
	v_add_u32_e32 v169, 0xa000, v169
	s_waitcnt lgkmcnt(1)
	global_store_dwordx4 v169, v[120:123], s[56:57]
	v_add_u32_e32 v169, 0xa000, v169
	s_waitcnt lgkmcnt(0)
	global_store_dwordx4 v169, v[124:127], s[56:57]
	v_add_u32_e32 v169, 0xa000, v169
	v_cvt_pk_bf16_f32 v48, v48, v49
	v_cvt_pk_bf16_f32 v49, v50, v51
	ds_write_b64 v170, v[48:49]
	v_cvt_pk_bf16_f32 v52, v52, v53
	v_cvt_pk_bf16_f32 v53, v54, v55
	ds_write_b64 v171, v[52:53]
	v_cvt_pk_bf16_f32 v56, v56, v57
	v_cvt_pk_bf16_f32 v57, v58, v59
	ds_write_b64 v172, v[56:57]
	v_cvt_pk_bf16_f32 v60, v60, v61
	v_cvt_pk_bf16_f32 v61, v62, v63
	ds_write_b64 v173, v[60:61]
	v_cvt_pk_bf16_f32 v32, v32, v33
	v_cvt_pk_bf16_f32 v33, v34, v35
	ds_write_b64 v174, v[32:33]
	v_cvt_pk_bf16_f32 v36, v36, v37
	v_cvt_pk_bf16_f32 v37, v38, v39
	ds_write_b64 v175, v[36:37]
	v_cvt_pk_bf16_f32 v40, v40, v41
	v_cvt_pk_bf16_f32 v41, v42, v43
	ds_write_b64 v176, v[40:41]
	v_cvt_pk_bf16_f32 v44, v44, v45
	v_cvt_pk_bf16_f32 v45, v46, v47
	ds_write_b64 v177, v[44:45]
	v_cvt_pk_bf16_f32 v16, v16, v17
	v_cvt_pk_bf16_f32 v17, v18, v19
	ds_write_b64 v170, v[16:17] offset:4096
	v_cvt_pk_bf16_f32 v20, v20, v21
	v_cvt_pk_bf16_f32 v21, v22, v23
	ds_write_b64 v171, v[20:21] offset:4096
	v_cvt_pk_bf16_f32 v24, v24, v25
	v_cvt_pk_bf16_f32 v25, v26, v27
	ds_write_b64 v172, v[24:25] offset:4096
	v_cvt_pk_bf16_f32 v28, v28, v29
	v_cvt_pk_bf16_f32 v29, v30, v31
	ds_write_b64 v173, v[28:29] offset:4096
	v_cvt_pk_bf16_f32 v0, v0, v1
	v_cvt_pk_bf16_f32 v1, v2, v3
	ds_write_b64 v174, v[0:1] offset:4096
	v_cvt_pk_bf16_f32 v4, v4, v5
	v_cvt_pk_bf16_f32 v5, v6, v7
	ds_write_b64 v175, v[4:5] offset:4096
	v_cvt_pk_bf16_f32 v8, v8, v9
	v_cvt_pk_bf16_f32 v9, v10, v11
	ds_write_b64 v176, v[8:9] offset:4096
	v_cvt_pk_bf16_f32 v12, v12, v13
	v_cvt_pk_bf16_f32 v13, v14, v15
	ds_write_b64 v177, v[12:13] offset:4096
	s_waitcnt lgkmcnt(0)
; DEV u16 f2bf(float f) { return (u16)(pack2(f, f) & 0xffffu); }
; DEV float silu_f(float x) { return x / (1.f + __expf(-x)); }
; DEV void phase_p1(const Params& p, int g, char* smem) {
;     ...
;       if (n0 < 2560) {
;         const bool dosilu = (n0 < 512) || (n0 >= 2048);
;         acc_foreach(acc, m0, n0, [&](int m, int n, float& v) {
;           const float o = dosilu ? silu_f(v) : v;
;           PHG[(size_t)m * 2560 + n] = f2bf(o);
;         });
	ds_read_b128 v[64:67], v168
	ds_read_b128 v[68:71], v168 offset:1024
	ds_read_b128 v[72:75], v168 offset:2048
	ds_read_b128 v[76:79], v168 offset:3072
	ds_read_b128 v[80:83], v168 offset:4096
	ds_read_b128 v[84:87], v168 offset:5120
	ds_read_b128 v[88:91], v168 offset:6144
	ds_read_b128 v[92:95], v168 offset:7168
	s_waitcnt lgkmcnt(7)
	global_store_dwordx4 v169, v[64:67], s[56:57]
	v_add_u32_e32 v169, 0xa000, v169
	s_waitcnt lgkmcnt(6)
	global_store_dwordx4 v169, v[68:71], s[56:57]
	v_add_u32_e32 v169, 0xa000, v169
	s_waitcnt lgkmcnt(5)
	global_store_dwordx4 v169, v[72:75], s[56:57]
	v_add_u32_e32 v169, 0xa000, v169
	s_waitcnt lgkmcnt(4)
	global_store_dwordx4 v169, v[76:79], s[56:57]
	v_add_u32_e32 v169, 0xa000, v169
	s_waitcnt lgkmcnt(3)
	global_store_dwordx4 v169, v[80:83], s[56:57]
	v_add_u32_e32 v169, 0xa000, v169
	s_waitcnt lgkmcnt(2)
	global_store_dwordx4 v169, v[84:87], s[56:57]
	v_add_u32_e32 v169, 0xa000, v169
	s_waitcnt lgkmcnt(1)
	global_store_dwordx4 v169, v[88:91], s[56:57]
	v_add_u32_e32 v169, 0xa000, v169
	s_waitcnt lgkmcnt(0)
	s_barrier
	global_store_dwordx4 v169, v[92:95], s[56:57]
	v_add_u32_e32 v169, 0xa000, v169
	s_branch .LBB0_261
.Lp1a_silu:
	s_nop 7
	s_nop 7
	s_nop 3
	v_and_b32_e32 v160, 63, v202
	v_lshrrev_b32_e32 v161, 6, v202
	v_and_b32_e32 v164, 3, v161
	v_lshlrev_b32_e32 v164, 13, v164
	v_add_u32_e32 v164, 0x8000, v164
	v_lshrrev_b32_e32 v160, 2, v161
	v_lshl_add_u32 v164, v160, 16, v164
	v_and_b32_e32 v160, 63, v202
	v_and_b32_e32 v166, 31, v160
	v_lshrrev_b32_e32 v167, 5, v160
	v_lshlrev_b32_e32 v168, 7, v166
	v_lshl_add_u32 v168, v167, 3, v168
	v_add_u32_e32 v168, v164, v168
	v_and_b32_e32 v166, 7, v166
	v_lshlrev_b32_e32 v166, 4, v166
	v_add_u32_e32 v170, v168, v166
	v_xor_b32_e32 v167, 0x10, v166
	v_add_u32_e32 v171, v168, v167
	v_xor_b32_e32 v167, 0x20, v166
	v_add_u32_e32 v172, v168, v167
	v_xor_b32_e32 v167, 0x30, v166
	v_add_u32_e32 v173, v168, v167
	v_xor_b32_e32 v167, 0x40, v166
	v_add_u32_e32 v174, v168, v167
	v_xor_b32_e32 v167, 0x50, v166
	v_add_u32_e32 v175, v168, v167
	v_xor_b32_e32 v167, 0x60, v166
	v_add_u32_e32 v176, v168, v167
	v_xor_b32_e32 v167, 0x70, v166
	v_add_u32_e32 v177, v168, v167
	v_lshrrev_b32_e32 v166, 3, v160
	v_and_b32_e32 v167, 7, v160
	v_lshrrev_b32_e32 v169, 2, v161
	v_lshl_add_u32 v169, v169, 7, v166
	v_add_u32_e32 v169, s5, v169
	v_mul_u32_u24_e32 v169, 0x1400, v169
	v_and_b32_e32 v168, 3, v161
	v_lshlrev_b32_e32 v168, 3, v168
	v_add_u32_e32 v168, v168, v167
	v_lshl_add_u32 v169, v168, 4, v169
	s_lshl_b32 s100, s4, 1
	v_add_u32_e32 v169, s100, v169
	v_xor_b32_e32 v167, v166, v167
	v_lshlrev_b32_e32 v167, 4, v167
	v_lshl_add_u32 v168, v166, 7, v167
	v_add_u32_e32 v168, v164, v168
	v_mul_f32_e32 v178, 0xbfb8aa3b, v112
	v_mul_f32_e32 v179, 0xbfb8aa3b, v113
	v_mul_f32_e32 v180, 0xbfb8aa3b, v114
	v_mul_f32_e32 v181, 0xbfb8aa3b, v115
	v_exp_f32_e32 v178, v178
	v_exp_f32_e32 v179, v179
	v_exp_f32_e32 v180, v180
	v_exp_f32_e32 v181, v181
	v_add_f32_e32 v178, 1.0, v178
	v_add_f32_e32 v179, 1.0, v179
	v_add_f32_e32 v180, 1.0, v180
	v_add_f32_e32 v181, 1.0, v181
	v_rcp_f32_e32 v178, v178
	v_rcp_f32_e32 v179, v179
	v_rcp_f32_e32 v180, v180
	v_rcp_f32_e32 v181, v181
	v_mul_f32_e32 v112, v112, v178
	v_mul_f32_e32 v113, v113, v179
	v_mul_f32_e32 v114, v114, v180
	v_mul_f32_e32 v115, v115, v181
	v_cvt_pk_bf16_f32 v112, v112, v113
	v_cvt_pk_bf16_f32 v113, v114, v115
	ds_write_b64 v170, v[112:113]
	v_mul_f32_e32 v178, 0xbfb8aa3b, v116
	v_mul_f32_e32 v179, 0xbfb8aa3b, v117
	v_mul_f32_e32 v180, 0xbfb8aa3b, v118
	v_mul_f32_e32 v181, 0xbfb8aa3b, v119
	v_exp_f32_e32 v178, v178
	v_exp_f32_e32 v179, v179
	v_exp_f32_e32 v180, v180
	v_exp_f32_e32 v181, v181
	v_add_f32_e32 v178, 1.0, v178
	v_add_f32_e32 v179, 1.0, v179
	v_add_f32_e32 v180, 1.0, v180
	v_add_f32_e32 v181, 1.0, v181
	v_rcp_f32_e32 v178, v178
	v_rcp_f32_e32 v179, v179
	v_rcp_f32_e32 v180, v180
	v_rcp_f32_e32 v181, v181
	v_mul_f32_e32 v116, v116, v178
	v_mul_f32_e32 v117, v117, v179
	v_mul_f32_e32 v118, v118, v180
	v_mul_f32_e32 v119, v119, v181
	v_cvt_pk_bf16_f32 v116, v116, v117
	v_cvt_pk_bf16_f32 v117, v118, v119
	ds_write_b64 v171, v[116:117]
	v_mul_f32_e32 v178, 0xbfb8aa3b, v120
	v_mul_f32_e32 v179, 0xbfb8aa3b, v121
	v_mul_f32_e32 v180, 0xbfb8aa3b, v122
	v_mul_f32_e32 v181, 0xbfb8aa3b, v123
	v_exp_f32_e32 v178, v178
	v_exp_f32_e32 v179, v179
	v_exp_f32_e32 v180, v180
	v_exp_f32_e32 v181, v181
	v_add_f32_e32 v178, 1.0, v178
	v_add_f32_e32 v179, 1.0, v179
	v_add_f32_e32 v180, 1.0, v180
	v_add_f32_e32 v181, 1.0, v181
	v_rcp_f32_e32 v178, v178
	v_rcp_f32_e32 v179, v179
	v_rcp_f32_e32 v180, v180
	v_rcp_f32_e32 v181, v181
	v_mul_f32_e32 v120, v120, v178
	v_mul_f32_e32 v121, v121, v179
	v_mul_f32_e32 v122, v122, v180
	v_mul_f32_e32 v123, v123, v181
	v_cvt_pk_bf16_f32 v120, v120, v121
	v_cvt_pk_bf16_f32 v121, v122, v123
	ds_write_b64 v172, v[120:121]
	v_mul_f32_e32 v178, 0xbfb8aa3b, v124
	v_mul_f32_e32 v179, 0xbfb8aa3b, v125
	v_mul_f32_e32 v180, 0xbfb8aa3b, v126
	v_mul_f32_e32 v181, 0xbfb8aa3b, v127
	v_exp_f32_e32 v178, v178
	v_exp_f32_e32 v179, v179
	v_exp_f32_e32 v180, v180
	v_exp_f32_e32 v181, v181
	v_add_f32_e32 v178, 1.0, v178
	v_add_f32_e32 v179, 1.0, v179
	v_add_f32_e32 v180, 1.0, v180
	v_add_f32_e32 v181, 1.0, v181
	v_rcp_f32_e32 v178, v178
	v_rcp_f32_e32 v179, v179
	v_rcp_f32_e32 v180, v180
	v_rcp_f32_e32 v181, v181
	v_mul_f32_e32 v124, v124, v178
	v_mul_f32_e32 v125, v125, v179
	v_mul_f32_e32 v126, v126, v180
	v_mul_f32_e32 v127, v127, v181
	v_cvt_pk_bf16_f32 v124, v124, v125
	v_cvt_pk_bf16_f32 v125, v126, v127
	ds_write_b64 v173, v[124:125]
	v_mul_f32_e32 v178, 0xbfb8aa3b, v96
	v_mul_f32_e32 v179, 0xbfb8aa3b, v97
; DEV u16 f2bf(float f) { return (u16)(pack2(f, f) & 0xffffu); }
; DEV float silu_f(float x) { return x / (1.f + __expf(-x)); }
; DEV void phase_p1(const Params& p, int g, char* smem) {
;     ...
;       if (n0 < 2560) {
;         const bool dosilu = (n0 < 512) || (n0 >= 2048);
;         acc_foreach(acc, m0, n0, [&](int m, int n, float& v) {
;           const float o = dosilu ? silu_f(v) : v;
;           PHG[(size_t)m * 2560 + n] = f2bf(o);
;         });
	v_mul_f32_e32 v180, 0xbfb8aa3b, v98
	v_mul_f32_e32 v181, 0xbfb8aa3b, v99
	v_exp_f32_e32 v178, v178
	v_exp_f32_e32 v179, v179
	v_exp_f32_e32 v180, v180
	v_exp_f32_e32 v181, v181
	v_add_f32_e32 v178, 1.0, v178
	v_add_f32_e32 v179, 1.0, v179
	v_add_f32_e32 v180, 1.0, v180
	v_add_f32_e32 v181, 1.0, v181
	v_rcp_f32_e32 v178, v178
	v_rcp_f32_e32 v179, v179
	v_rcp_f32_e32 v180, v180
	v_rcp_f32_e32 v181, v181
	v_mul_f32_e32 v96, v96, v178
	v_mul_f32_e32 v97, v97, v179
	v_mul_f32_e32 v98, v98, v180
	v_mul_f32_e32 v99, v99, v181
	v_cvt_pk_bf16_f32 v96, v96, v97
	v_cvt_pk_bf16_f32 v97, v98, v99
	ds_write_b64 v174, v[96:97]
	v_mul_f32_e32 v178, 0xbfb8aa3b, v100
	v_mul_f32_e32 v179, 0xbfb8aa3b, v101
	v_mul_f32_e32 v180, 0xbfb8aa3b, v102
	v_mul_f32_e32 v181, 0xbfb8aa3b, v103
	v_exp_f32_e32 v178, v178
	v_exp_f32_e32 v179, v179
	v_exp_f32_e32 v180, v180
	v_exp_f32_e32 v181, v181
	v_add_f32_e32 v178, 1.0, v178
	v_add_f32_e32 v179, 1.0, v179
	v_add_f32_e32 v180, 1.0, v180
	v_add_f32_e32 v181, 1.0, v181
	v_rcp_f32_e32 v178, v178
	v_rcp_f32_e32 v179, v179
	v_rcp_f32_e32 v180, v180
	v_rcp_f32_e32 v181, v181
	v_mul_f32_e32 v100, v100, v178
	v_mul_f32_e32 v101, v101, v179
	v_mul_f32_e32 v102, v102, v180
	v_mul_f32_e32 v103, v103, v181
	v_cvt_pk_bf16_f32 v100, v100, v101
	v_cvt_pk_bf16_f32 v101, v102, v103
	ds_write_b64 v175, v[100:101]
	v_mul_f32_e32 v178, 0xbfb8aa3b, v104
	v_mul_f32_e32 v179, 0xbfb8aa3b, v105
	v_mul_f32_e32 v180, 0xbfb8aa3b, v106
	v_mul_f32_e32 v181, 0xbfb8aa3b, v107
	v_exp_f32_e32 v178, v178
	v_exp_f32_e32 v179, v179
	v_exp_f32_e32 v180, v180
	v_exp_f32_e32 v181, v181
	v_add_f32_e32 v178, 1.0, v178
	v_add_f32_e32 v179, 1.0, v179
	v_add_f32_e32 v180, 1.0, v180
	v_add_f32_e32 v181, 1.0, v181
	v_rcp_f32_e32 v178, v178
	v_rcp_f32_e32 v179, v179
	v_rcp_f32_e32 v180, v180
	v_rcp_f32_e32 v181, v181
	v_mul_f32_e32 v104, v104, v178
	v_mul_f32_e32 v105, v105, v179
	v_mul_f32_e32 v106, v106, v180
	v_mul_f32_e32 v107, v107, v181
	v_cvt_pk_bf16_f32 v104, v104, v105
	v_cvt_pk_bf16_f32 v105, v106, v107
	ds_write_b64 v176, v[104:105]
	v_mul_f32_e32 v178, 0xbfb8aa3b, v108
	v_mul_f32_e32 v179, 0xbfb8aa3b, v109
	v_mul_f32_e32 v180, 0xbfb8aa3b, v110
	v_mul_f32_e32 v181, 0xbfb8aa3b, v111
	v_exp_f32_e32 v178, v178
	v_exp_f32_e32 v179, v179
	v_exp_f32_e32 v180, v180
	v_exp_f32_e32 v181, v181
	v_add_f32_e32 v178, 1.0, v178
	v_add_f32_e32 v179, 1.0, v179
	v_add_f32_e32 v180, 1.0, v180
	v_add_f32_e32 v181, 1.0, v181
	v_rcp_f32_e32 v178, v178
	v_rcp_f32_e32 v179, v179
	v_rcp_f32_e32 v180, v180
	v_rcp_f32_e32 v181, v181
	v_mul_f32_e32 v108, v108, v178
	v_mul_f32_e32 v109, v109, v179
	v_mul_f32_e32 v110, v110, v180
	v_mul_f32_e32 v111, v111, v181
	v_cvt_pk_bf16_f32 v108, v108, v109
	v_cvt_pk_bf16_f32 v109, v110, v111
	ds_write_b64 v177, v[108:109]
	v_mul_f32_e32 v178, 0xbfb8aa3b, v80
	v_mul_f32_e32 v179, 0xbfb8aa3b, v81
	v_mul_f32_e32 v180, 0xbfb8aa3b, v82
	v_mul_f32_e32 v181, 0xbfb8aa3b, v83
	v_exp_f32_e32 v178, v178
	v_exp_f32_e32 v179, v179
	v_exp_f32_e32 v180, v180
	v_exp_f32_e32 v181, v181
	v_add_f32_e32 v178, 1.0, v178
	v_add_f32_e32 v179, 1.0, v179
	v_add_f32_e32 v180, 1.0, v180
	v_add_f32_e32 v181, 1.0, v181
	v_rcp_f32_e32 v178, v178
	v_rcp_f32_e32 v179, v179
	v_rcp_f32_e32 v180, v180
	v_rcp_f32_e32 v181, v181
	v_mul_f32_e32 v80, v80, v178
	v_mul_f32_e32 v81, v81, v179
	v_mul_f32_e32 v82, v82, v180
	v_mul_f32_e32 v83, v83, v181
	v_cvt_pk_bf16_f32 v80, v80, v81
	v_cvt_pk_bf16_f32 v81, v82, v83
	ds_write_b64 v170, v[80:81] offset:4096
	v_mul_f32_e32 v178, 0xbfb8aa3b, v84
	v_mul_f32_e32 v179, 0xbfb8aa3b, v85
	v_mul_f32_e32 v180, 0xbfb8aa3b, v86
	v_mul_f32_e32 v181, 0xbfb8aa3b, v87
	v_exp_f32_e32 v178, v178
	v_exp_f32_e32 v179, v179
	v_exp_f32_e32 v180, v180
	v_exp_f32_e32 v181, v181
	v_add_f32_e32 v178, 1.0, v178
	v_add_f32_e32 v179, 1.0, v179
	v_add_f32_e32 v180, 1.0, v180
	v_add_f32_e32 v181, 1.0, v181
	v_rcp_f32_e32 v178, v178
	v_rcp_f32_e32 v179, v179
	v_rcp_f32_e32 v180, v180
	v_rcp_f32_e32 v181, v181
	v_mul_f32_e32 v84, v84, v178
	v_mul_f32_e32 v85, v85, v179
	v_mul_f32_e32 v86, v86, v180
	v_mul_f32_e32 v87, v87, v181
	v_cvt_pk_bf16_f32 v84, v84, v85
	v_cvt_pk_bf16_f32 v85, v86, v87
	ds_write_b64 v171, v[84:85] offset:4096
	v_mul_f32_e32 v178, 0xbfb8aa3b, v88
	v_mul_f32_e32 v179, 0xbfb8aa3b, v89
	v_mul_f32_e32 v180, 0xbfb8aa3b, v90
	v_mul_f32_e32 v181, 0xbfb8aa3b, v91
	v_exp_f32_e32 v178, v178
	v_exp_f32_e32 v179, v179
	v_exp_f32_e32 v180, v180
	v_exp_f32_e32 v181, v181
	v_add_f32_e32 v178, 1.0, v178
	v_add_f32_e32 v179, 1.0, v179
	v_add_f32_e32 v180, 1.0, v180
	v_add_f32_e32 v181, 1.0, v181
	v_rcp_f32_e32 v178, v178
	v_rcp_f32_e32 v179, v179
	v_rcp_f32_e32 v180, v180
	v_rcp_f32_e32 v181, v181
	v_mul_f32_e32 v88, v88, v178
	v_mul_f32_e32 v89, v89, v179
	v_mul_f32_e32 v90, v90, v180
	v_mul_f32_e32 v91, v91, v181
	v_cvt_pk_bf16_f32 v88, v88, v89
	v_cvt_pk_bf16_f32 v89, v90, v91
	ds_write_b64 v172, v[88:89] offset:4096
	v_mul_f32_e32 v178, 0xbfb8aa3b, v92
	v_mul_f32_e32 v179, 0xbfb8aa3b, v93
	v_mul_f32_e32 v180, 0xbfb8aa3b, v94
	v_mul_f32_e32 v181, 0xbfb8aa3b, v95
	v_exp_f32_e32 v178, v178
	v_exp_f32_e32 v179, v179
	v_exp_f32_e32 v180, v180
	v_exp_f32_e32 v181, v181
	v_add_f32_e32 v178, 1.0, v178
	v_add_f32_e32 v179, 1.0, v179
	v_add_f32_e32 v180, 1.0, v180
	v_add_f32_e32 v181, 1.0, v181
	v_rcp_f32_e32 v178, v178
	v_rcp_f32_e32 v179, v179
	v_rcp_f32_e32 v180, v180
	v_rcp_f32_e32 v181, v181
	v_mul_f32_e32 v92, v92, v178
	v_mul_f32_e32 v93, v93, v179
	v_mul_f32_e32 v94, v94, v180
	v_mul_f32_e32 v95, v95, v181
	v_cvt_pk_bf16_f32 v92, v92, v93
	v_cvt_pk_bf16_f32 v93, v94, v95
	ds_write_b64 v173, v[92:93] offset:4096
	v_mul_f32_e32 v178, 0xbfb8aa3b, v64
; DEV u16 f2bf(float f) { return (u16)(pack2(f, f) & 0xffffu); }
; DEV float silu_f(float x) { return x / (1.f + __expf(-x)); }
; template <class F>
; DEV void acc_foreach(Acc& acc, int m0, int n0, F f) {
;   asm volatile("s_nop 7\n\ts_nop 7\n\ts_nop 3" ::: "memory");
;   const int tid = tidx_full();
;   const int wave = tid >> 6, lane = tid & 63;
;   const int wm = (wave >> 2) * 128, wn = (wave & 3) * 64;
;   const int lr = lane & 31, lh = lane >> 5;
; #pragma unroll
;   for (int i = 0; i < 4; ++i)
; #pragma unroll
;     for (int j = 0; j < 2; ++j)
; #pragma unroll
;       for (int r = 0; r < 16; ++r) {
;         const int m = m0 + wm + 32 * i + (r & 3) + 8 * (r >> 2) + 4 * lh;
;         const int n = n0 + wn + 32 * j + lr;
;         float v = acc[i][j][r];
;         f(m, n, v);
;         acc[i][j][r] = v;
;       }
; }
; DEV void phase_p1(const Params& p, int g, char* smem) {
;     ...
;         const bool dosilu = (n0 < 512) || (n0 >= 2048);
;         acc_foreach(acc, m0, n0, [&](int m, int n, float& v) {
;           const float o = dosilu ? silu_f(v) : v;
;           PHG[(size_t)m * 2560 + n] = f2bf(o);
;         });
	v_mul_f32_e32 v179, 0xbfb8aa3b, v65
	v_mul_f32_e32 v180, 0xbfb8aa3b, v66
	v_mul_f32_e32 v181, 0xbfb8aa3b, v67
	v_exp_f32_e32 v178, v178
	v_exp_f32_e32 v179, v179
	v_exp_f32_e32 v180, v180
	v_exp_f32_e32 v181, v181
	v_add_f32_e32 v178, 1.0, v178
	v_add_f32_e32 v179, 1.0, v179
	v_add_f32_e32 v180, 1.0, v180
	v_add_f32_e32 v181, 1.0, v181
	v_rcp_f32_e32 v178, v178
	v_rcp_f32_e32 v179, v179
	v_rcp_f32_e32 v180, v180
	v_rcp_f32_e32 v181, v181
	v_mul_f32_e32 v64, v64, v178
	v_mul_f32_e32 v65, v65, v179
	v_mul_f32_e32 v66, v66, v180
	v_mul_f32_e32 v67, v67, v181
	v_cvt_pk_bf16_f32 v64, v64, v65
	v_cvt_pk_bf16_f32 v65, v66, v67
	ds_write_b64 v174, v[64:65] offset:4096
	v_mul_f32_e32 v178, 0xbfb8aa3b, v68
	v_mul_f32_e32 v179, 0xbfb8aa3b, v69
	v_mul_f32_e32 v180, 0xbfb8aa3b, v70
	v_mul_f32_e32 v181, 0xbfb8aa3b, v71
	v_exp_f32_e32 v178, v178
	v_exp_f32_e32 v179, v179
	v_exp_f32_e32 v180, v180
	v_exp_f32_e32 v181, v181
	v_add_f32_e32 v178, 1.0, v178
	v_add_f32_e32 v179, 1.0, v179
	v_add_f32_e32 v180, 1.0, v180
	v_add_f32_e32 v181, 1.0, v181
	v_rcp_f32_e32 v178, v178
	v_rcp_f32_e32 v179, v179
	v_rcp_f32_e32 v180, v180
	v_rcp_f32_e32 v181, v181
	v_mul_f32_e32 v68, v68, v178
	v_mul_f32_e32 v69, v69, v179
	v_mul_f32_e32 v70, v70, v180
	v_mul_f32_e32 v71, v71, v181
	v_cvt_pk_bf16_f32 v68, v68, v69
	v_cvt_pk_bf16_f32 v69, v70, v71
	ds_write_b64 v175, v[68:69] offset:4096
	v_mul_f32_e32 v178, 0xbfb8aa3b, v72
	v_mul_f32_e32 v179, 0xbfb8aa3b, v73
	v_mul_f32_e32 v180, 0xbfb8aa3b, v74
	v_mul_f32_e32 v181, 0xbfb8aa3b, v75
	v_exp_f32_e32 v178, v178
	v_exp_f32_e32 v179, v179
	v_exp_f32_e32 v180, v180
	v_exp_f32_e32 v181, v181
	v_add_f32_e32 v178, 1.0, v178
	v_add_f32_e32 v179, 1.0, v179
	v_add_f32_e32 v180, 1.0, v180
	v_add_f32_e32 v181, 1.0, v181
	v_rcp_f32_e32 v178, v178
	v_rcp_f32_e32 v179, v179
	v_rcp_f32_e32 v180, v180
	v_rcp_f32_e32 v181, v181
	v_mul_f32_e32 v72, v72, v178
	v_mul_f32_e32 v73, v73, v179
	v_mul_f32_e32 v74, v74, v180
	v_mul_f32_e32 v75, v75, v181
	v_cvt_pk_bf16_f32 v72, v72, v73
	v_cvt_pk_bf16_f32 v73, v74, v75
	ds_write_b64 v176, v[72:73] offset:4096
	v_mul_f32_e32 v178, 0xbfb8aa3b, v76
	v_mul_f32_e32 v179, 0xbfb8aa3b, v77
	v_mul_f32_e32 v180, 0xbfb8aa3b, v78
	v_mul_f32_e32 v181, 0xbfb8aa3b, v79
	v_exp_f32_e32 v178, v178
	v_exp_f32_e32 v179, v179
	v_exp_f32_e32 v180, v180
	v_exp_f32_e32 v181, v181
	v_add_f32_e32 v178, 1.0, v178
	v_add_f32_e32 v179, 1.0, v179
	v_add_f32_e32 v180, 1.0, v180
	v_add_f32_e32 v181, 1.0, v181
	v_rcp_f32_e32 v178, v178
	v_rcp_f32_e32 v179, v179
	v_rcp_f32_e32 v180, v180
	v_rcp_f32_e32 v181, v181
	v_mul_f32_e32 v76, v76, v178
	v_mul_f32_e32 v77, v77, v179
	v_mul_f32_e32 v78, v78, v180
	v_mul_f32_e32 v79, v79, v181
	v_cvt_pk_bf16_f32 v76, v76, v77
	v_cvt_pk_bf16_f32 v77, v78, v79
	ds_write_b64 v177, v[76:77] offset:4096
	s_waitcnt lgkmcnt(0)
	ds_read_b128 v[96:99], v168
	ds_read_b128 v[100:103], v168 offset:1024
	ds_read_b128 v[104:107], v168 offset:2048
	ds_read_b128 v[108:111], v168 offset:3072
	ds_read_b128 v[112:115], v168 offset:4096
	ds_read_b128 v[116:119], v168 offset:5120
	ds_read_b128 v[120:123], v168 offset:6144
	ds_read_b128 v[124:127], v168 offset:7168
	s_waitcnt lgkmcnt(7)
	global_store_dwordx4 v169, v[96:99], s[56:57]
	v_add_u32_e32 v169, 0xa000, v169
	s_waitcnt lgkmcnt(6)
	global_store_dwordx4 v169, v[100:103], s[56:57]
	v_add_u32_e32 v169, 0xa000, v169
	s_waitcnt lgkmcnt(5)
	global_store_dwordx4 v169, v[104:107], s[56:57]
	v_add_u32_e32 v169, 0xa000, v169
	s_waitcnt lgkmcnt(4)
	global_store_dwordx4 v169, v[108:111], s[56:57]
	v_add_u32_e32 v169, 0xa000, v169
	s_waitcnt lgkmcnt(3)
	global_store_dwordx4 v169, v[112:115], s[56:57]
	v_add_u32_e32 v169, 0xa000, v169
	s_waitcnt lgkmcnt(2)
	global_store_dwordx4 v169, v[116:119], s[56:57]
	v_add_u32_e32 v169, 0xa000, v169
	s_waitcnt lgkmcnt(1)
	global_store_dwordx4 v169, v[120:123], s[56:57]
	v_add_u32_e32 v169, 0xa000, v169
	s_waitcnt lgkmcnt(0)
	global_store_dwordx4 v169, v[124:127], s[56:57]
	v_add_u32_e32 v169, 0xa000, v169
	v_mul_f32_e32 v178, 0xbfb8aa3b, v48
	v_mul_f32_e32 v179, 0xbfb8aa3b, v49
	v_mul_f32_e32 v180, 0xbfb8aa3b, v50
	v_mul_f32_e32 v181, 0xbfb8aa3b, v51
	v_exp_f32_e32 v178, v178
	v_exp_f32_e32 v179, v179
	v_exp_f32_e32 v180, v180
	v_exp_f32_e32 v181, v181
	v_add_f32_e32 v178, 1.0, v178
	v_add_f32_e32 v179, 1.0, v179
	v_add_f32_e32 v180, 1.0, v180
	v_add_f32_e32 v181, 1.0, v181
	v_rcp_f32_e32 v178, v178
	v_rcp_f32_e32 v179, v179
	v_rcp_f32_e32 v180, v180
	v_rcp_f32_e32 v181, v181
	v_mul_f32_e32 v48, v48, v178
	v_mul_f32_e32 v49, v49, v179
	v_mul_f32_e32 v50, v50, v180
	v_mul_f32_e32 v51, v51, v181
	v_cvt_pk_bf16_f32 v48, v48, v49
	v_cvt_pk_bf16_f32 v49, v50, v51
	ds_write_b64 v170, v[48:49]
	v_mul_f32_e32 v178, 0xbfb8aa3b, v52
	v_mul_f32_e32 v179, 0xbfb8aa3b, v53
	v_mul_f32_e32 v180, 0xbfb8aa3b, v54
	v_mul_f32_e32 v181, 0xbfb8aa3b, v55
	v_exp_f32_e32 v178, v178
	v_exp_f32_e32 v179, v179
	v_exp_f32_e32 v180, v180
	v_exp_f32_e32 v181, v181
	v_add_f32_e32 v178, 1.0, v178
	v_add_f32_e32 v179, 1.0, v179
	v_add_f32_e32 v180, 1.0, v180
	v_add_f32_e32 v181, 1.0, v181
	v_rcp_f32_e32 v178, v178
	v_rcp_f32_e32 v179, v179
	v_rcp_f32_e32 v180, v180
	v_rcp_f32_e32 v181, v181
	v_mul_f32_e32 v52, v52, v178
	v_mul_f32_e32 v53, v53, v179
	v_mul_f32_e32 v54, v54, v180
	v_mul_f32_e32 v55, v55, v181
	v_cvt_pk_bf16_f32 v52, v52, v53
	v_cvt_pk_bf16_f32 v53, v54, v55
	ds_write_b64 v171, v[52:53]
	v_mul_f32_e32 v178, 0xbfb8aa3b, v56
	v_mul_f32_e32 v179, 0xbfb8aa3b, v57
	v_mul_f32_e32 v180, 0xbfb8aa3b, v58
	v_mul_f32_e32 v181, 0xbfb8aa3b, v59
	v_exp_f32_e32 v178, v178
	v_exp_f32_e32 v179, v179
	v_exp_f32_e32 v180, v180
	v_exp_f32_e32 v181, v181
	v_add_f32_e32 v178, 1.0, v178
; DEV u16 f2bf(float f) { return (u16)(pack2(f, f) & 0xffffu); }
; DEV float silu_f(float x) { return x / (1.f + __expf(-x)); }
; template <class F>
; DEV void acc_foreach(Acc& acc, int m0, int n0, F f) {
;   asm volatile("s_nop 7\n\ts_nop 7\n\ts_nop 3" ::: "memory");
;   const int tid = tidx_full();
;   const int wave = tid >> 6, lane = tid & 63;
;   const int wm = (wave >> 2) * 128, wn = (wave & 3) * 64;
;   const int lr = lane & 31, lh = lane >> 5;
; #pragma unroll
;   for (int i = 0; i < 4; ++i)
; #pragma unroll
;     for (int j = 0; j < 2; ++j)
; #pragma unroll
;       for (int r = 0; r < 16; ++r) {
;         const int m = m0 + wm + 32 * i + (r & 3) + 8 * (r >> 2) + 4 * lh;
;         const int n = n0 + wn + 32 * j + lr;
;         float v = acc[i][j][r];
;         f(m, n, v);
;         acc[i][j][r] = v;
;       }
; }
; DEV void phase_p1(const Params& p, int g, char* smem) {
;     ...
;         const bool dosilu = (n0 < 512) || (n0 >= 2048);
;         acc_foreach(acc, m0, n0, [&](int m, int n, float& v) {
;           const float o = dosilu ? silu_f(v) : v;
;           PHG[(size_t)m * 2560 + n] = f2bf(o);
;         });
	v_add_f32_e32 v179, 1.0, v179
	v_add_f32_e32 v180, 1.0, v180
	v_add_f32_e32 v181, 1.0, v181
	v_rcp_f32_e32 v178, v178
	v_rcp_f32_e32 v179, v179
	v_rcp_f32_e32 v180, v180
	v_rcp_f32_e32 v181, v181
	v_mul_f32_e32 v56, v56, v178
	v_mul_f32_e32 v57, v57, v179
	v_mul_f32_e32 v58, v58, v180
	v_mul_f32_e32 v59, v59, v181
	v_cvt_pk_bf16_f32 v56, v56, v57
	v_cvt_pk_bf16_f32 v57, v58, v59
	ds_write_b64 v172, v[56:57]
	v_mul_f32_e32 v178, 0xbfb8aa3b, v60
	v_mul_f32_e32 v179, 0xbfb8aa3b, v61
	v_mul_f32_e32 v180, 0xbfb8aa3b, v62
	v_mul_f32_e32 v181, 0xbfb8aa3b, v63
	v_exp_f32_e32 v178, v178
	v_exp_f32_e32 v179, v179
	v_exp_f32_e32 v180, v180
	v_exp_f32_e32 v181, v181
	v_add_f32_e32 v178, 1.0, v178
	v_add_f32_e32 v179, 1.0, v179
	v_add_f32_e32 v180, 1.0, v180
	v_add_f32_e32 v181, 1.0, v181
	v_rcp_f32_e32 v178, v178
	v_rcp_f32_e32 v179, v179
	v_rcp_f32_e32 v180, v180
	v_rcp_f32_e32 v181, v181
	v_mul_f32_e32 v60, v60, v178
	v_mul_f32_e32 v61, v61, v179
	v_mul_f32_e32 v62, v62, v180
	v_mul_f32_e32 v63, v63, v181
	v_cvt_pk_bf16_f32 v60, v60, v61
	v_cvt_pk_bf16_f32 v61, v62, v63
	ds_write_b64 v173, v[60:61]
	v_mul_f32_e32 v178, 0xbfb8aa3b, v32
	v_mul_f32_e32 v179, 0xbfb8aa3b, v33
	v_mul_f32_e32 v180, 0xbfb8aa3b, v34
	v_mul_f32_e32 v181, 0xbfb8aa3b, v35
	v_exp_f32_e32 v178, v178
	v_exp_f32_e32 v179, v179
	v_exp_f32_e32 v180, v180
	v_exp_f32_e32 v181, v181
	v_add_f32_e32 v178, 1.0, v178
	v_add_f32_e32 v179, 1.0, v179
	v_add_f32_e32 v180, 1.0, v180
	v_add_f32_e32 v181, 1.0, v181
	v_rcp_f32_e32 v178, v178
	v_rcp_f32_e32 v179, v179
	v_rcp_f32_e32 v180, v180
	v_rcp_f32_e32 v181, v181
	v_mul_f32_e32 v32, v32, v178
	v_mul_f32_e32 v33, v33, v179
	v_mul_f32_e32 v34, v34, v180
	v_mul_f32_e32 v35, v35, v181
	v_cvt_pk_bf16_f32 v32, v32, v33
	v_cvt_pk_bf16_f32 v33, v34, v35
	ds_write_b64 v174, v[32:33]
	v_mul_f32_e32 v178, 0xbfb8aa3b, v36
	v_mul_f32_e32 v179, 0xbfb8aa3b, v37
	v_mul_f32_e32 v180, 0xbfb8aa3b, v38
	v_mul_f32_e32 v181, 0xbfb8aa3b, v39
	v_exp_f32_e32 v178, v178
	v_exp_f32_e32 v179, v179
	v_exp_f32_e32 v180, v180
	v_exp_f32_e32 v181, v181
	v_add_f32_e32 v178, 1.0, v178
	v_add_f32_e32 v179, 1.0, v179
	v_add_f32_e32 v180, 1.0, v180
	v_add_f32_e32 v181, 1.0, v181
	v_rcp_f32_e32 v178, v178
	v_rcp_f32_e32 v179, v179
	v_rcp_f32_e32 v180, v180
	v_rcp_f32_e32 v181, v181
	v_mul_f32_e32 v36, v36, v178
	v_mul_f32_e32 v37, v37, v179
	v_mul_f32_e32 v38, v38, v180
	v_mul_f32_e32 v39, v39, v181
	v_cvt_pk_bf16_f32 v36, v36, v37
	v_cvt_pk_bf16_f32 v37, v38, v39
	ds_write_b64 v175, v[36:37]
	v_mul_f32_e32 v178, 0xbfb8aa3b, v40
	v_mul_f32_e32 v179, 0xbfb8aa3b, v41
	v_mul_f32_e32 v180, 0xbfb8aa3b, v42
	v_mul_f32_e32 v181, 0xbfb8aa3b, v43
	v_exp_f32_e32 v178, v178
	v_exp_f32_e32 v179, v179
	v_exp_f32_e32 v180, v180
	v_exp_f32_e32 v181, v181
	v_add_f32_e32 v178, 1.0, v178
	v_add_f32_e32 v179, 1.0, v179
	v_add_f32_e32 v180, 1.0, v180
	v_add_f32_e32 v181, 1.0, v181
	v_rcp_f32_e32 v178, v178
	v_rcp_f32_e32 v179, v179
	v_rcp_f32_e32 v180, v180
	v_rcp_f32_e32 v181, v181
	v_mul_f32_e32 v40, v40, v178
	v_mul_f32_e32 v41, v41, v179
	v_mul_f32_e32 v42, v42, v180
	v_mul_f32_e32 v43, v43, v181
	v_cvt_pk_bf16_f32 v40, v40, v41
	v_cvt_pk_bf16_f32 v41, v42, v43
	ds_write_b64 v176, v[40:41]
	v_mul_f32_e32 v178, 0xbfb8aa3b, v44
	v_mul_f32_e32 v179, 0xbfb8aa3b, v45
	v_mul_f32_e32 v180, 0xbfb8aa3b, v46
	v_mul_f32_e32 v181, 0xbfb8aa3b, v47
	v_exp_f32_e32 v178, v178
	v_exp_f32_e32 v179, v179
	v_exp_f32_e32 v180, v180
	v_exp_f32_e32 v181, v181
	v_add_f32_e32 v178, 1.0, v178
	v_add_f32_e32 v179, 1.0, v179
	v_add_f32_e32 v180, 1.0, v180
	v_add_f32_e32 v181, 1.0, v181
	v_rcp_f32_e32 v178, v178
	v_rcp_f32_e32 v179, v179
	v_rcp_f32_e32 v180, v180
	v_rcp_f32_e32 v181, v181
	v_mul_f32_e32 v44, v44, v178
	v_mul_f32_e32 v45, v45, v179
	v_mul_f32_e32 v46, v46, v180
	v_mul_f32_e32 v47, v47, v181
	v_cvt_pk_bf16_f32 v44, v44, v45
	v_cvt_pk_bf16_f32 v45, v46, v47
	ds_write_b64 v177, v[44:45]
	v_mul_f32_e32 v178, 0xbfb8aa3b, v16
	v_mul_f32_e32 v179, 0xbfb8aa3b, v17
	v_mul_f32_e32 v180, 0xbfb8aa3b, v18
	v_mul_f32_e32 v181, 0xbfb8aa3b, v19
	v_exp_f32_e32 v178, v178
	v_exp_f32_e32 v179, v179
	v_exp_f32_e32 v180, v180
	v_exp_f32_e32 v181, v181
	v_add_f32_e32 v178, 1.0, v178
	v_add_f32_e32 v179, 1.0, v179
	v_add_f32_e32 v180, 1.0, v180
	v_add_f32_e32 v181, 1.0, v181
	v_rcp_f32_e32 v178, v178
	v_rcp_f32_e32 v179, v179
	v_rcp_f32_e32 v180, v180
	v_rcp_f32_e32 v181, v181
	v_mul_f32_e32 v16, v16, v178
	v_mul_f32_e32 v17, v17, v179
	v_mul_f32_e32 v18, v18, v180
	v_mul_f32_e32 v19, v19, v181
	v_cvt_pk_bf16_f32 v16, v16, v17
	v_cvt_pk_bf16_f32 v17, v18, v19
	ds_write_b64 v170, v[16:17] offset:4096
	v_mul_f32_e32 v178, 0xbfb8aa3b, v20
	v_mul_f32_e32 v179, 0xbfb8aa3b, v21
	v_mul_f32_e32 v180, 0xbfb8aa3b, v22
	v_mul_f32_e32 v181, 0xbfb8aa3b, v23
	v_exp_f32_e32 v178, v178
	v_exp_f32_e32 v179, v179
	v_exp_f32_e32 v180, v180
	v_exp_f32_e32 v181, v181
	v_add_f32_e32 v178, 1.0, v178
	v_add_f32_e32 v179, 1.0, v179
	v_add_f32_e32 v180, 1.0, v180
	v_add_f32_e32 v181, 1.0, v181
	v_rcp_f32_e32 v178, v178
	v_rcp_f32_e32 v179, v179
	v_rcp_f32_e32 v180, v180
	v_rcp_f32_e32 v181, v181
	v_mul_f32_e32 v20, v20, v178
	v_mul_f32_e32 v21, v21, v179
	v_mul_f32_e32 v22, v22, v180
	v_mul_f32_e32 v23, v23, v181
	v_cvt_pk_bf16_f32 v20, v20, v21
	v_cvt_pk_bf16_f32 v21, v22, v23
	ds_write_b64 v171, v[20:21] offset:4096
	v_mul_f32_e32 v178, 0xbfb8aa3b, v24
	v_mul_f32_e32 v179, 0xbfb8aa3b, v25
	v_mul_f32_e32 v180, 0xbfb8aa3b, v26
	v_mul_f32_e32 v181, 0xbfb8aa3b, v27
	v_exp_f32_e32 v178, v178
	v_exp_f32_e32 v179, v179
	v_exp_f32_e32 v180, v180
	v_exp_f32_e32 v181, v181
	v_add_f32_e32 v178, 1.0, v178
	v_add_f32_e32 v179, 1.0, v179
	v_add_f32_e32 v180, 1.0, v180
; DEV u16 f2bf(float f) { return (u16)(pack2(f, f) & 0xffffu); }
; DEV float silu_f(float x) { return x / (1.f + __expf(-x)); }
; template <class F>
; DEV void acc_foreach(Acc& acc, int m0, int n0, F f) {
;   asm volatile("s_nop 7\n\ts_nop 7\n\ts_nop 3" ::: "memory");
;   const int tid = tidx_full();
;   const int wave = tid >> 6, lane = tid & 63;
;   const int wm = (wave >> 2) * 128, wn = (wave & 3) * 64;
;   const int lr = lane & 31, lh = lane >> 5;
; #pragma unroll
;   for (int i = 0; i < 4; ++i)
; #pragma unroll
;     for (int j = 0; j < 2; ++j)
; #pragma unroll
;       for (int r = 0; r < 16; ++r) {
;         const int m = m0 + wm + 32 * i + (r & 3) + 8 * (r >> 2) + 4 * lh;
;         const int n = n0 + wn + 32 * j + lr;
;         float v = acc[i][j][r];
;         f(m, n, v);
;         acc[i][j][r] = v;
;       }
; }
; DEV void phase_p1(const Params& p, int g, char* smem) {
;     ...
;         const bool dosilu = (n0 < 512) || (n0 >= 2048);
;         acc_foreach(acc, m0, n0, [&](int m, int n, float& v) {
;           const float o = dosilu ? silu_f(v) : v;
;           PHG[(size_t)m * 2560 + n] = f2bf(o);
;         });
	v_add_f32_e32 v181, 1.0, v181
	v_rcp_f32_e32 v178, v178
	v_rcp_f32_e32 v179, v179
	v_rcp_f32_e32 v180, v180
	v_rcp_f32_e32 v181, v181
	v_mul_f32_e32 v24, v24, v178
	v_mul_f32_e32 v25, v25, v179
	v_mul_f32_e32 v26, v26, v180
	v_mul_f32_e32 v27, v27, v181
	v_cvt_pk_bf16_f32 v24, v24, v25
	v_cvt_pk_bf16_f32 v25, v26, v27
	ds_write_b64 v172, v[24:25] offset:4096
	v_mul_f32_e32 v178, 0xbfb8aa3b, v28
	v_mul_f32_e32 v179, 0xbfb8aa3b, v29
	v_mul_f32_e32 v180, 0xbfb8aa3b, v30
	v_mul_f32_e32 v181, 0xbfb8aa3b, v31
	v_exp_f32_e32 v178, v178
	v_exp_f32_e32 v179, v179
	v_exp_f32_e32 v180, v180
	v_exp_f32_e32 v181, v181
	v_add_f32_e32 v178, 1.0, v178
	v_add_f32_e32 v179, 1.0, v179
	v_add_f32_e32 v180, 1.0, v180
	v_add_f32_e32 v181, 1.0, v181
	v_rcp_f32_e32 v178, v178
	v_rcp_f32_e32 v179, v179
	v_rcp_f32_e32 v180, v180
	v_rcp_f32_e32 v181, v181
	v_mul_f32_e32 v28, v28, v178
	v_mul_f32_e32 v29, v29, v179
	v_mul_f32_e32 v30, v30, v180
	v_mul_f32_e32 v31, v31, v181
	v_cvt_pk_bf16_f32 v28, v28, v29
	v_cvt_pk_bf16_f32 v29, v30, v31
	ds_write_b64 v173, v[28:29] offset:4096
	v_mul_f32_e32 v178, 0xbfb8aa3b, v0
	v_mul_f32_e32 v179, 0xbfb8aa3b, v1
	v_mul_f32_e32 v180, 0xbfb8aa3b, v2
	v_mul_f32_e32 v181, 0xbfb8aa3b, v3
	v_exp_f32_e32 v178, v178
	v_exp_f32_e32 v179, v179
	v_exp_f32_e32 v180, v180
	v_exp_f32_e32 v181, v181
	v_add_f32_e32 v178, 1.0, v178
	v_add_f32_e32 v179, 1.0, v179
	v_add_f32_e32 v180, 1.0, v180
	v_add_f32_e32 v181, 1.0, v181
	v_rcp_f32_e32 v178, v178
	v_rcp_f32_e32 v179, v179
	v_rcp_f32_e32 v180, v180
	v_rcp_f32_e32 v181, v181
	v_mul_f32_e32 v0, v0, v178
	v_mul_f32_e32 v1, v1, v179
	v_mul_f32_e32 v2, v2, v180
	v_mul_f32_e32 v3, v3, v181
	v_cvt_pk_bf16_f32 v0, v0, v1
	v_cvt_pk_bf16_f32 v1, v2, v3
	ds_write_b64 v174, v[0:1] offset:4096
	v_mul_f32_e32 v178, 0xbfb8aa3b, v4
	v_mul_f32_e32 v179, 0xbfb8aa3b, v5
	v_mul_f32_e32 v180, 0xbfb8aa3b, v6
	v_mul_f32_e32 v181, 0xbfb8aa3b, v7
	v_exp_f32_e32 v178, v178
	v_exp_f32_e32 v179, v179
	v_exp_f32_e32 v180, v180
	v_exp_f32_e32 v181, v181
	v_add_f32_e32 v178, 1.0, v178
	v_add_f32_e32 v179, 1.0, v179
	v_add_f32_e32 v180, 1.0, v180
	v_add_f32_e32 v181, 1.0, v181
	v_rcp_f32_e32 v178, v178
	v_rcp_f32_e32 v179, v179
	v_rcp_f32_e32 v180, v180
	v_rcp_f32_e32 v181, v181
	v_mul_f32_e32 v4, v4, v178
	v_mul_f32_e32 v5, v5, v179
	v_mul_f32_e32 v6, v6, v180
	v_mul_f32_e32 v7, v7, v181
	v_cvt_pk_bf16_f32 v4, v4, v5
	v_cvt_pk_bf16_f32 v5, v6, v7
	ds_write_b64 v175, v[4:5] offset:4096
	v_mul_f32_e32 v178, 0xbfb8aa3b, v8
	v_mul_f32_e32 v179, 0xbfb8aa3b, v9
	v_mul_f32_e32 v180, 0xbfb8aa3b, v10
	v_mul_f32_e32 v181, 0xbfb8aa3b, v11
	v_exp_f32_e32 v178, v178
	v_exp_f32_e32 v179, v179
	v_exp_f32_e32 v180, v180
	v_exp_f32_e32 v181, v181
	v_add_f32_e32 v178, 1.0, v178
	v_add_f32_e32 v179, 1.0, v179
	v_add_f32_e32 v180, 1.0, v180
	v_add_f32_e32 v181, 1.0, v181
	v_rcp_f32_e32 v178, v178
	v_rcp_f32_e32 v179, v179
	v_rcp_f32_e32 v180, v180
	v_rcp_f32_e32 v181, v181
	v_mul_f32_e32 v8, v8, v178
	v_mul_f32_e32 v9, v9, v179
	v_mul_f32_e32 v10, v10, v180
	v_mul_f32_e32 v11, v11, v181
	v_cvt_pk_bf16_f32 v8, v8, v9
	v_cvt_pk_bf16_f32 v9, v10, v11
	ds_write_b64 v176, v[8:9] offset:4096
	v_mul_f32_e32 v178, 0xbfb8aa3b, v12
	v_mul_f32_e32 v179, 0xbfb8aa3b, v13
	v_mul_f32_e32 v180, 0xbfb8aa3b, v14
	v_mul_f32_e32 v181, 0xbfb8aa3b, v15
	v_exp_f32_e32 v178, v178
	v_exp_f32_e32 v179, v179
	v_exp_f32_e32 v180, v180
	v_exp_f32_e32 v181, v181
	v_add_f32_e32 v178, 1.0, v178
	v_add_f32_e32 v179, 1.0, v179
	v_add_f32_e32 v180, 1.0, v180
	v_add_f32_e32 v181, 1.0, v181
	v_rcp_f32_e32 v178, v178
	v_rcp_f32_e32 v179, v179
	v_rcp_f32_e32 v180, v180
	v_rcp_f32_e32 v181, v181
	v_mul_f32_e32 v12, v12, v178
	v_mul_f32_e32 v13, v13, v179
	v_mul_f32_e32 v14, v14, v180
	v_mul_f32_e32 v15, v15, v181
	v_cvt_pk_bf16_f32 v12, v12, v13
	v_cvt_pk_bf16_f32 v13, v14, v15
	ds_write_b64 v177, v[12:13] offset:4096
	s_waitcnt lgkmcnt(0)
	ds_read_b128 v[64:67], v168
	ds_read_b128 v[68:71], v168 offset:1024
	ds_read_b128 v[72:75], v168 offset:2048
	ds_read_b128 v[76:79], v168 offset:3072
	ds_read_b128 v[80:83], v168 offset:4096
	ds_read_b128 v[84:87], v168 offset:5120
	ds_read_b128 v[88:91], v168 offset:6144
	ds_read_b128 v[92:95], v168 offset:7168
	s_waitcnt lgkmcnt(7)
	global_store_dwordx4 v169, v[64:67], s[56:57]
	v_add_u32_e32 v169, 0xa000, v169
	s_waitcnt lgkmcnt(6)
	global_store_dwordx4 v169, v[68:71], s[56:57]
	v_add_u32_e32 v169, 0xa000, v169
	s_waitcnt lgkmcnt(5)
	global_store_dwordx4 v169, v[72:75], s[56:57]
	v_add_u32_e32 v169, 0xa000, v169
	s_waitcnt lgkmcnt(4)
	global_store_dwordx4 v169, v[76:79], s[56:57]
	v_add_u32_e32 v169, 0xa000, v169
	s_waitcnt lgkmcnt(3)
	global_store_dwordx4 v169, v[80:83], s[56:57]
	v_add_u32_e32 v169, 0xa000, v169
	s_waitcnt lgkmcnt(2)
	global_store_dwordx4 v169, v[84:87], s[56:57]
	v_add_u32_e32 v169, 0xa000, v169
	s_waitcnt lgkmcnt(1)
	global_store_dwordx4 v169, v[88:91], s[56:57]
	v_add_u32_e32 v169, 0xa000, v169
	s_waitcnt lgkmcnt(0)
	s_barrier
	global_store_dwordx4 v169, v[92:95], s[56:57]
	v_add_u32_e32 v169, 0xa000, v169
	s_branch .LBB0_261
; DEV u16 f2bf(float f) { return (u16)(pack2(f, f) & 0xffffu); }
; DEV float sigmoid_f(float x) { return __builtin_amdgcn_rcpf(1.f + __expf(-x)); }
; template <class F>
; DEV void acc_foreach(Acc& acc, int m0, int n0, F f) {
;   asm volatile("s_nop 7\n\ts_nop 7\n\ts_nop 3" ::: "memory");
;   const int tid = tidx_full();
;   const int wave = tid >> 6, lane = tid & 63;
;   const int wm = (wave >> 2) * 128, wn = (wave & 3) * 64;
;   const int lr = lane & 31, lh = lane >> 5;
; #pragma unroll
;   for (int i = 0; i < 4; ++i)
; #pragma unroll
;     for (int j = 0; j < 2; ++j)
; #pragma unroll
;       for (int r = 0; r < 16; ++r) {
;         const int m = m0 + wm + 32 * i + (r & 3) + 8 * (r >> 2) + 4 * lh;
;         const int n = n0 + wn + 32 * j + lr;
;         float v = acc[i][j][r];
;         f(m, n, v);
;         acc[i][j][r] = v;
;       }
; }
; DEV void phase_p1(const Params& p, int g, char* smem) {
;     ...
;         acc_foreach(acc, m0, n0, [&](int m, int n, float& v) { GT[(size_t)m * 2048 + (n - 2560)] = f2bf(sigmoid_f(v)); });
.Lp1a_gt:
	s_nop 7
	s_nop 7
	s_nop 3
	v_and_b32_e32 v160, 63, v202
	v_lshrrev_b32_e32 v161, 6, v202
	v_and_b32_e32 v164, 3, v161
	v_lshlrev_b32_e32 v164, 13, v164
	v_add_u32_e32 v164, 0x8000, v164
	v_lshrrev_b32_e32 v160, 2, v161
	v_lshl_add_u32 v164, v160, 16, v164
	v_and_b32_e32 v160, 63, v202
	v_and_b32_e32 v166, 31, v160
	v_lshrrev_b32_e32 v167, 5, v160
	v_lshlrev_b32_e32 v168, 7, v166
	v_lshl_add_u32 v168, v167, 3, v168
	v_add_u32_e32 v168, v164, v168
	v_and_b32_e32 v166, 7, v166
	v_lshlrev_b32_e32 v166, 4, v166
	v_add_u32_e32 v170, v168, v166
	v_xor_b32_e32 v167, 0x10, v166
	v_add_u32_e32 v171, v168, v167
	v_xor_b32_e32 v167, 0x20, v166
	v_add_u32_e32 v172, v168, v167
	v_xor_b32_e32 v167, 0x30, v166
	v_add_u32_e32 v173, v168, v167
	v_xor_b32_e32 v167, 0x40, v166
	v_add_u32_e32 v174, v168, v167
	v_xor_b32_e32 v167, 0x50, v166
	v_add_u32_e32 v175, v168, v167
	v_xor_b32_e32 v167, 0x60, v166
	v_add_u32_e32 v176, v168, v167
	v_xor_b32_e32 v167, 0x70, v166
	v_add_u32_e32 v177, v168, v167
	v_lshrrev_b32_e32 v166, 3, v160
	v_and_b32_e32 v167, 7, v160
	v_lshrrev_b32_e32 v169, 2, v161
	v_lshl_add_u32 v169, v169, 7, v166
	v_add_u32_e32 v169, s5, v169
	v_mul_u32_u24_e32 v169, 0x1000, v169
	v_and_b32_e32 v168, 3, v161
	v_lshlrev_b32_e32 v168, 3, v168
	v_add_u32_e32 v168, v168, v167
	v_lshl_add_u32 v169, v168, 4, v169
	s_lshl_b32 s100, s4, 1
	s_sub_u32 s100, s100, 0x1400
	v_add_u32_e32 v169, s100, v169
	v_xor_b32_e32 v167, v166, v167
	v_lshlrev_b32_e32 v167, 4, v167
	v_lshl_add_u32 v168, v166, 7, v167
	v_add_u32_e32 v168, v164, v168
	v_mul_f32_e32 v112, 0xbfb8aa3b, v112
	v_mul_f32_e32 v113, 0xbfb8aa3b, v113
	v_mul_f32_e32 v114, 0xbfb8aa3b, v114
	v_mul_f32_e32 v115, 0xbfb8aa3b, v115
	v_exp_f32_e32 v112, v112
	v_exp_f32_e32 v113, v113
	v_exp_f32_e32 v114, v114
	v_exp_f32_e32 v115, v115
	v_add_f32_e32 v112, 1.0, v112
	v_add_f32_e32 v113, 1.0, v113
	v_add_f32_e32 v114, 1.0, v114
	v_add_f32_e32 v115, 1.0, v115
	v_rcp_f32_e32 v112, v112
	v_rcp_f32_e32 v113, v113
	v_rcp_f32_e32 v114, v114
	v_rcp_f32_e32 v115, v115
	v_cvt_pk_bf16_f32 v112, v112, v113
	v_cvt_pk_bf16_f32 v113, v114, v115
	ds_write_b64 v170, v[112:113]
	v_mul_f32_e32 v116, 0xbfb8aa3b, v116
	v_mul_f32_e32 v117, 0xbfb8aa3b, v117
	v_mul_f32_e32 v118, 0xbfb8aa3b, v118
	v_mul_f32_e32 v119, 0xbfb8aa3b, v119
	v_exp_f32_e32 v116, v116
	v_exp_f32_e32 v117, v117
	v_exp_f32_e32 v118, v118
	v_exp_f32_e32 v119, v119
	v_add_f32_e32 v116, 1.0, v116
	v_add_f32_e32 v117, 1.0, v117
	v_add_f32_e32 v118, 1.0, v118
	v_add_f32_e32 v119, 1.0, v119
	v_rcp_f32_e32 v116, v116
	v_rcp_f32_e32 v117, v117
	v_rcp_f32_e32 v118, v118
	v_rcp_f32_e32 v119, v119
	v_cvt_pk_bf16_f32 v116, v116, v117
	v_cvt_pk_bf16_f32 v117, v118, v119
	ds_write_b64 v171, v[116:117]
	v_mul_f32_e32 v120, 0xbfb8aa3b, v120
	v_mul_f32_e32 v121, 0xbfb8aa3b, v121
	v_mul_f32_e32 v122, 0xbfb8aa3b, v122
	v_mul_f32_e32 v123, 0xbfb8aa3b, v123
	v_exp_f32_e32 v120, v120
	v_exp_f32_e32 v121, v121
	v_exp_f32_e32 v122, v122
	v_exp_f32_e32 v123, v123
	v_add_f32_e32 v120, 1.0, v120
	v_add_f32_e32 v121, 1.0, v121
	v_add_f32_e32 v122, 1.0, v122
	v_add_f32_e32 v123, 1.0, v123
	v_rcp_f32_e32 v120, v120
	v_rcp_f32_e32 v121, v121
	v_rcp_f32_e32 v122, v122
	v_rcp_f32_e32 v123, v123
	v_cvt_pk_bf16_f32 v120, v120, v121
	v_cvt_pk_bf16_f32 v121, v122, v123
	ds_write_b64 v172, v[120:121]
	v_mul_f32_e32 v124, 0xbfb8aa3b, v124
	v_mul_f32_e32 v125, 0xbfb8aa3b, v125
	v_mul_f32_e32 v126, 0xbfb8aa3b, v126
	v_mul_f32_e32 v127, 0xbfb8aa3b, v127
	v_exp_f32_e32 v124, v124
	v_exp_f32_e32 v125, v125
	v_exp_f32_e32 v126, v126
	v_exp_f32_e32 v127, v127
	v_add_f32_e32 v124, 1.0, v124
	v_add_f32_e32 v125, 1.0, v125
	v_add_f32_e32 v126, 1.0, v126
	v_add_f32_e32 v127, 1.0, v127
	v_rcp_f32_e32 v124, v124
	v_rcp_f32_e32 v125, v125
	v_rcp_f32_e32 v126, v126
	v_rcp_f32_e32 v127, v127
	v_cvt_pk_bf16_f32 v124, v124, v125
	v_cvt_pk_bf16_f32 v125, v126, v127
	ds_write_b64 v173, v[124:125]
	v_mul_f32_e32 v96, 0xbfb8aa3b, v96
	v_mul_f32_e32 v97, 0xbfb8aa3b, v97
	v_mul_f32_e32 v98, 0xbfb8aa3b, v98
	v_mul_f32_e32 v99, 0xbfb8aa3b, v99
	v_exp_f32_e32 v96, v96
	v_exp_f32_e32 v97, v97
	v_exp_f32_e32 v98, v98
	v_exp_f32_e32 v99, v99
	v_add_f32_e32 v96, 1.0, v96
	v_add_f32_e32 v97, 1.0, v97
	v_add_f32_e32 v98, 1.0, v98
	v_add_f32_e32 v99, 1.0, v99
	v_rcp_f32_e32 v96, v96
	v_rcp_f32_e32 v97, v97
	v_rcp_f32_e32 v98, v98
	v_rcp_f32_e32 v99, v99
	v_cvt_pk_bf16_f32 v96, v96, v97
	v_cvt_pk_bf16_f32 v97, v98, v99
	ds_write_b64 v174, v[96:97]
	v_mul_f32_e32 v100, 0xbfb8aa3b, v100
	v_mul_f32_e32 v101, 0xbfb8aa3b, v101
	v_mul_f32_e32 v102, 0xbfb8aa3b, v102
	v_mul_f32_e32 v103, 0xbfb8aa3b, v103
	v_exp_f32_e32 v100, v100
	v_exp_f32_e32 v101, v101
	v_exp_f32_e32 v102, v102
	v_exp_f32_e32 v103, v103
	v_add_f32_e32 v100, 1.0, v100
	v_add_f32_e32 v101, 1.0, v101
	v_add_f32_e32 v102, 1.0, v102
	v_add_f32_e32 v103, 1.0, v103
	v_rcp_f32_e32 v100, v100
	v_rcp_f32_e32 v101, v101
	v_rcp_f32_e32 v102, v102
	v_rcp_f32_e32 v103, v103
	v_cvt_pk_bf16_f32 v100, v100, v101
	v_cvt_pk_bf16_f32 v101, v102, v103
	ds_write_b64 v175, v[100:101]
	v_mul_f32_e32 v104, 0xbfb8aa3b, v104
	v_mul_f32_e32 v105, 0xbfb8aa3b, v105
	v_mul_f32_e32 v106, 0xbfb8aa3b, v106
	v_mul_f32_e32 v107, 0xbfb8aa3b, v107
	v_exp_f32_e32 v104, v104
	v_exp_f32_e32 v105, v105
	v_exp_f32_e32 v106, v106
	v_exp_f32_e32 v107, v107
	v_add_f32_e32 v104, 1.0, v104
	v_add_f32_e32 v105, 1.0, v105
	v_add_f32_e32 v106, 1.0, v106
	v_add_f32_e32 v107, 1.0, v107
	v_rcp_f32_e32 v104, v104
	v_rcp_f32_e32 v105, v105
	v_rcp_f32_e32 v106, v106
	v_rcp_f32_e32 v107, v107
	v_cvt_pk_bf16_f32 v104, v104, v105
	v_cvt_pk_bf16_f32 v105, v106, v107
	ds_write_b64 v176, v[104:105]
	v_mul_f32_e32 v108, 0xbfb8aa3b, v108
; DEV u16 f2bf(float f) { return (u16)(pack2(f, f) & 0xffffu); }
; DEV float sigmoid_f(float x) { return __builtin_amdgcn_rcpf(1.f + __expf(-x)); }
; template <class F>
; DEV void acc_foreach(Acc& acc, int m0, int n0, F f) {
;   asm volatile("s_nop 7\n\ts_nop 7\n\ts_nop 3" ::: "memory");
;   const int tid = tidx_full();
;   const int wave = tid >> 6, lane = tid & 63;
;   const int wm = (wave >> 2) * 128, wn = (wave & 3) * 64;
;   const int lr = lane & 31, lh = lane >> 5;
; #pragma unroll
;   for (int i = 0; i < 4; ++i)
; #pragma unroll
;     for (int j = 0; j < 2; ++j)
; #pragma unroll
;       for (int r = 0; r < 16; ++r) {
;         const int m = m0 + wm + 32 * i + (r & 3) + 8 * (r >> 2) + 4 * lh;
;         const int n = n0 + wn + 32 * j + lr;
;         float v = acc[i][j][r];
;         f(m, n, v);
;         acc[i][j][r] = v;
;       }
; }
; DEV void phase_p1(const Params& p, int g, char* smem) {
;     ...
;         acc_foreach(acc, m0, n0, [&](int m, int n, float& v) { GT[(size_t)m * 2048 + (n - 2560)] = f2bf(sigmoid_f(v)); });
	v_mul_f32_e32 v109, 0xbfb8aa3b, v109
	v_mul_f32_e32 v110, 0xbfb8aa3b, v110
	v_mul_f32_e32 v111, 0xbfb8aa3b, v111
	v_exp_f32_e32 v108, v108
	v_exp_f32_e32 v109, v109
	v_exp_f32_e32 v110, v110
	v_exp_f32_e32 v111, v111
	v_add_f32_e32 v108, 1.0, v108
	v_add_f32_e32 v109, 1.0, v109
	v_add_f32_e32 v110, 1.0, v110
	v_add_f32_e32 v111, 1.0, v111
	v_rcp_f32_e32 v108, v108
	v_rcp_f32_e32 v109, v109
	v_rcp_f32_e32 v110, v110
	v_rcp_f32_e32 v111, v111
	v_cvt_pk_bf16_f32 v108, v108, v109
	v_cvt_pk_bf16_f32 v109, v110, v111
	ds_write_b64 v177, v[108:109]
	v_mul_f32_e32 v80, 0xbfb8aa3b, v80
	v_mul_f32_e32 v81, 0xbfb8aa3b, v81
	v_mul_f32_e32 v82, 0xbfb8aa3b, v82
	v_mul_f32_e32 v83, 0xbfb8aa3b, v83
	v_exp_f32_e32 v80, v80
	v_exp_f32_e32 v81, v81
	v_exp_f32_e32 v82, v82
	v_exp_f32_e32 v83, v83
	v_add_f32_e32 v80, 1.0, v80
	v_add_f32_e32 v81, 1.0, v81
	v_add_f32_e32 v82, 1.0, v82
	v_add_f32_e32 v83, 1.0, v83
	v_rcp_f32_e32 v80, v80
	v_rcp_f32_e32 v81, v81
	v_rcp_f32_e32 v82, v82
	v_rcp_f32_e32 v83, v83
	v_cvt_pk_bf16_f32 v80, v80, v81
	v_cvt_pk_bf16_f32 v81, v82, v83
	ds_write_b64 v170, v[80:81] offset:4096
	v_mul_f32_e32 v84, 0xbfb8aa3b, v84
	v_mul_f32_e32 v85, 0xbfb8aa3b, v85
	v_mul_f32_e32 v86, 0xbfb8aa3b, v86
	v_mul_f32_e32 v87, 0xbfb8aa3b, v87
	v_exp_f32_e32 v84, v84
	v_exp_f32_e32 v85, v85
	v_exp_f32_e32 v86, v86
	v_exp_f32_e32 v87, v87
	v_add_f32_e32 v84, 1.0, v84
	v_add_f32_e32 v85, 1.0, v85
	v_add_f32_e32 v86, 1.0, v86
	v_add_f32_e32 v87, 1.0, v87
	v_rcp_f32_e32 v84, v84
	v_rcp_f32_e32 v85, v85
	v_rcp_f32_e32 v86, v86
	v_rcp_f32_e32 v87, v87
	v_cvt_pk_bf16_f32 v84, v84, v85
	v_cvt_pk_bf16_f32 v85, v86, v87
	ds_write_b64 v171, v[84:85] offset:4096
	v_mul_f32_e32 v88, 0xbfb8aa3b, v88
	v_mul_f32_e32 v89, 0xbfb8aa3b, v89
	v_mul_f32_e32 v90, 0xbfb8aa3b, v90
	v_mul_f32_e32 v91, 0xbfb8aa3b, v91
	v_exp_f32_e32 v88, v88
	v_exp_f32_e32 v89, v89
	v_exp_f32_e32 v90, v90
	v_exp_f32_e32 v91, v91
	v_add_f32_e32 v88, 1.0, v88
	v_add_f32_e32 v89, 1.0, v89
	v_add_f32_e32 v90, 1.0, v90
	v_add_f32_e32 v91, 1.0, v91
	v_rcp_f32_e32 v88, v88
	v_rcp_f32_e32 v89, v89
	v_rcp_f32_e32 v90, v90
	v_rcp_f32_e32 v91, v91
	v_cvt_pk_bf16_f32 v88, v88, v89
	v_cvt_pk_bf16_f32 v89, v90, v91
	ds_write_b64 v172, v[88:89] offset:4096
	v_mul_f32_e32 v92, 0xbfb8aa3b, v92
	v_mul_f32_e32 v93, 0xbfb8aa3b, v93
	v_mul_f32_e32 v94, 0xbfb8aa3b, v94
	v_mul_f32_e32 v95, 0xbfb8aa3b, v95
	v_exp_f32_e32 v92, v92
	v_exp_f32_e32 v93, v93
	v_exp_f32_e32 v94, v94
	v_exp_f32_e32 v95, v95
	v_add_f32_e32 v92, 1.0, v92
	v_add_f32_e32 v93, 1.0, v93
	v_add_f32_e32 v94, 1.0, v94
	v_add_f32_e32 v95, 1.0, v95
	v_rcp_f32_e32 v92, v92
	v_rcp_f32_e32 v93, v93
	v_rcp_f32_e32 v94, v94
	v_rcp_f32_e32 v95, v95
	v_cvt_pk_bf16_f32 v92, v92, v93
	v_cvt_pk_bf16_f32 v93, v94, v95
	ds_write_b64 v173, v[92:93] offset:4096
	v_mul_f32_e32 v64, 0xbfb8aa3b, v64
	v_mul_f32_e32 v65, 0xbfb8aa3b, v65
	v_mul_f32_e32 v66, 0xbfb8aa3b, v66
	v_mul_f32_e32 v67, 0xbfb8aa3b, v67
	v_exp_f32_e32 v64, v64
	v_exp_f32_e32 v65, v65
	v_exp_f32_e32 v66, v66
	v_exp_f32_e32 v67, v67
	v_add_f32_e32 v64, 1.0, v64
	v_add_f32_e32 v65, 1.0, v65
	v_add_f32_e32 v66, 1.0, v66
	v_add_f32_e32 v67, 1.0, v67
	v_rcp_f32_e32 v64, v64
	v_rcp_f32_e32 v65, v65
	v_rcp_f32_e32 v66, v66
	v_rcp_f32_e32 v67, v67
	v_cvt_pk_bf16_f32 v64, v64, v65
	v_cvt_pk_bf16_f32 v65, v66, v67
	ds_write_b64 v174, v[64:65] offset:4096
	v_mul_f32_e32 v68, 0xbfb8aa3b, v68
	v_mul_f32_e32 v69, 0xbfb8aa3b, v69
	v_mul_f32_e32 v70, 0xbfb8aa3b, v70
	v_mul_f32_e32 v71, 0xbfb8aa3b, v71
	v_exp_f32_e32 v68, v68
	v_exp_f32_e32 v69, v69
	v_exp_f32_e32 v70, v70
	v_exp_f32_e32 v71, v71
	v_add_f32_e32 v68, 1.0, v68
	v_add_f32_e32 v69, 1.0, v69
	v_add_f32_e32 v70, 1.0, v70
	v_add_f32_e32 v71, 1.0, v71
	v_rcp_f32_e32 v68, v68
	v_rcp_f32_e32 v69, v69
	v_rcp_f32_e32 v70, v70
	v_rcp_f32_e32 v71, v71
	v_cvt_pk_bf16_f32 v68, v68, v69
	v_cvt_pk_bf16_f32 v69, v70, v71
	ds_write_b64 v175, v[68:69] offset:4096
	v_mul_f32_e32 v72, 0xbfb8aa3b, v72
	v_mul_f32_e32 v73, 0xbfb8aa3b, v73
	v_mul_f32_e32 v74, 0xbfb8aa3b, v74
	v_mul_f32_e32 v75, 0xbfb8aa3b, v75
	v_exp_f32_e32 v72, v72
	v_exp_f32_e32 v73, v73
	v_exp_f32_e32 v74, v74
	v_exp_f32_e32 v75, v75
	v_add_f32_e32 v72, 1.0, v72
	v_add_f32_e32 v73, 1.0, v73
	v_add_f32_e32 v74, 1.0, v74
	v_add_f32_e32 v75, 1.0, v75
	v_rcp_f32_e32 v72, v72
	v_rcp_f32_e32 v73, v73
	v_rcp_f32_e32 v74, v74
	v_rcp_f32_e32 v75, v75
	v_cvt_pk_bf16_f32 v72, v72, v73
	v_cvt_pk_bf16_f32 v73, v74, v75
	ds_write_b64 v176, v[72:73] offset:4096
	v_mul_f32_e32 v76, 0xbfb8aa3b, v76
	v_mul_f32_e32 v77, 0xbfb8aa3b, v77
	v_mul_f32_e32 v78, 0xbfb8aa3b, v78
	v_mul_f32_e32 v79, 0xbfb8aa3b, v79
	v_exp_f32_e32 v76, v76
	v_exp_f32_e32 v77, v77
	v_exp_f32_e32 v78, v78
	v_exp_f32_e32 v79, v79
	v_add_f32_e32 v76, 1.0, v76
	v_add_f32_e32 v77, 1.0, v77
	v_add_f32_e32 v78, 1.0, v78
	v_add_f32_e32 v79, 1.0, v79
	v_rcp_f32_e32 v76, v76
	v_rcp_f32_e32 v77, v77
	v_rcp_f32_e32 v78, v78
	v_rcp_f32_e32 v79, v79
	v_cvt_pk_bf16_f32 v76, v76, v77
	v_cvt_pk_bf16_f32 v77, v78, v79
	ds_write_b64 v177, v[76:77] offset:4096
	s_waitcnt lgkmcnt(0)
	ds_read_b128 v[96:99], v168
	ds_read_b128 v[100:103], v168 offset:1024
	ds_read_b128 v[104:107], v168 offset:2048
	ds_read_b128 v[108:111], v168 offset:3072
	ds_read_b128 v[112:115], v168 offset:4096
	ds_read_b128 v[116:119], v168 offset:5120
	ds_read_b128 v[120:123], v168 offset:6144
	ds_read_b128 v[124:127], v168 offset:7168
	s_waitcnt lgkmcnt(7)
	global_store_dwordx4 v169, v[96:99], s[20:21]
	v_add_u32_e32 v169, 0x8000, v169
	s_waitcnt lgkmcnt(6)
	global_store_dwordx4 v169, v[100:103], s[20:21]
	v_add_u32_e32 v169, 0x8000, v169
	s_waitcnt lgkmcnt(5)
; DEV u16 f2bf(float f) { return (u16)(pack2(f, f) & 0xffffu); }
; DEV float sigmoid_f(float x) { return __builtin_amdgcn_rcpf(1.f + __expf(-x)); }
; template <class F>
; DEV void acc_foreach(Acc& acc, int m0, int n0, F f) {
;   asm volatile("s_nop 7\n\ts_nop 7\n\ts_nop 3" ::: "memory");
;   const int tid = tidx_full();
;   const int wave = tid >> 6, lane = tid & 63;
;   const int wm = (wave >> 2) * 128, wn = (wave & 3) * 64;
;   const int lr = lane & 31, lh = lane >> 5;
; #pragma unroll
;   for (int i = 0; i < 4; ++i)
; #pragma unroll
;     for (int j = 0; j < 2; ++j)
; #pragma unroll
;       for (int r = 0; r < 16; ++r) {
;         const int m = m0 + wm + 32 * i + (r & 3) + 8 * (r >> 2) + 4 * lh;
;         const int n = n0 + wn + 32 * j + lr;
;         float v = acc[i][j][r];
;         f(m, n, v);
;         acc[i][j][r] = v;
;       }
; }
; DEV void phase_p1(const Params& p, int g, char* smem) {
;     ...
;         acc_foreach(acc, m0, n0, [&](int m, int n, float& v) { GT[(size_t)m * 2048 + (n - 2560)] = f2bf(sigmoid_f(v)); });
	global_store_dwordx4 v169, v[104:107], s[20:21]
	v_add_u32_e32 v169, 0x8000, v169
	s_waitcnt lgkmcnt(4)
	global_store_dwordx4 v169, v[108:111], s[20:21]
	v_add_u32_e32 v169, 0x8000, v169
	s_waitcnt lgkmcnt(3)
	global_store_dwordx4 v169, v[112:115], s[20:21]
	v_add_u32_e32 v169, 0x8000, v169
	s_waitcnt lgkmcnt(2)
	global_store_dwordx4 v169, v[116:119], s[20:21]
	v_add_u32_e32 v169, 0x8000, v169
	s_waitcnt lgkmcnt(1)
	global_store_dwordx4 v169, v[120:123], s[20:21]
	v_add_u32_e32 v169, 0x8000, v169
	s_waitcnt lgkmcnt(0)
	global_store_dwordx4 v169, v[124:127], s[20:21]
	v_add_u32_e32 v169, 0x8000, v169
	v_mul_f32_e32 v48, 0xbfb8aa3b, v48
	v_mul_f32_e32 v49, 0xbfb8aa3b, v49
	v_mul_f32_e32 v50, 0xbfb8aa3b, v50
	v_mul_f32_e32 v51, 0xbfb8aa3b, v51
	v_exp_f32_e32 v48, v48
	v_exp_f32_e32 v49, v49
	v_exp_f32_e32 v50, v50
	v_exp_f32_e32 v51, v51
	v_add_f32_e32 v48, 1.0, v48
	v_add_f32_e32 v49, 1.0, v49
	v_add_f32_e32 v50, 1.0, v50
	v_add_f32_e32 v51, 1.0, v51
	v_rcp_f32_e32 v48, v48
	v_rcp_f32_e32 v49, v49
	v_rcp_f32_e32 v50, v50
	v_rcp_f32_e32 v51, v51
	v_cvt_pk_bf16_f32 v48, v48, v49
	v_cvt_pk_bf16_f32 v49, v50, v51
	ds_write_b64 v170, v[48:49]
	v_mul_f32_e32 v52, 0xbfb8aa3b, v52
	v_mul_f32_e32 v53, 0xbfb8aa3b, v53
	v_mul_f32_e32 v54, 0xbfb8aa3b, v54
	v_mul_f32_e32 v55, 0xbfb8aa3b, v55
	v_exp_f32_e32 v52, v52
	v_exp_f32_e32 v53, v53
	v_exp_f32_e32 v54, v54
	v_exp_f32_e32 v55, v55
	v_add_f32_e32 v52, 1.0, v52
	v_add_f32_e32 v53, 1.0, v53
	v_add_f32_e32 v54, 1.0, v54
	v_add_f32_e32 v55, 1.0, v55
	v_rcp_f32_e32 v52, v52
	v_rcp_f32_e32 v53, v53
	v_rcp_f32_e32 v54, v54
	v_rcp_f32_e32 v55, v55
	v_cvt_pk_bf16_f32 v52, v52, v53
	v_cvt_pk_bf16_f32 v53, v54, v55
	ds_write_b64 v171, v[52:53]
	v_mul_f32_e32 v56, 0xbfb8aa3b, v56
	v_mul_f32_e32 v57, 0xbfb8aa3b, v57
	v_mul_f32_e32 v58, 0xbfb8aa3b, v58
	v_mul_f32_e32 v59, 0xbfb8aa3b, v59
	v_exp_f32_e32 v56, v56
	v_exp_f32_e32 v57, v57
	v_exp_f32_e32 v58, v58
	v_exp_f32_e32 v59, v59
	v_add_f32_e32 v56, 1.0, v56
	v_add_f32_e32 v57, 1.0, v57
	v_add_f32_e32 v58, 1.0, v58
	v_add_f32_e32 v59, 1.0, v59
	v_rcp_f32_e32 v56, v56
	v_rcp_f32_e32 v57, v57
	v_rcp_f32_e32 v58, v58
	v_rcp_f32_e32 v59, v59
	v_cvt_pk_bf16_f32 v56, v56, v57
	v_cvt_pk_bf16_f32 v57, v58, v59
	ds_write_b64 v172, v[56:57]
	v_mul_f32_e32 v60, 0xbfb8aa3b, v60
	v_mul_f32_e32 v61, 0xbfb8aa3b, v61
	v_mul_f32_e32 v62, 0xbfb8aa3b, v62
	v_mul_f32_e32 v63, 0xbfb8aa3b, v63
	v_exp_f32_e32 v60, v60
	v_exp_f32_e32 v61, v61
	v_exp_f32_e32 v62, v62
	v_exp_f32_e32 v63, v63
	v_add_f32_e32 v60, 1.0, v60
	v_add_f32_e32 v61, 1.0, v61
	v_add_f32_e32 v62, 1.0, v62
	v_add_f32_e32 v63, 1.0, v63
	v_rcp_f32_e32 v60, v60
	v_rcp_f32_e32 v61, v61
	v_rcp_f32_e32 v62, v62
	v_rcp_f32_e32 v63, v63
	v_cvt_pk_bf16_f32 v60, v60, v61
	v_cvt_pk_bf16_f32 v61, v62, v63
	ds_write_b64 v173, v[60:61]
	v_mul_f32_e32 v32, 0xbfb8aa3b, v32
	v_mul_f32_e32 v33, 0xbfb8aa3b, v33
	v_mul_f32_e32 v34, 0xbfb8aa3b, v34
	v_mul_f32_e32 v35, 0xbfb8aa3b, v35
	v_exp_f32_e32 v32, v32
	v_exp_f32_e32 v33, v33
	v_exp_f32_e32 v34, v34
	v_exp_f32_e32 v35, v35
	v_add_f32_e32 v32, 1.0, v32
	v_add_f32_e32 v33, 1.0, v33
	v_add_f32_e32 v34, 1.0, v34
	v_add_f32_e32 v35, 1.0, v35
	v_rcp_f32_e32 v32, v32
	v_rcp_f32_e32 v33, v33
	v_rcp_f32_e32 v34, v34
	v_rcp_f32_e32 v35, v35
	v_cvt_pk_bf16_f32 v32, v32, v33
	v_cvt_pk_bf16_f32 v33, v34, v35
	ds_write_b64 v174, v[32:33]
	v_mul_f32_e32 v36, 0xbfb8aa3b, v36
	v_mul_f32_e32 v37, 0xbfb8aa3b, v37
	v_mul_f32_e32 v38, 0xbfb8aa3b, v38
	v_mul_f32_e32 v39, 0xbfb8aa3b, v39
	v_exp_f32_e32 v36, v36
	v_exp_f32_e32 v37, v37
	v_exp_f32_e32 v38, v38
	v_exp_f32_e32 v39, v39
	v_add_f32_e32 v36, 1.0, v36
	v_add_f32_e32 v37, 1.0, v37
	v_add_f32_e32 v38, 1.0, v38
	v_add_f32_e32 v39, 1.0, v39
	v_rcp_f32_e32 v36, v36
	v_rcp_f32_e32 v37, v37
	v_rcp_f32_e32 v38, v38
	v_rcp_f32_e32 v39, v39
	v_cvt_pk_bf16_f32 v36, v36, v37
	v_cvt_pk_bf16_f32 v37, v38, v39
	ds_write_b64 v175, v[36:37]
	v_mul_f32_e32 v40, 0xbfb8aa3b, v40
	v_mul_f32_e32 v41, 0xbfb8aa3b, v41
	v_mul_f32_e32 v42, 0xbfb8aa3b, v42
	v_mul_f32_e32 v43, 0xbfb8aa3b, v43
	v_exp_f32_e32 v40, v40
	v_exp_f32_e32 v41, v41
	v_exp_f32_e32 v42, v42
	v_exp_f32_e32 v43, v43
	v_add_f32_e32 v40, 1.0, v40
	v_add_f32_e32 v41, 1.0, v41
	v_add_f32_e32 v42, 1.0, v42
	v_add_f32_e32 v43, 1.0, v43
	v_rcp_f32_e32 v40, v40
	v_rcp_f32_e32 v41, v41
	v_rcp_f32_e32 v42, v42
	v_rcp_f32_e32 v43, v43
	v_cvt_pk_bf16_f32 v40, v40, v41
	v_cvt_pk_bf16_f32 v41, v42, v43
	ds_write_b64 v176, v[40:41]
	v_mul_f32_e32 v44, 0xbfb8aa3b, v44
	v_mul_f32_e32 v45, 0xbfb8aa3b, v45
	v_mul_f32_e32 v46, 0xbfb8aa3b, v46
	v_mul_f32_e32 v47, 0xbfb8aa3b, v47
	v_exp_f32_e32 v44, v44
	v_exp_f32_e32 v45, v45
	v_exp_f32_e32 v46, v46
	v_exp_f32_e32 v47, v47
	v_add_f32_e32 v44, 1.0, v44
	v_add_f32_e32 v45, 1.0, v45
	v_add_f32_e32 v46, 1.0, v46
	v_add_f32_e32 v47, 1.0, v47
	v_rcp_f32_e32 v44, v44
	v_rcp_f32_e32 v45, v45
	v_rcp_f32_e32 v46, v46
	v_rcp_f32_e32 v47, v47
	v_cvt_pk_bf16_f32 v44, v44, v45
	v_cvt_pk_bf16_f32 v45, v46, v47
	ds_write_b64 v177, v[44:45]
	v_mul_f32_e32 v16, 0xbfb8aa3b, v16
	v_mul_f32_e32 v17, 0xbfb8aa3b, v17
	v_mul_f32_e32 v18, 0xbfb8aa3b, v18
	v_mul_f32_e32 v19, 0xbfb8aa3b, v19
	v_exp_f32_e32 v16, v16
	v_exp_f32_e32 v17, v17
	v_exp_f32_e32 v18, v18
	v_exp_f32_e32 v19, v19
	v_add_f32_e32 v16, 1.0, v16
	v_add_f32_e32 v17, 1.0, v17
; DEV u16 f2bf(float f) { return (u16)(pack2(f, f) & 0xffffu); }
; DEV float sigmoid_f(float x) { return __builtin_amdgcn_rcpf(1.f + __expf(-x)); }
; template <class F>
; DEV void acc_foreach(Acc& acc, int m0, int n0, F f) {
;   asm volatile("s_nop 7\n\ts_nop 7\n\ts_nop 3" ::: "memory");
;   const int tid = tidx_full();
;   const int wave = tid >> 6, lane = tid & 63;
;   const int wm = (wave >> 2) * 128, wn = (wave & 3) * 64;
;   const int lr = lane & 31, lh = lane >> 5;
; #pragma unroll
;   for (int i = 0; i < 4; ++i)
; #pragma unroll
;     for (int j = 0; j < 2; ++j)
; #pragma unroll
;       for (int r = 0; r < 16; ++r) {
;         const int m = m0 + wm + 32 * i + (r & 3) + 8 * (r >> 2) + 4 * lh;
;         const int n = n0 + wn + 32 * j + lr;
;         float v = acc[i][j][r];
;         f(m, n, v);
;         acc[i][j][r] = v;
;       }
; }
; DEV void phase_p1(const Params& p, int g, char* smem) {
;     ...
;         acc_foreach(acc, m0, n0, [&](int m, int n, float& v) { GT[(size_t)m * 2048 + (n - 2560)] = f2bf(sigmoid_f(v)); });
	v_add_f32_e32 v18, 1.0, v18
	v_add_f32_e32 v19, 1.0, v19
	v_rcp_f32_e32 v16, v16
	v_rcp_f32_e32 v17, v17
	v_rcp_f32_e32 v18, v18
	v_rcp_f32_e32 v19, v19
	v_cvt_pk_bf16_f32 v16, v16, v17
	v_cvt_pk_bf16_f32 v17, v18, v19
	ds_write_b64 v170, v[16:17] offset:4096
	v_mul_f32_e32 v20, 0xbfb8aa3b, v20
	v_mul_f32_e32 v21, 0xbfb8aa3b, v21
	v_mul_f32_e32 v22, 0xbfb8aa3b, v22
	v_mul_f32_e32 v23, 0xbfb8aa3b, v23
	v_exp_f32_e32 v20, v20
	v_exp_f32_e32 v21, v21
	v_exp_f32_e32 v22, v22
	v_exp_f32_e32 v23, v23
	v_add_f32_e32 v20, 1.0, v20
	v_add_f32_e32 v21, 1.0, v21
	v_add_f32_e32 v22, 1.0, v22
	v_add_f32_e32 v23, 1.0, v23
	v_rcp_f32_e32 v20, v20
	v_rcp_f32_e32 v21, v21
	v_rcp_f32_e32 v22, v22
	v_rcp_f32_e32 v23, v23
	v_cvt_pk_bf16_f32 v20, v20, v21
	v_cvt_pk_bf16_f32 v21, v22, v23
	ds_write_b64 v171, v[20:21] offset:4096
	v_mul_f32_e32 v24, 0xbfb8aa3b, v24
	v_mul_f32_e32 v25, 0xbfb8aa3b, v25
	v_mul_f32_e32 v26, 0xbfb8aa3b, v26
	v_mul_f32_e32 v27, 0xbfb8aa3b, v27
	v_exp_f32_e32 v24, v24
	v_exp_f32_e32 v25, v25
	v_exp_f32_e32 v26, v26
	v_exp_f32_e32 v27, v27
	v_add_f32_e32 v24, 1.0, v24
	v_add_f32_e32 v25, 1.0, v25
	v_add_f32_e32 v26, 1.0, v26
	v_add_f32_e32 v27, 1.0, v27
	v_rcp_f32_e32 v24, v24
	v_rcp_f32_e32 v25, v25
	v_rcp_f32_e32 v26, v26
	v_rcp_f32_e32 v27, v27
	v_cvt_pk_bf16_f32 v24, v24, v25
	v_cvt_pk_bf16_f32 v25, v26, v27
	ds_write_b64 v172, v[24:25] offset:4096
	v_mul_f32_e32 v28, 0xbfb8aa3b, v28
	v_mul_f32_e32 v29, 0xbfb8aa3b, v29
	v_mul_f32_e32 v30, 0xbfb8aa3b, v30
	v_mul_f32_e32 v31, 0xbfb8aa3b, v31
	v_exp_f32_e32 v28, v28
	v_exp_f32_e32 v29, v29
	v_exp_f32_e32 v30, v30
	v_exp_f32_e32 v31, v31
	v_add_f32_e32 v28, 1.0, v28
	v_add_f32_e32 v29, 1.0, v29
	v_add_f32_e32 v30, 1.0, v30
	v_add_f32_e32 v31, 1.0, v31
	v_rcp_f32_e32 v28, v28
	v_rcp_f32_e32 v29, v29
	v_rcp_f32_e32 v30, v30
	v_rcp_f32_e32 v31, v31
	v_cvt_pk_bf16_f32 v28, v28, v29
	v_cvt_pk_bf16_f32 v29, v30, v31
	ds_write_b64 v173, v[28:29] offset:4096
	v_mul_f32_e32 v0, 0xbfb8aa3b, v0
	v_mul_f32_e32 v1, 0xbfb8aa3b, v1
	v_mul_f32_e32 v2, 0xbfb8aa3b, v2
	v_mul_f32_e32 v3, 0xbfb8aa3b, v3
	v_exp_f32_e32 v0, v0
	v_exp_f32_e32 v1, v1
	v_exp_f32_e32 v2, v2
	v_exp_f32_e32 v3, v3
	v_add_f32_e32 v0, 1.0, v0
	v_add_f32_e32 v1, 1.0, v1
	v_add_f32_e32 v2, 1.0, v2
	v_add_f32_e32 v3, 1.0, v3
	v_rcp_f32_e32 v0, v0
	v_rcp_f32_e32 v1, v1
	v_rcp_f32_e32 v2, v2
	v_rcp_f32_e32 v3, v3
	v_cvt_pk_bf16_f32 v0, v0, v1
	v_cvt_pk_bf16_f32 v1, v2, v3
	ds_write_b64 v174, v[0:1] offset:4096
	v_mul_f32_e32 v4, 0xbfb8aa3b, v4
	v_mul_f32_e32 v5, 0xbfb8aa3b, v5
	v_mul_f32_e32 v6, 0xbfb8aa3b, v6
	v_mul_f32_e32 v7, 0xbfb8aa3b, v7
	v_exp_f32_e32 v4, v4
	v_exp_f32_e32 v5, v5
	v_exp_f32_e32 v6, v6
	v_exp_f32_e32 v7, v7
	v_add_f32_e32 v4, 1.0, v4
	v_add_f32_e32 v5, 1.0, v5
	v_add_f32_e32 v6, 1.0, v6
	v_add_f32_e32 v7, 1.0, v7
	v_rcp_f32_e32 v4, v4
	v_rcp_f32_e32 v5, v5
	v_rcp_f32_e32 v6, v6
	v_rcp_f32_e32 v7, v7
	v_cvt_pk_bf16_f32 v4, v4, v5
	v_cvt_pk_bf16_f32 v5, v6, v7
	ds_write_b64 v175, v[4:5] offset:4096
	v_mul_f32_e32 v8, 0xbfb8aa3b, v8
	v_mul_f32_e32 v9, 0xbfb8aa3b, v9
	v_mul_f32_e32 v10, 0xbfb8aa3b, v10
	v_mul_f32_e32 v11, 0xbfb8aa3b, v11
	v_exp_f32_e32 v8, v8
	v_exp_f32_e32 v9, v9
	v_exp_f32_e32 v10, v10
	v_exp_f32_e32 v11, v11
	v_add_f32_e32 v8, 1.0, v8
	v_add_f32_e32 v9, 1.0, v9
	v_add_f32_e32 v10, 1.0, v10
	v_add_f32_e32 v11, 1.0, v11
	v_rcp_f32_e32 v8, v8
	v_rcp_f32_e32 v9, v9
	v_rcp_f32_e32 v10, v10
	v_rcp_f32_e32 v11, v11
	v_cvt_pk_bf16_f32 v8, v8, v9
	v_cvt_pk_bf16_f32 v9, v10, v11
	ds_write_b64 v176, v[8:9] offset:4096
	v_mul_f32_e32 v12, 0xbfb8aa3b, v12
	v_mul_f32_e32 v13, 0xbfb8aa3b, v13
	v_mul_f32_e32 v14, 0xbfb8aa3b, v14
	v_mul_f32_e32 v15, 0xbfb8aa3b, v15
	v_exp_f32_e32 v12, v12
	v_exp_f32_e32 v13, v13
	v_exp_f32_e32 v14, v14
	v_exp_f32_e32 v15, v15
	v_add_f32_e32 v12, 1.0, v12
	v_add_f32_e32 v13, 1.0, v13
	v_add_f32_e32 v14, 1.0, v14
	v_add_f32_e32 v15, 1.0, v15
	v_rcp_f32_e32 v12, v12
	v_rcp_f32_e32 v13, v13
	v_rcp_f32_e32 v14, v14
	v_rcp_f32_e32 v15, v15
	v_cvt_pk_bf16_f32 v12, v12, v13
	v_cvt_pk_bf16_f32 v13, v14, v15
	ds_write_b64 v177, v[12:13] offset:4096
	s_waitcnt lgkmcnt(0)
	ds_read_b128 v[64:67], v168
	ds_read_b128 v[68:71], v168 offset:1024
	ds_read_b128 v[72:75], v168 offset:2048
	ds_read_b128 v[76:79], v168 offset:3072
	ds_read_b128 v[80:83], v168 offset:4096
	ds_read_b128 v[84:87], v168 offset:5120
	ds_read_b128 v[88:91], v168 offset:6144
	ds_read_b128 v[92:95], v168 offset:7168
	s_waitcnt lgkmcnt(7)
	global_store_dwordx4 v169, v[64:67], s[20:21]
	v_add_u32_e32 v169, 0x8000, v169
	s_waitcnt lgkmcnt(6)
	global_store_dwordx4 v169, v[68:71], s[20:21]
	v_add_u32_e32 v169, 0x8000, v169
	s_waitcnt lgkmcnt(5)
	global_store_dwordx4 v169, v[72:75], s[20:21]
	v_add_u32_e32 v169, 0x8000, v169
	s_waitcnt lgkmcnt(4)
	global_store_dwordx4 v169, v[76:79], s[20:21]
	v_add_u32_e32 v169, 0x8000, v169
	s_waitcnt lgkmcnt(3)
	global_store_dwordx4 v169, v[80:83], s[20:21]
	v_add_u32_e32 v169, 0x8000, v169
	s_waitcnt lgkmcnt(2)
	global_store_dwordx4 v169, v[84:87], s[20:21]
	v_add_u32_e32 v169, 0x8000, v169
	s_waitcnt lgkmcnt(1)
	global_store_dwordx4 v169, v[88:91], s[20:21]
	v_add_u32_e32 v169, 0x8000, v169
	s_waitcnt lgkmcnt(0)
	s_barrier
	global_store_dwordx4 v169, v[92:95], s[20:21]
	v_add_u32_e32 v169, 0x8000, v169
	s_branch .LBB0_261

; template <class AL, class BL>
; DEV void gemm_mainloop_p(Acc& acc, const AL& al, const BL& bl, int m0, int n0, int m0n, int n0n, int K, char* lds,
;                          GemmPipe& gp) {
;   const int tid = tidx_full();
;   const int wave = tid >> 6, lane = tid & 63;
;   const int wm = (wave >> 2) * 128, wn = (wave & 3) * 64;
;   const int lr = lane & 31, lh = lane >> 5;
;   const int nk = K / BK;
;   if (!gp.primed) {
;     gp.ra = al.load(tid, m0, 0);
;     gp.rb = bl.load(tid, n0, 0);
;     __syncthreads();
;     al.store(tid, lds, gp.ra);
;     bl.store(tid, lds + TILE_BYTES, gp.rb);
;     gp.ra = al.load(tid, m0, BK);
;     gp.rb = bl.load(tid, n0, BK);
;     __syncthreads();
;   }
.LBB0_560:
	s_and_b64 vcc, exec, s[2:3]
	s_lshl_b32 s11, s7, 8
	s_lshl_b32 s2, s8, 8
	v_lshrrev_b32_e32 v149, 6, v202
	v_and_b32_e32 v148, 63, v202
	s_nop 0
	v_readfirstlane_b32 s9, v149
	v_lshrrev_b32_e32 v150, 3, v148
	v_lshl_add_u32 v150, v149, 5, v150
	v_and_b32_e32 v151, 7, v148
	v_lshrrev_b32_e32 v128, 4, v148
	v_xor_b32_e32 v151, v128, v151
	v_lshlrev_b32_e32 v151, 4, v151
	s_lshl_b32 s9, s9, 12
	v_add_u32_e32 v128, s11, v150
	v_lshlrev_b32_e32 v128, 11, v128
	v_add_u32_e32 v128, v128, v151
	v_add_u32_e32 v129, 0x4000, v128
	v_add_u32_e32 v130, 0x8000, v128
	v_add_u32_e32 v131, 0xc000, v128
	v_xor_b32_e32 v129, 0x40, v129
	v_xor_b32_e32 v131, 0x40, v131
	v_add_u32_e32 v132, s2, v150
	v_lshlrev_b32_e32 v132, 11, v132
	v_add_u32_e32 v132, v132, v151
	v_add_u32_e32 v133, 0x4000, v132
	v_add_u32_e32 v134, 0x8000, v132
	v_add_u32_e32 v135, 0xc000, v132
	v_xor_b32_e32 v133, 0x40, v133
	v_xor_b32_e32 v135, 0x40, v135
	v_lshrrev_b32_e32 v144, 1, v148
	v_and_b32_e32 v144, 7, v144
	v_lshrrev_b32_e32 v145, 5, v148
	v_xor_b32_e32 v144, v144, v145
	v_lshlrev_b32_e32 v144, 4, v144
	v_and_b32_e32 v145, 31, v148
	v_lshlrev_b32_e32 v145, 7, v145
	v_lshrrev_b32_e32 v136, 2, v149
	v_lshl_add_u32 v136, v136, 14, v145
	v_and_b32_e32 v140, 3, v149
	v_lshl_add_u32 v140, v140, 13, v145
	v_add_u32_e32 v140, 0x10000, v140
	v_xor_b32_e32 v139, 0x60, v144
	v_add_u32_e32 v139, v136, v139
	v_xor_b32_e32 v138, 0x40, v144
	v_add_u32_e32 v138, v136, v138
	v_xor_b32_e32 v137, 0x20, v144
	v_add_u32_e32 v137, v136, v137
	v_add_u32_e32 v136, v136, v144
	v_xor_b32_e32 v143, 0x60, v144
	v_add_u32_e32 v143, v140, v143
	v_xor_b32_e32 v142, 0x40, v144
	v_add_u32_e32 v142, v140, v142
	v_xor_b32_e32 v141, 0x20, v144
	v_add_u32_e32 v141, v140, v141
	v_add_u32_e32 v140, v140, v144
	s_mov_b64 s[14:15], s[88:89]
	s_mov_b64 s[16:17], s[64:65]
	s_cbranch_vccnz .Lp1b_primed
	s_add_u32 m0, s9, 0x0
	s_nop 0
	global_load_lds_dwordx4 v128, s[14:15]
	s_add_u32 m0, m0, 0x400
	s_nop 0
	global_load_lds_dwordx4 v129, s[14:15]
	s_add_u32 m0, m0, 0x400
	s_nop 0
	global_load_lds_dwordx4 v130, s[14:15]
	s_add_u32 m0, m0, 0x400
	s_nop 0
	global_load_lds_dwordx4 v131, s[14:15]
	s_add_u32 m0, s9, 0x10000
	s_nop 0
	global_load_lds_dwordx4 v132, s[16:17]
	s_add_u32 m0, m0, 0x400
	s_nop 0
	global_load_lds_dwordx4 v133, s[16:17]
	s_add_u32 m0, m0, 0x400
	s_nop 0
	global_load_lds_dwordx4 v134, s[16:17]
	s_add_u32 m0, m0, 0x400
	s_nop 0
	global_load_lds_dwordx4 v135, s[16:17]
.Lp1b_primed:
	s_add_u32 s14, s14, 0x80
	s_addc_u32 s15, s15, 0
	s_add_u32 s16, s16, 0x80
	s_addc_u32 s17, s17, 0
	v_mov_b32_e32 v0, 0
	v_mov_b32_e32 v1, 0
	v_mov_b64_e32 v[2:3], v[0:1]
	v_mov_b64_e32 v[4:5], v[0:1]
	v_mov_b64_e32 v[6:7], v[0:1]
	v_mov_b64_e32 v[8:9], v[0:1]
	v_mov_b64_e32 v[10:11], v[0:1]
	v_mov_b64_e32 v[12:13], v[0:1]
	v_mov_b64_e32 v[14:15], v[0:1]
	v_mov_b64_e32 v[16:17], v[0:1]
	v_mov_b64_e32 v[18:19], v[0:1]
	v_mov_b64_e32 v[20:21], v[0:1]
	v_mov_b64_e32 v[22:23], v[0:1]
	v_mov_b64_e32 v[24:25], v[0:1]
	v_mov_b64_e32 v[26:27], v[0:1]
	v_mov_b64_e32 v[28:29], v[0:1]
	v_mov_b64_e32 v[30:31], v[0:1]
	v_mov_b64_e32 v[32:33], v[0:1]
	v_mov_b64_e32 v[34:35], v[0:1]
	v_mov_b64_e32 v[36:37], v[0:1]
	v_mov_b64_e32 v[38:39], v[0:1]
	v_mov_b64_e32 v[40:41], v[0:1]
	v_mov_b64_e32 v[42:43], v[0:1]
	v_mov_b64_e32 v[44:45], v[0:1]
	v_mov_b64_e32 v[46:47], v[0:1]
	v_mov_b64_e32 v[48:49], v[0:1]
	v_mov_b64_e32 v[50:51], v[0:1]
	v_mov_b64_e32 v[52:53], v[0:1]
	v_mov_b64_e32 v[54:55], v[0:1]
	v_mov_b64_e32 v[56:57], v[0:1]
	v_mov_b64_e32 v[58:59], v[0:1]
	v_mov_b64_e32 v[60:61], v[0:1]
	v_mov_b64_e32 v[62:63], v[0:1]
	v_mov_b64_e32 v[64:65], v[0:1]
	v_mov_b64_e32 v[66:67], v[0:1]
	v_mov_b64_e32 v[68:69], v[0:1]
	v_mov_b64_e32 v[70:71], v[0:1]
	v_mov_b64_e32 v[72:73], v[0:1]
	v_mov_b64_e32 v[74:75], v[0:1]
	v_mov_b64_e32 v[76:77], v[0:1]
	v_mov_b64_e32 v[78:79], v[0:1]
	v_mov_b64_e32 v[80:81], v[0:1]
	v_mov_b64_e32 v[82:83], v[0:1]
	v_mov_b64_e32 v[84:85], v[0:1]
	v_mov_b64_e32 v[86:87], v[0:1]
	v_mov_b64_e32 v[88:89], v[0:1]
	v_mov_b64_e32 v[90:91], v[0:1]
	v_mov_b64_e32 v[92:93], v[0:1]
	v_mov_b64_e32 v[94:95], v[0:1]
	v_mov_b64_e32 v[96:97], v[0:1]
	v_mov_b64_e32 v[98:99], v[0:1]
	v_mov_b64_e32 v[100:101], v[0:1]
	v_mov_b64_e32 v[102:103], v[0:1]
	v_mov_b64_e32 v[104:105], v[0:1]
	v_mov_b64_e32 v[106:107], v[0:1]
	v_mov_b64_e32 v[108:109], v[0:1]
	v_mov_b64_e32 v[110:111], v[0:1]
	v_mov_b64_e32 v[112:113], v[0:1]
	v_mov_b64_e32 v[114:115], v[0:1]
	v_mov_b64_e32 v[116:117], v[0:1]
	v_mov_b64_e32 v[118:119], v[0:1]
	v_mov_b64_e32 v[120:121], v[0:1]
	v_mov_b64_e32 v[122:123], v[0:1]
	v_mov_b64_e32 v[124:125], v[0:1]
	v_mov_b64_e32 v[126:127], v[0:1]
	s_mov_b32 s10, 0
	s_waitcnt vmcnt(0)
	s_barrier
; template <class AL, class BL>
; DEV void gemm_ktile(Acc& acc, const char* A, const char* B, int wm, int wn, int lr, int lh, const AL& al, const BL& bl,
;                     int tid, int m0, int n0, int knext, char* nxt, R4& ra, R4& rb) {
;   bf16x8 a[2][4], b[2][2];
;   const char* pa = A + (wm + lr) * LDSROW + lh * 16;
;   const char* pb = B + (wn + lr) * LDSROW + lh * 16;
; #pragma unroll
;   for (int i = 0; i < 4; ++i) a[0][i] = *(const bf16x8*)(pa + 32 * i * LDSROW);
; #pragma unroll
;   for (int j = 0; j < 2; ++j) b[0][j] = *(const bf16x8*)(pb + 32 * j * LDSROW);
; #pragma unroll
;   for (int ks = 0; ks < 4; ++ks) {
;     const int cur = ks & 1, nx = cur ^ 1;
;     if (ks < 3) {
; #pragma unroll
;       for (int i = 0; i < 4; ++i) a[nx][i] = *(const bf16x8*)(pa + 32 * i * LDSROW + (ks + 1) * 32);
; #pragma unroll
;       for (int j = 0; j < 2; ++j) b[nx][j] = *(const bf16x8*)(pb + 32 * j * LDSROW + (ks + 1) * 32);
;     }
;     __builtin_amdgcn_sched_barrier(0);
; #pragma unroll
;     for (int i = 0; i < 4; ++i)
; #pragma unroll
;       for (int j = 0; j < 2; ++j)
;         acc[i][j] = __builtin_amdgcn_mfma_f32_32x32x16_bf16(a[cur][i], b[cur][j], acc[i][j], 0, 0, 0);
;     __builtin_amdgcn_sched_barrier(0);
;     if (ks == 1) {
;       al.store(tid, nxt, ra);
;       bl.store(tid, nxt + TILE_BYTES, rb);
;       __builtin_amdgcn_sched_barrier(0);
;       ra = al.load(tid, m0, knext);
;       rb = bl.load(tid, n0, knext);
;       __builtin_amdgcn_sched_barrier(0);
;     }
;   }
; template <class AL, class BL>
; DEV void gemm_mainloop_p(Acc& acc, const AL& al, const BL& bl, int m0, int n0, int m0n, int n0n, int K, char* lds,
;                          GemmPipe& gp) {
;     ...
;   for (int kt = 0; kt < nk; ++kt) {
;     const char* cur = lds + (kt & 1) * 2 * TILE_BYTES;
;     char* nxt = lds + ((kt + 1) & 1) * 2 * TILE_BYTES;
;     const bool wrap = (kt + 2 >= nk);
;     const int kk = (wrap ? kt + 2 - nk : kt + 2) * BK;
;     const int mr = wrap ? m0n : m0, nr = wrap ? n0n : n0;
;     __builtin_amdgcn_sched_barrier(0);
;     gemm_ktile(acc, cur, cur + TILE_BYTES, wm, wn, lr, lh, al, bl, tid, mr, nr, kk, nxt, gp.ra, gp.rb);
;     __builtin_amdgcn_sched_barrier(0);
;     __syncthreads();
;   }
.Lp1b_kloop:
	s_add_u32 m0, s9, 0x8000
	s_nop 0
	global_load_lds_dwordx4 v128, s[14:15]
	s_add_u32 m0, m0, 0x400
	s_nop 0
	global_load_lds_dwordx4 v129, s[14:15]
	s_add_u32 m0, m0, 0x400
	s_nop 0
	global_load_lds_dwordx4 v130, s[14:15]
	s_add_u32 m0, m0, 0x400
	s_nop 0
	global_load_lds_dwordx4 v131, s[14:15]
	s_add_u32 m0, s9, 0x18000
	s_nop 0
	global_load_lds_dwordx4 v132, s[16:17]
	s_add_u32 m0, m0, 0x400
	s_nop 0
	global_load_lds_dwordx4 v133, s[16:17]
	s_add_u32 m0, m0, 0x400
	s_nop 0
	global_load_lds_dwordx4 v134, s[16:17]
	s_add_u32 m0, m0, 0x400
	s_nop 0
	global_load_lds_dwordx4 v135, s[16:17]
	s_add_u32 s14, s14, 0x80
	s_addc_u32 s15, s15, 0
	s_add_u32 s16, s16, 0x80
	s_addc_u32 s17, s17, 0
	ds_read_b128 v[174:177], v136
	ds_read_b128 v[178:181], v137
	ds_read_b128 v[182:185], v136 offset:4096
	ds_read_b128 v[186:189], v137 offset:4096
	ds_read_b128 v[190:193], v136 offset:8192
	ds_read_b128 v[194:197], v137 offset:8192
	ds_read_b128 v[198:201], v136 offset:12288
	ds_read_b128 v[222:225], v137 offset:12288
	ds_read_b128 v[226:229], v140
	ds_read_b128 v[230:233], v141
	ds_read_b128 v[234:237], v140 offset:4096
	ds_read_b128 v[238:241], v141 offset:4096
	s_waitcnt lgkmcnt(3)
	v_mfma_f32_32x32x16_bf16 v[112:127], v[226:229], v[174:177], v[112:127]
	s_waitcnt lgkmcnt(1)
	v_mfma_f32_32x32x16_bf16 v[96:111], v[234:237], v[174:177], v[96:111]
	v_mfma_f32_32x32x16_bf16 v[80:95], v[226:229], v[182:185], v[80:95]
	v_mfma_f32_32x32x16_bf16 v[64:79], v[234:237], v[182:185], v[64:79]
	v_mfma_f32_32x32x16_bf16 v[48:63], v[226:229], v[190:193], v[48:63]
	v_mfma_f32_32x32x16_bf16 v[32:47], v[234:237], v[190:193], v[32:47]
	v_mfma_f32_32x32x16_bf16 v[16:31], v[226:229], v[198:201], v[16:31]
	v_mfma_f32_32x32x16_bf16 v[0:15], v[234:237], v[198:201], v[0:15]
	ds_read_b128 v[174:177], v138
	ds_read_b128 v[182:185], v138 offset:4096
	ds_read_b128 v[190:193], v138 offset:8192
	ds_read_b128 v[198:201], v138 offset:12288
	ds_read_b128 v[226:229], v142
	ds_read_b128 v[234:237], v142 offset:4096
	v_mfma_f32_32x32x16_bf16 v[112:127], v[230:233], v[178:181], v[112:127]
	s_waitcnt lgkmcnt(6)
	v_mfma_f32_32x32x16_bf16 v[96:111], v[238:241], v[178:181], v[96:111]
	v_mfma_f32_32x32x16_bf16 v[80:95], v[230:233], v[186:189], v[80:95]
	v_mfma_f32_32x32x16_bf16 v[64:79], v[238:241], v[186:189], v[64:79]
	v_mfma_f32_32x32x16_bf16 v[48:63], v[230:233], v[194:197], v[48:63]
	v_mfma_f32_32x32x16_bf16 v[32:47], v[238:241], v[194:197], v[32:47]
	v_mfma_f32_32x32x16_bf16 v[16:31], v[230:233], v[222:225], v[16:31]
	v_mfma_f32_32x32x16_bf16 v[0:15], v[238:241], v[222:225], v[0:15]
	ds_read_b128 v[178:181], v139
	ds_read_b128 v[186:189], v139 offset:4096
	ds_read_b128 v[194:197], v139 offset:8192
	ds_read_b128 v[222:225], v139 offset:12288
	ds_read_b128 v[230:233], v143
	ds_read_b128 v[238:241], v143 offset:4096
	s_waitcnt lgkmcnt(6)
	v_mfma_f32_32x32x16_bf16 v[112:127], v[226:229], v[174:177], v[112:127]
	v_mfma_f32_32x32x16_bf16 v[96:111], v[234:237], v[174:177], v[96:111]
	v_mfma_f32_32x32x16_bf16 v[80:95], v[226:229], v[182:185], v[80:95]
	v_mfma_f32_32x32x16_bf16 v[64:79], v[234:237], v[182:185], v[64:79]
	v_mfma_f32_32x32x16_bf16 v[48:63], v[226:229], v[190:193], v[48:63]
	v_mfma_f32_32x32x16_bf16 v[32:47], v[234:237], v[190:193], v[32:47]
	v_mfma_f32_32x32x16_bf16 v[16:31], v[226:229], v[198:201], v[16:31]
	v_mfma_f32_32x32x16_bf16 v[0:15], v[234:237], v[198:201], v[0:15]
	s_waitcnt lgkmcnt(1)
	v_mfma_f32_32x32x16_bf16 v[112:127], v[230:233], v[178:181], v[112:127]
	s_waitcnt lgkmcnt(0)
	v_mfma_f32_32x32x16_bf16 v[96:111], v[238:241], v[178:181], v[96:111]
	v_mfma_f32_32x32x16_bf16 v[80:95], v[230:233], v[186:189], v[80:95]
	v_mfma_f32_32x32x16_bf16 v[64:79], v[238:241], v[186:189], v[64:79]
	v_mfma_f32_32x32x16_bf16 v[48:63], v[230:233], v[194:197], v[48:63]
	v_mfma_f32_32x32x16_bf16 v[32:47], v[238:241], v[194:197], v[32:47]
	v_mfma_f32_32x32x16_bf16 v[16:31], v[230:233], v[222:225], v[16:31]
	v_mfma_f32_32x32x16_bf16 v[0:15], v[238:241], v[222:225], v[0:15]
	s_waitcnt vmcnt(0)
	s_barrier
	s_cmp_eq_u32 s10, 7
	s_cbranch_scc1 .Lp1b_skipdma
	s_add_u32 m0, s9, 0x0
	s_nop 0
	global_load_lds_dwordx4 v128, s[14:15]
	s_add_u32 m0, m0, 0x400
	s_nop 0
	global_load_lds_dwordx4 v129, s[14:15]
	s_add_u32 m0, m0, 0x400
	s_nop 0
	global_load_lds_dwordx4 v130, s[14:15]
	s_add_u32 m0, m0, 0x400
	s_nop 0
	global_load_lds_dwordx4 v131, s[14:15]
	s_add_u32 m0, s9, 0x10000
	s_nop 0
	global_load_lds_dwordx4 v132, s[16:17]
	s_add_u32 m0, m0, 0x400
	s_nop 0
	global_load_lds_dwordx4 v133, s[16:17]
	s_add_u32 m0, m0, 0x400
	s_nop 0
	global_load_lds_dwordx4 v134, s[16:17]
	s_add_u32 m0, m0, 0x400
	s_nop 0
	global_load_lds_dwordx4 v135, s[16:17]
	s_add_u32 s14, s14, 0x80
	s_addc_u32 s15, s15, 0
	s_add_u32 s16, s16, 0x80
	s_addc_u32 s17, s17, 0
; template <class AL, class BL>
; DEV void gemm_ktile(Acc& acc, const char* A, const char* B, int wm, int wn, int lr, int lh, const AL& al, const BL& bl,
;                     int tid, int m0, int n0, int knext, char* nxt, R4& ra, R4& rb) {
;   bf16x8 a[2][4], b[2][2];
;   const char* pa = A + (wm + lr) * LDSROW + lh * 16;
;   const char* pb = B + (wn + lr) * LDSROW + lh * 16;
; #pragma unroll
;   for (int i = 0; i < 4; ++i) a[0][i] = *(const bf16x8*)(pa + 32 * i * LDSROW);
; #pragma unroll
;   for (int j = 0; j < 2; ++j) b[0][j] = *(const bf16x8*)(pb + 32 * j * LDSROW);
; #pragma unroll
;   for (int ks = 0; ks < 4; ++ks) {
;     const int cur = ks & 1, nx = cur ^ 1;
;     if (ks < 3) {
; #pragma unroll
;       for (int i = 0; i < 4; ++i) a[nx][i] = *(const bf16x8*)(pa + 32 * i * LDSROW + (ks + 1) * 32);
; #pragma unroll
;       for (int j = 0; j < 2; ++j) b[nx][j] = *(const bf16x8*)(pb + 32 * j * LDSROW + (ks + 1) * 32);
;     }
;     __builtin_amdgcn_sched_barrier(0);
; #pragma unroll
;     for (int i = 0; i < 4; ++i)
; #pragma unroll
;       for (int j = 0; j < 2; ++j)
;         acc[i][j] = __builtin_amdgcn_mfma_f32_32x32x16_bf16(a[cur][i], b[cur][j], acc[i][j], 0, 0, 0);
;     __builtin_amdgcn_sched_barrier(0);
;     if (ks == 1) {
;       al.store(tid, nxt, ra);
;       bl.store(tid, nxt + TILE_BYTES, rb);
;       __builtin_amdgcn_sched_barrier(0);
;       ra = al.load(tid, m0, knext);
;       rb = bl.load(tid, n0, knext);
;       __builtin_amdgcn_sched_barrier(0);
;     }
;   }
; DEV void phase_p1(const Params& p, int g, char* smem) {
;     ...
;     for (int iter = 0;; ++iter) {
;       int cm, tn, cmn, tnn;
;       if (!tile_map(iter, 6, 128, cm, tn)) break;
;       const bool more = tile_map(iter + 1, 6, 128, cmn, tnn);
;       if (!more) { cmn = cm; tnn = tn; }
;       Acc acc;
;       acc_zero(acc);
;       const int m0 = cm * 256, n0 = tn * 256;
;       RowLoader al{WinT, 1024}, bl{H, 1024};
;       gemm_mainloop_p(acc, al, bl, m0, n0, cmn * 256, tnn * 256, 1024, smem, gp);
;       gp.primed = more;
.Lp1b_skipdma:
	ds_read_b128 v[174:177], v136 offset:32768
	ds_read_b128 v[178:181], v137 offset:32768
	ds_read_b128 v[182:185], v136 offset:36864
	ds_read_b128 v[186:189], v137 offset:36864
	ds_read_b128 v[190:193], v136 offset:40960
	ds_read_b128 v[194:197], v137 offset:40960
	ds_read_b128 v[198:201], v136 offset:45056
	ds_read_b128 v[222:225], v137 offset:45056
	ds_read_b128 v[226:229], v140 offset:32768
	ds_read_b128 v[230:233], v141 offset:32768
	ds_read_b128 v[234:237], v140 offset:36864
	ds_read_b128 v[238:241], v141 offset:36864
	s_waitcnt lgkmcnt(3)
	v_mfma_f32_32x32x16_bf16 v[112:127], v[226:229], v[174:177], v[112:127]
	s_waitcnt lgkmcnt(1)
	v_mfma_f32_32x32x16_bf16 v[96:111], v[234:237], v[174:177], v[96:111]
	v_mfma_f32_32x32x16_bf16 v[80:95], v[226:229], v[182:185], v[80:95]
	v_mfma_f32_32x32x16_bf16 v[64:79], v[234:237], v[182:185], v[64:79]
	v_mfma_f32_32x32x16_bf16 v[48:63], v[226:229], v[190:193], v[48:63]
	v_mfma_f32_32x32x16_bf16 v[32:47], v[234:237], v[190:193], v[32:47]
	v_mfma_f32_32x32x16_bf16 v[16:31], v[226:229], v[198:201], v[16:31]
	v_mfma_f32_32x32x16_bf16 v[0:15], v[234:237], v[198:201], v[0:15]
	ds_read_b128 v[174:177], v138 offset:32768
	ds_read_b128 v[182:185], v138 offset:36864
	ds_read_b128 v[190:193], v138 offset:40960
	ds_read_b128 v[198:201], v138 offset:45056
	ds_read_b128 v[226:229], v142 offset:32768
	ds_read_b128 v[234:237], v142 offset:36864
	v_mfma_f32_32x32x16_bf16 v[112:127], v[230:233], v[178:181], v[112:127]
	s_waitcnt lgkmcnt(6)
	v_mfma_f32_32x32x16_bf16 v[96:111], v[238:241], v[178:181], v[96:111]
	v_mfma_f32_32x32x16_bf16 v[80:95], v[230:233], v[186:189], v[80:95]
	v_mfma_f32_32x32x16_bf16 v[64:79], v[238:241], v[186:189], v[64:79]
	v_mfma_f32_32x32x16_bf16 v[48:63], v[230:233], v[194:197], v[48:63]
	v_mfma_f32_32x32x16_bf16 v[32:47], v[238:241], v[194:197], v[32:47]
	v_mfma_f32_32x32x16_bf16 v[16:31], v[230:233], v[222:225], v[16:31]
	v_mfma_f32_32x32x16_bf16 v[0:15], v[238:241], v[222:225], v[0:15]
	ds_read_b128 v[178:181], v139 offset:32768
	ds_read_b128 v[186:189], v139 offset:36864
	ds_read_b128 v[194:197], v139 offset:40960
	ds_read_b128 v[222:225], v139 offset:45056
	ds_read_b128 v[230:233], v143 offset:32768
	ds_read_b128 v[238:241], v143 offset:36864
	s_waitcnt lgkmcnt(6)
	v_mfma_f32_32x32x16_bf16 v[112:127], v[226:229], v[174:177], v[112:127]
	v_mfma_f32_32x32x16_bf16 v[96:111], v[234:237], v[174:177], v[96:111]
	v_mfma_f32_32x32x16_bf16 v[80:95], v[226:229], v[182:185], v[80:95]
	v_mfma_f32_32x32x16_bf16 v[64:79], v[234:237], v[182:185], v[64:79]
	v_mfma_f32_32x32x16_bf16 v[48:63], v[226:229], v[190:193], v[48:63]
	v_mfma_f32_32x32x16_bf16 v[32:47], v[234:237], v[190:193], v[32:47]
	v_mfma_f32_32x32x16_bf16 v[16:31], v[226:229], v[198:201], v[16:31]
	v_mfma_f32_32x32x16_bf16 v[0:15], v[234:237], v[198:201], v[0:15]
	s_waitcnt lgkmcnt(1)
	v_mfma_f32_32x32x16_bf16 v[112:127], v[230:233], v[178:181], v[112:127]
	s_waitcnt lgkmcnt(0)
	v_mfma_f32_32x32x16_bf16 v[96:111], v[238:241], v[178:181], v[96:111]
	v_mfma_f32_32x32x16_bf16 v[80:95], v[230:233], v[186:189], v[80:95]
	v_mfma_f32_32x32x16_bf16 v[64:79], v[238:241], v[186:189], v[64:79]
	v_mfma_f32_32x32x16_bf16 v[48:63], v[230:233], v[194:197], v[48:63]
	v_mfma_f32_32x32x16_bf16 v[32:47], v[238:241], v[194:197], v[32:47]
	v_mfma_f32_32x32x16_bf16 v[16:31], v[230:233], v[222:225], v[16:31]
	v_mfma_f32_32x32x16_bf16 v[0:15], v[238:241], v[222:225], v[0:15]
	s_add_i32 s10, s10, 1
	s_waitcnt vmcnt(0)
	s_cmp_lg_u32 s10, 8
	s_barrier
	s_cbranch_scc1 .Lp1b_kloop
	s_and_b64 vcc, exec, s[0:1]
	s_cbranch_vccz .Lp1b_nomore
	s_lshl_b32 s4, s12, 8
	s_lshl_b32 s5, s13, 8
	v_add_u32_e32 v128, s4, v150
	v_lshlrev_b32_e32 v128, 11, v128
	v_add_u32_e32 v128, v128, v151
	v_add_u32_e32 v129, 0x4000, v128
	v_add_u32_e32 v130, 0x8000, v128
	v_add_u32_e32 v131, 0xc000, v128
	v_xor_b32_e32 v129, 0x40, v129
	v_xor_b32_e32 v131, 0x40, v131
	v_add_u32_e32 v132, s5, v150
	v_lshlrev_b32_e32 v132, 11, v132
	v_add_u32_e32 v132, v132, v151
	v_add_u32_e32 v133, 0x4000, v132
	v_add_u32_e32 v134, 0x8000, v132
	v_add_u32_e32 v135, 0xc000, v132
	v_xor_b32_e32 v133, 0x40, v133
	v_xor_b32_e32 v135, 0x40, v135
	s_mov_b64 s[14:15], s[88:89]
	s_mov_b64 s[16:17], s[64:65]
	s_add_u32 m0, s9, 0x0
	s_nop 0
	global_load_lds_dwordx4 v128, s[14:15]
	s_add_u32 m0, m0, 0x400
	s_nop 0
	global_load_lds_dwordx4 v129, s[14:15]
	s_add_u32 m0, m0, 0x400
	s_nop 0
	global_load_lds_dwordx4 v130, s[14:15]
	s_add_u32 m0, m0, 0x400
	s_nop 0
	global_load_lds_dwordx4 v131, s[14:15]
	s_add_u32 m0, s9, 0x10000
	s_nop 0
	global_load_lds_dwordx4 v132, s[16:17]
	s_add_u32 m0, m0, 0x400
	s_nop 0
	global_load_lds_dwordx4 v133, s[16:17]
	s_add_u32 m0, m0, 0x400
	s_nop 0
	global_load_lds_dwordx4 v134, s[16:17]
	s_add_u32 m0, m0, 0x400
	s_nop 0
	global_load_lds_dwordx4 v135, s[16:17]
; DEV u16 f2bf(float f) { return (u16)(pack2(f, f) & 0xffffu); }
; template <class F>
; DEV void acc_foreach(Acc& acc, int m0, int n0, F f) {
;   asm volatile("s_nop 7\n\ts_nop 7\n\ts_nop 3" ::: "memory");
;   const int tid = tidx_full();
;   const int wave = tid >> 6, lane = tid & 63;
;   const int wm = (wave >> 2) * 128, wn = (wave & 3) * 64;
;   const int lr = lane & 31, lh = lane >> 5;
; #pragma unroll
;   for (int i = 0; i < 4; ++i)
; #pragma unroll
;     for (int j = 0; j < 2; ++j)
; #pragma unroll
;       for (int r = 0; r < 16; ++r) {
;         const int m = m0 + wm + 32 * i + (r & 3) + 8 * (r >> 2) + 4 * lh;
;         const int n = n0 + wn + 32 * j + lr;
;         float v = acc[i][j][r];
;         f(m, n, v);
;         acc[i][j][r] = v;
;       }
; }
; DEV void phase_p1(const Params& p, int g, char* smem) {
;     ...
;       const int b = n0 / L, tb = n0 - b * L;
;       u16* dst = UHY + (size_t)b * 1536 * L + tb - n0;
;       acc_foreach(acc, m0, n0, [&](int m, int n, float& v) { dst[(size_t)m * L + n] = f2bf(v); });
.Lp1b_nomore:
	s_lshr_b32 s3, s2, s24
	s_lshl_b32 s4, s3, s24
	s_sub_u32 s4, s2, s4
	s_mul_i32 s5, s3, 0x600
	s_add_u32 s5, s5, s11
	s_add_u32 s12, s24, 1
	s_lshl_b32 s13, 8, s12
	s_nop 7
	s_nop 7
	s_nop 3
	v_and_b32_e32 v160, 63, v202
	v_lshrrev_b32_e32 v161, 6, v202
	v_and_b32_e32 v164, 3, v161
	v_lshlrev_b32_e32 v164, 13, v164
	v_add_u32_e32 v164, 0x8000, v164
	v_lshrrev_b32_e32 v160, 2, v161
	v_lshl_add_u32 v164, v160, 16, v164
	v_and_b32_e32 v160, 63, v202
	v_and_b32_e32 v166, 31, v160
	v_lshrrev_b32_e32 v167, 5, v160
	v_lshlrev_b32_e32 v168, 7, v166
	v_lshl_add_u32 v168, v167, 3, v168
	v_add_u32_e32 v168, v164, v168
	v_and_b32_e32 v166, 7, v166
	v_lshlrev_b32_e32 v166, 4, v166
	v_add_u32_e32 v170, v168, v166
	v_xor_b32_e32 v167, 0x10, v166
	v_add_u32_e32 v171, v168, v167
	v_xor_b32_e32 v167, 0x20, v166
	v_add_u32_e32 v172, v168, v167
	v_xor_b32_e32 v167, 0x30, v166
	v_add_u32_e32 v173, v168, v167
	v_xor_b32_e32 v167, 0x40, v166
	v_add_u32_e32 v174, v168, v167
	v_xor_b32_e32 v167, 0x50, v166
	v_add_u32_e32 v175, v168, v167
	v_xor_b32_e32 v167, 0x60, v166
	v_add_u32_e32 v176, v168, v167
	v_xor_b32_e32 v167, 0x70, v166
	v_add_u32_e32 v177, v168, v167
	v_lshrrev_b32_e32 v166, 3, v160
	v_and_b32_e32 v167, 7, v160
	v_lshrrev_b32_e32 v169, 2, v161
	v_lshl_add_u32 v169, v169, 7, v166
	v_add_u32_e32 v169, s5, v169
	v_lshlrev_b32_e32 v169, s12, v169
	v_and_b32_e32 v168, 3, v161
	v_lshlrev_b32_e32 v168, 3, v168
	v_add_u32_e32 v168, v168, v167
	v_lshl_add_u32 v169, v168, 4, v169
	s_lshl_b32 s100, s4, 1
	v_add_u32_e32 v169, s100, v169
	v_xor_b32_e32 v167, v166, v167
	v_lshlrev_b32_e32 v167, 4, v167
	v_lshl_add_u32 v168, v166, 7, v167
	v_add_u32_e32 v168, v164, v168
	v_cvt_pk_bf16_f32 v112, v112, v113
	v_cvt_pk_bf16_f32 v113, v114, v115
	ds_write_b64 v170, v[112:113]
	v_cvt_pk_bf16_f32 v116, v116, v117
	v_cvt_pk_bf16_f32 v117, v118, v119
	ds_write_b64 v171, v[116:117]
	v_cvt_pk_bf16_f32 v120, v120, v121
	v_cvt_pk_bf16_f32 v121, v122, v123
	ds_write_b64 v172, v[120:121]
	v_cvt_pk_bf16_f32 v124, v124, v125
	v_cvt_pk_bf16_f32 v125, v126, v127
	ds_write_b64 v173, v[124:125]
	v_cvt_pk_bf16_f32 v96, v96, v97
	v_cvt_pk_bf16_f32 v97, v98, v99
	ds_write_b64 v174, v[96:97]
	v_cvt_pk_bf16_f32 v100, v100, v101
	v_cvt_pk_bf16_f32 v101, v102, v103
	ds_write_b64 v175, v[100:101]
	v_cvt_pk_bf16_f32 v104, v104, v105
	v_cvt_pk_bf16_f32 v105, v106, v107
	ds_write_b64 v176, v[104:105]
	v_cvt_pk_bf16_f32 v108, v108, v109
	v_cvt_pk_bf16_f32 v109, v110, v111
	ds_write_b64 v177, v[108:109]
	v_cvt_pk_bf16_f32 v80, v80, v81
	v_cvt_pk_bf16_f32 v81, v82, v83
	ds_write_b64 v170, v[80:81] offset:4096
	v_cvt_pk_bf16_f32 v84, v84, v85
	v_cvt_pk_bf16_f32 v85, v86, v87
	ds_write_b64 v171, v[84:85] offset:4096
	v_cvt_pk_bf16_f32 v88, v88, v89
	v_cvt_pk_bf16_f32 v89, v90, v91
	ds_write_b64 v172, v[88:89] offset:4096
	v_cvt_pk_bf16_f32 v92, v92, v93
	v_cvt_pk_bf16_f32 v93, v94, v95
	ds_write_b64 v173, v[92:93] offset:4096
	v_cvt_pk_bf16_f32 v64, v64, v65
	v_cvt_pk_bf16_f32 v65, v66, v67
	ds_write_b64 v174, v[64:65] offset:4096
	v_cvt_pk_bf16_f32 v68, v68, v69
	v_cvt_pk_bf16_f32 v69, v70, v71
	ds_write_b64 v175, v[68:69] offset:4096
	v_cvt_pk_bf16_f32 v72, v72, v73
	v_cvt_pk_bf16_f32 v73, v74, v75
	ds_write_b64 v176, v[72:73] offset:4096
	v_cvt_pk_bf16_f32 v76, v76, v77
	v_cvt_pk_bf16_f32 v77, v78, v79
	ds_write_b64 v177, v[76:77] offset:4096
	s_waitcnt lgkmcnt(0)
	ds_read_b128 v[96:99], v168
	ds_read_b128 v[100:103], v168 offset:1024
	ds_read_b128 v[104:107], v168 offset:2048
	ds_read_b128 v[108:111], v168 offset:3072
	ds_read_b128 v[112:115], v168 offset:4096
	ds_read_b128 v[116:119], v168 offset:5120
	ds_read_b128 v[120:123], v168 offset:6144
	ds_read_b128 v[124:127], v168 offset:7168
	s_waitcnt lgkmcnt(7)
; DEV u16 f2bf(float f) { return (u16)(pack2(f, f) & 0xffffu); }
; template <class F>
; DEV void acc_foreach(Acc& acc, int m0, int n0, F f) {
;   asm volatile("s_nop 7\n\ts_nop 7\n\ts_nop 3" ::: "memory");
;   const int tid = tidx_full();
;   const int wave = tid >> 6, lane = tid & 63;
;   const int wm = (wave >> 2) * 128, wn = (wave & 3) * 64;
;   const int lr = lane & 31, lh = lane >> 5;
; #pragma unroll
;   for (int i = 0; i < 4; ++i)
; #pragma unroll
;     for (int j = 0; j < 2; ++j)
; #pragma unroll
;       for (int r = 0; r < 16; ++r) {
;         const int m = m0 + wm + 32 * i + (r & 3) + 8 * (r >> 2) + 4 * lh;
;         const int n = n0 + wn + 32 * j + lr;
;         float v = acc[i][j][r];
;         f(m, n, v);
;         acc[i][j][r] = v;
;       }
; }
; DEV void phase_p1(const Params& p, int g, char* smem) {
;     ...
;       const int b = n0 / L, tb = n0 - b * L;
;       u16* dst = UHY + (size_t)b * 1536 * L + tb - n0;
;       acc_foreach(acc, m0, n0, [&](int m, int n, float& v) { dst[(size_t)m * L + n] = f2bf(v); });
	global_store_dwordx4 v169, v[96:99], s[74:75]
	v_add_u32_e32 v169, s13, v169
	s_waitcnt lgkmcnt(6)
	global_store_dwordx4 v169, v[100:103], s[74:75]
	v_add_u32_e32 v169, s13, v169
	s_waitcnt lgkmcnt(5)
	global_store_dwordx4 v169, v[104:107], s[74:75]
	v_add_u32_e32 v169, s13, v169
	s_waitcnt lgkmcnt(4)
	global_store_dwordx4 v169, v[108:111], s[74:75]
	v_add_u32_e32 v169, s13, v169
	s_waitcnt lgkmcnt(3)
	global_store_dwordx4 v169, v[112:115], s[74:75]
	v_add_u32_e32 v169, s13, v169
	s_waitcnt lgkmcnt(2)
	global_store_dwordx4 v169, v[116:119], s[74:75]
	v_add_u32_e32 v169, s13, v169
	s_waitcnt lgkmcnt(1)
	global_store_dwordx4 v169, v[120:123], s[74:75]
	v_add_u32_e32 v169, s13, v169
	s_waitcnt lgkmcnt(0)
	global_store_dwordx4 v169, v[124:127], s[74:75]
	v_add_u32_e32 v169, s13, v169
	v_cvt_pk_bf16_f32 v48, v48, v49
	v_cvt_pk_bf16_f32 v49, v50, v51
	ds_write_b64 v170, v[48:49]
	v_cvt_pk_bf16_f32 v52, v52, v53
	v_cvt_pk_bf16_f32 v53, v54, v55
	ds_write_b64 v171, v[52:53]
	v_cvt_pk_bf16_f32 v56, v56, v57
	v_cvt_pk_bf16_f32 v57, v58, v59
	ds_write_b64 v172, v[56:57]
	v_cvt_pk_bf16_f32 v60, v60, v61
	v_cvt_pk_bf16_f32 v61, v62, v63
	ds_write_b64 v173, v[60:61]
	v_cvt_pk_bf16_f32 v32, v32, v33
	v_cvt_pk_bf16_f32 v33, v34, v35
	ds_write_b64 v174, v[32:33]
	v_cvt_pk_bf16_f32 v36, v36, v37
	v_cvt_pk_bf16_f32 v37, v38, v39
	ds_write_b64 v175, v[36:37]
	v_cvt_pk_bf16_f32 v40, v40, v41
	v_cvt_pk_bf16_f32 v41, v42, v43
	ds_write_b64 v176, v[40:41]
	v_cvt_pk_bf16_f32 v44, v44, v45
	v_cvt_pk_bf16_f32 v45, v46, v47
	ds_write_b64 v177, v[44:45]
	v_cvt_pk_bf16_f32 v16, v16, v17
	v_cvt_pk_bf16_f32 v17, v18, v19
	ds_write_b64 v170, v[16:17] offset:4096
	v_cvt_pk_bf16_f32 v20, v20, v21
	v_cvt_pk_bf16_f32 v21, v22, v23
	ds_write_b64 v171, v[20:21] offset:4096
	v_cvt_pk_bf16_f32 v24, v24, v25
	v_cvt_pk_bf16_f32 v25, v26, v27
	ds_write_b64 v172, v[24:25] offset:4096
	v_cvt_pk_bf16_f32 v28, v28, v29
	v_cvt_pk_bf16_f32 v29, v30, v31
	ds_write_b64 v173, v[28:29] offset:4096
	v_cvt_pk_bf16_f32 v0, v0, v1
	v_cvt_pk_bf16_f32 v1, v2, v3
	ds_write_b64 v174, v[0:1] offset:4096
	v_cvt_pk_bf16_f32 v4, v4, v5
	v_cvt_pk_bf16_f32 v5, v6, v7
	ds_write_b64 v175, v[4:5] offset:4096
	v_cvt_pk_bf16_f32 v8, v8, v9
	v_cvt_pk_bf16_f32 v9, v10, v11
	ds_write_b64 v176, v[8:9] offset:4096
	v_cvt_pk_bf16_f32 v12, v12, v13
	v_cvt_pk_bf16_f32 v13, v14, v15
	ds_write_b64 v177, v[12:13] offset:4096
	s_waitcnt lgkmcnt(0)
	ds_read_b128 v[64:67], v168
	ds_read_b128 v[68:71], v168 offset:1024
	ds_read_b128 v[72:75], v168 offset:2048
	ds_read_b128 v[76:79], v168 offset:3072
	ds_read_b128 v[80:83], v168 offset:4096
	ds_read_b128 v[84:87], v168 offset:5120
	ds_read_b128 v[88:91], v168 offset:6144
	ds_read_b128 v[92:95], v168 offset:7168
	s_waitcnt lgkmcnt(7)
	global_store_dwordx4 v169, v[64:67], s[74:75]
	v_add_u32_e32 v169, s13, v169
	s_waitcnt lgkmcnt(6)
	global_store_dwordx4 v169, v[68:71], s[74:75]
	v_add_u32_e32 v169, s13, v169
	s_waitcnt lgkmcnt(5)
	global_store_dwordx4 v169, v[72:75], s[74:75]
	v_add_u32_e32 v169, s13, v169
	s_waitcnt lgkmcnt(4)
	global_store_dwordx4 v169, v[76:79], s[74:75]
	v_add_u32_e32 v169, s13, v169
	s_waitcnt lgkmcnt(3)
	global_store_dwordx4 v169, v[80:83], s[74:75]
	v_add_u32_e32 v169, s13, v169
	s_waitcnt lgkmcnt(2)
	global_store_dwordx4 v169, v[84:87], s[74:75]
	v_add_u32_e32 v169, s13, v169
	s_waitcnt lgkmcnt(1)
	global_store_dwordx4 v169, v[88:91], s[74:75]
	v_add_u32_e32 v169, s13, v169
	s_waitcnt lgkmcnt(0)
	s_barrier
	global_store_dwordx4 v169, v[92:95], s[74:75]
	v_add_u32_e32 v169, s13, v169
	s_mov_b64 s[4:5], 0
	s_branch .LBB0_544

; template <class AL, class BL>
; DEV void gemm_mainloop_p(Acc& acc, const AL& al, const BL& bl, int m0, int n0, int m0n, int n0n, int K, char* lds,
;                          GemmPipe& gp) {
;   const int tid = tidx_full();
;   const int wave = tid >> 6, lane = tid & 63;
;   const int wm = (wave >> 2) * 128, wn = (wave & 3) * 64;
;   const int lr = lane & 31, lh = lane >> 5;
;   const int nk = K / BK;
;   if (!gp.primed) {
;     gp.ra = al.load(tid, m0, 0);
;     gp.rb = bl.load(tid, n0, 0);
;     __syncthreads();
;     al.store(tid, lds, gp.ra);
;     bl.store(tid, lds + TILE_BYTES, gp.rb);
;     gp.ra = al.load(tid, m0, BK);
;     gp.rb = bl.load(tid, n0, BK);
;     __syncthreads();
;   }
; DEV void phase_ff1(const Params& p, int g, char* smem) {
;     ...
;   GemmPipe gp;
;   gp.primed = false;
;   for (int iter = 0;; ++iter) {
;     int mt, nt, mtn, ntn;
;     if (!tile_map(iter, 128, 16, mt, nt)) break;
;     const bool more = tile_map(iter + 1, 128, 16, mtn, ntn);
;     if (!more) { mtn = mt; ntn = nt; }
;     const int m0 = mt * 256, n0 = nt * 256;
;     Acc acc;
;     acc_zero(acc);
;     RowLoader al{H2, 1024}, bl{W, 1024};
;     gemm_mainloop_p(acc, al, bl, m0, n0, mtn * 256, ntn * 256, 1024, smem, gp);
.LBB0_1126:
	v_readlane_b32 s18, v249, 48
	v_readlane_b32 s19, v249, 49
	v_readlane_b32 s20, v251, 25
	v_readlane_b32 s21, v251, 26
	s_lshl_b32 s5, s9, 8
	s_lshl_b32 s4, s10, 8
	v_lshrrev_b32_e32 v149, 6, v202
	v_and_b32_e32 v148, 63, v202
	s_nop 0
	v_readfirstlane_b32 s13, v149
	v_lshrrev_b32_e32 v150, 3, v148
	v_lshl_add_u32 v150, v149, 5, v150
	v_and_b32_e32 v151, 7, v148
	v_lshrrev_b32_e32 v128, 4, v148
	v_xor_b32_e32 v151, v128, v151
	v_lshlrev_b32_e32 v151, 4, v151
	s_lshl_b32 s13, s13, 12
	v_add_u32_e32 v128, s5, v150
	v_lshlrev_b32_e32 v128, 11, v128
	v_add_u32_e32 v128, v128, v151
	v_add_u32_e32 v129, 0x4000, v128
	v_add_u32_e32 v130, 0x8000, v128
	v_add_u32_e32 v131, 0xc000, v128
	v_xor_b32_e32 v129, 0x40, v129
	v_xor_b32_e32 v131, 0x40, v131
	v_add_u32_e32 v132, s4, v150
	v_lshlrev_b32_e32 v132, 11, v132
	v_add_u32_e32 v132, v132, v151
	v_add_u32_e32 v133, 0x4000, v132
	v_add_u32_e32 v134, 0x8000, v132
	v_add_u32_e32 v135, 0xc000, v132
	v_xor_b32_e32 v133, 0x40, v133
	v_xor_b32_e32 v135, 0x40, v135
	v_lshrrev_b32_e32 v144, 1, v148
	v_and_b32_e32 v144, 7, v144
	v_lshrrev_b32_e32 v145, 5, v148
	v_xor_b32_e32 v144, v144, v145
	v_lshlrev_b32_e32 v144, 4, v144
	v_and_b32_e32 v145, 31, v148
	v_lshlrev_b32_e32 v145, 7, v145
	v_lshrrev_b32_e32 v136, 2, v149
	v_lshl_add_u32 v136, v136, 14, v145
	v_and_b32_e32 v140, 3, v149
	v_lshl_add_u32 v140, v140, 13, v145
	v_add_u32_e32 v140, 0x10000, v140
	v_xor_b32_e32 v139, 0x60, v144
	v_add_u32_e32 v139, v136, v139
	v_xor_b32_e32 v138, 0x40, v144
	v_add_u32_e32 v138, v136, v138
	v_xor_b32_e32 v137, 0x20, v144
	v_add_u32_e32 v137, v136, v137
	v_add_u32_e32 v136, v136, v144
	v_xor_b32_e32 v143, 0x60, v144
	v_add_u32_e32 v143, v140, v143
	v_xor_b32_e32 v142, 0x40, v144
	v_add_u32_e32 v142, v140, v142
	v_xor_b32_e32 v141, 0x20, v144
	v_add_u32_e32 v141, v140, v141
	v_add_u32_e32 v140, v140, v144
	s_mov_b64 s[22:23], s[18:19]
	s_mov_b64 s[14:15], s[20:21]
	s_and_b64 vcc, exec, s[2:3]
	s_cbranch_vccnz .Lff1_primed
	s_add_u32 m0, s13, 0x0
	s_nop 0
	global_load_lds_dwordx4 v128, s[22:23]
	s_add_u32 m0, m0, 0x400
	s_nop 0
	global_load_lds_dwordx4 v129, s[22:23]
	s_add_u32 m0, m0, 0x400
	s_nop 0
	global_load_lds_dwordx4 v130, s[22:23]
	s_add_u32 m0, m0, 0x400
	s_nop 0
	global_load_lds_dwordx4 v131, s[22:23]
	s_add_u32 m0, s13, 0x10000
	s_nop 0
	global_load_lds_dwordx4 v132, s[14:15]
	s_add_u32 m0, m0, 0x400
	s_nop 0
	global_load_lds_dwordx4 v133, s[14:15]
	s_add_u32 m0, m0, 0x400
	s_nop 0
	global_load_lds_dwordx4 v134, s[14:15]
	s_add_u32 m0, m0, 0x400
	s_nop 0
	global_load_lds_dwordx4 v135, s[14:15]
.Lff1_primed:
	s_add_u32 s22, s22, 0x80
	s_addc_u32 s23, s23, 0
	s_add_u32 s14, s14, 0x80
	s_addc_u32 s15, s15, 0
	v_mov_b32_e32 v0, 0
	v_mov_b32_e32 v1, 0
	v_mov_b64_e32 v[2:3], v[0:1]
	v_mov_b64_e32 v[4:5], v[0:1]
	v_mov_b64_e32 v[6:7], v[0:1]
	v_mov_b64_e32 v[8:9], v[0:1]
	v_mov_b64_e32 v[10:11], v[0:1]
	v_mov_b64_e32 v[12:13], v[0:1]
	v_mov_b64_e32 v[14:15], v[0:1]
	v_mov_b64_e32 v[16:17], v[0:1]
	v_mov_b64_e32 v[18:19], v[0:1]
	v_mov_b64_e32 v[20:21], v[0:1]
	v_mov_b64_e32 v[22:23], v[0:1]
	v_mov_b64_e32 v[24:25], v[0:1]
	v_mov_b64_e32 v[26:27], v[0:1]
	v_mov_b64_e32 v[28:29], v[0:1]
	v_mov_b64_e32 v[30:31], v[0:1]
	v_mov_b64_e32 v[32:33], v[0:1]
	v_mov_b64_e32 v[34:35], v[0:1]
	v_mov_b64_e32 v[36:37], v[0:1]
	v_mov_b64_e32 v[38:39], v[0:1]
	v_mov_b64_e32 v[40:41], v[0:1]
	v_mov_b64_e32 v[42:43], v[0:1]
	v_mov_b64_e32 v[44:45], v[0:1]
	v_mov_b64_e32 v[46:47], v[0:1]
	v_mov_b64_e32 v[48:49], v[0:1]
	v_mov_b64_e32 v[50:51], v[0:1]
	v_mov_b64_e32 v[52:53], v[0:1]
	v_mov_b64_e32 v[54:55], v[0:1]
	v_mov_b64_e32 v[56:57], v[0:1]
	v_mov_b64_e32 v[58:59], v[0:1]
	v_mov_b64_e32 v[60:61], v[0:1]
	v_mov_b64_e32 v[62:63], v[0:1]
	v_mov_b64_e32 v[64:65], v[0:1]
	v_mov_b64_e32 v[66:67], v[0:1]
	v_mov_b64_e32 v[68:69], v[0:1]
	v_mov_b64_e32 v[70:71], v[0:1]
	v_mov_b64_e32 v[72:73], v[0:1]
	v_mov_b64_e32 v[74:75], v[0:1]
	v_mov_b64_e32 v[76:77], v[0:1]
	v_mov_b64_e32 v[78:79], v[0:1]
	v_mov_b64_e32 v[80:81], v[0:1]
	v_mov_b64_e32 v[82:83], v[0:1]
	v_mov_b64_e32 v[84:85], v[0:1]
	v_mov_b64_e32 v[86:87], v[0:1]
	v_mov_b64_e32 v[88:89], v[0:1]
	v_mov_b64_e32 v[90:91], v[0:1]
	v_mov_b64_e32 v[92:93], v[0:1]
	v_mov_b64_e32 v[94:95], v[0:1]
	v_mov_b64_e32 v[96:97], v[0:1]
	v_mov_b64_e32 v[98:99], v[0:1]
	v_mov_b64_e32 v[100:101], v[0:1]
	v_mov_b64_e32 v[102:103], v[0:1]
	v_mov_b64_e32 v[104:105], v[0:1]
	v_mov_b64_e32 v[106:107], v[0:1]
	v_mov_b64_e32 v[108:109], v[0:1]
	v_mov_b64_e32 v[110:111], v[0:1]
	v_mov_b64_e32 v[112:113], v[0:1]
	v_mov_b64_e32 v[114:115], v[0:1]
	v_mov_b64_e32 v[116:117], v[0:1]
	v_mov_b64_e32 v[118:119], v[0:1]
	v_mov_b64_e32 v[120:121], v[0:1]
	v_mov_b64_e32 v[122:123], v[0:1]
	v_mov_b64_e32 v[124:125], v[0:1]
	v_mov_b64_e32 v[126:127], v[0:1]
	s_mov_b32 s17, 0
	s_waitcnt vmcnt(0)
	s_barrier
; template <class AL, class BL>
; DEV void gemm_ktile(Acc& acc, const char* A, const char* B, int wm, int wn, int lr, int lh, const AL& al, const BL& bl,
;                     int tid, int m0, int n0, int knext, char* nxt, R4& ra, R4& rb) {
;   bf16x8 a[2][4], b[2][2];
;   const char* pa = A + (wm + lr) * LDSROW + lh * 16;
;   const char* pb = B + (wn + lr) * LDSROW + lh * 16;
; #pragma unroll
;   for (int i = 0; i < 4; ++i) a[0][i] = *(const bf16x8*)(pa + 32 * i * LDSROW);
; #pragma unroll
;   for (int j = 0; j < 2; ++j) b[0][j] = *(const bf16x8*)(pb + 32 * j * LDSROW);
; #pragma unroll
;   for (int ks = 0; ks < 4; ++ks) {
;     const int cur = ks & 1, nx = cur ^ 1;
;     if (ks < 3) {
; #pragma unroll
;       for (int i = 0; i < 4; ++i) a[nx][i] = *(const bf16x8*)(pa + 32 * i * LDSROW + (ks + 1) * 32);
; #pragma unroll
;       for (int j = 0; j < 2; ++j) b[nx][j] = *(const bf16x8*)(pb + 32 * j * LDSROW + (ks + 1) * 32);
;     }
;     __builtin_amdgcn_sched_barrier(0);
; #pragma unroll
;     for (int i = 0; i < 4; ++i)
; #pragma unroll
;       for (int j = 0; j < 2; ++j)
;         acc[i][j] = __builtin_amdgcn_mfma_f32_32x32x16_bf16(a[cur][i], b[cur][j], acc[i][j], 0, 0, 0);
;     __builtin_amdgcn_sched_barrier(0);
;     if (ks == 1) {
;       al.store(tid, nxt, ra);
;       bl.store(tid, nxt + TILE_BYTES, rb);
;       __builtin_amdgcn_sched_barrier(0);
;       ra = al.load(tid, m0, knext);
;       rb = bl.load(tid, n0, knext);
;       __builtin_amdgcn_sched_barrier(0);
;     }
;   }
; template <class AL, class BL>
; DEV void gemm_mainloop_p(Acc& acc, const AL& al, const BL& bl, int m0, int n0, int m0n, int n0n, int K, char* lds,
;                          GemmPipe& gp) {
;     ...
;   for (int kt = 0; kt < nk; ++kt) {
;     const char* cur = lds + (kt & 1) * 2 * TILE_BYTES;
;     char* nxt = lds + ((kt + 1) & 1) * 2 * TILE_BYTES;
;     const bool wrap = (kt + 2 >= nk);
;     const int kk = (wrap ? kt + 2 - nk : kt + 2) * BK;
;     const int mr = wrap ? m0n : m0, nr = wrap ? n0n : n0;
;     __builtin_amdgcn_sched_barrier(0);
;     gemm_ktile(acc, cur, cur + TILE_BYTES, wm, wn, lr, lh, al, bl, tid, mr, nr, kk, nxt, gp.ra, gp.rb);
;     __builtin_amdgcn_sched_barrier(0);
;     __syncthreads();
;   }
.Lff1_kloop:
	s_add_u32 m0, s13, 0x8000
	s_nop 0
	global_load_lds_dwordx4 v128, s[22:23]
	s_add_u32 m0, m0, 0x400
	s_nop 0
	global_load_lds_dwordx4 v129, s[22:23]
	s_add_u32 m0, m0, 0x400
	s_nop 0
	global_load_lds_dwordx4 v130, s[22:23]
	s_add_u32 m0, m0, 0x400
	s_nop 0
	global_load_lds_dwordx4 v131, s[22:23]
	s_add_u32 m0, s13, 0x18000
	s_nop 0
	global_load_lds_dwordx4 v132, s[14:15]
	s_add_u32 m0, m0, 0x400
	s_nop 0
	global_load_lds_dwordx4 v133, s[14:15]
	s_add_u32 m0, m0, 0x400
	s_nop 0
	global_load_lds_dwordx4 v134, s[14:15]
	s_add_u32 m0, m0, 0x400
	s_nop 0
	global_load_lds_dwordx4 v135, s[14:15]
	s_add_u32 s22, s22, 0x80
	s_addc_u32 s23, s23, 0
	s_add_u32 s14, s14, 0x80
	s_addc_u32 s15, s15, 0
	ds_read_b128 v[174:177], v136
	ds_read_b128 v[178:181], v137
	ds_read_b128 v[182:185], v136 offset:4096
	ds_read_b128 v[186:189], v137 offset:4096
	ds_read_b128 v[190:193], v136 offset:8192
	ds_read_b128 v[194:197], v137 offset:8192
	ds_read_b128 v[198:201], v136 offset:12288
	ds_read_b128 v[222:225], v137 offset:12288
	ds_read_b128 v[226:229], v140
	ds_read_b128 v[230:233], v141
	ds_read_b128 v[234:237], v140 offset:4096
	ds_read_b128 v[238:241], v141 offset:4096
	s_waitcnt lgkmcnt(3)
	v_mfma_f32_32x32x16_bf16 v[112:127], v[226:229], v[174:177], v[112:127]
	s_waitcnt lgkmcnt(1)
	v_mfma_f32_32x32x16_bf16 v[96:111], v[234:237], v[174:177], v[96:111]
	v_mfma_f32_32x32x16_bf16 v[80:95], v[226:229], v[182:185], v[80:95]
	v_mfma_f32_32x32x16_bf16 v[64:79], v[234:237], v[182:185], v[64:79]
	v_mfma_f32_32x32x16_bf16 v[48:63], v[226:229], v[190:193], v[48:63]
	v_mfma_f32_32x32x16_bf16 v[32:47], v[234:237], v[190:193], v[32:47]
	v_mfma_f32_32x32x16_bf16 v[16:31], v[226:229], v[198:201], v[16:31]
	v_mfma_f32_32x32x16_bf16 v[0:15], v[234:237], v[198:201], v[0:15]
	ds_read_b128 v[174:177], v138
	ds_read_b128 v[182:185], v138 offset:4096
	ds_read_b128 v[190:193], v138 offset:8192
	ds_read_b128 v[198:201], v138 offset:12288
	ds_read_b128 v[226:229], v142
	ds_read_b128 v[234:237], v142 offset:4096
	v_mfma_f32_32x32x16_bf16 v[112:127], v[230:233], v[178:181], v[112:127]
	s_waitcnt lgkmcnt(6)
	v_mfma_f32_32x32x16_bf16 v[96:111], v[238:241], v[178:181], v[96:111]
	v_mfma_f32_32x32x16_bf16 v[80:95], v[230:233], v[186:189], v[80:95]
	v_mfma_f32_32x32x16_bf16 v[64:79], v[238:241], v[186:189], v[64:79]
	v_mfma_f32_32x32x16_bf16 v[48:63], v[230:233], v[194:197], v[48:63]
	v_mfma_f32_32x32x16_bf16 v[32:47], v[238:241], v[194:197], v[32:47]
	v_mfma_f32_32x32x16_bf16 v[16:31], v[230:233], v[222:225], v[16:31]
	v_mfma_f32_32x32x16_bf16 v[0:15], v[238:241], v[222:225], v[0:15]
	ds_read_b128 v[178:181], v139
	ds_read_b128 v[186:189], v139 offset:4096
	ds_read_b128 v[194:197], v139 offset:8192
	ds_read_b128 v[222:225], v139 offset:12288
	ds_read_b128 v[230:233], v143
	ds_read_b128 v[238:241], v143 offset:4096
	s_waitcnt lgkmcnt(6)
	v_mfma_f32_32x32x16_bf16 v[112:127], v[226:229], v[174:177], v[112:127]
	v_mfma_f32_32x32x16_bf16 v[96:111], v[234:237], v[174:177], v[96:111]
	v_mfma_f32_32x32x16_bf16 v[80:95], v[226:229], v[182:185], v[80:95]
	v_mfma_f32_32x32x16_bf16 v[64:79], v[234:237], v[182:185], v[64:79]
	v_mfma_f32_32x32x16_bf16 v[48:63], v[226:229], v[190:193], v[48:63]
	v_mfma_f32_32x32x16_bf16 v[32:47], v[234:237], v[190:193], v[32:47]
	v_mfma_f32_32x32x16_bf16 v[16:31], v[226:229], v[198:201], v[16:31]
	v_mfma_f32_32x32x16_bf16 v[0:15], v[234:237], v[198:201], v[0:15]
	s_waitcnt lgkmcnt(1)
	v_mfma_f32_32x32x16_bf16 v[112:127], v[230:233], v[178:181], v[112:127]
	s_waitcnt lgkmcnt(0)
	v_mfma_f32_32x32x16_bf16 v[96:111], v[238:241], v[178:181], v[96:111]
	v_mfma_f32_32x32x16_bf16 v[80:95], v[230:233], v[186:189], v[80:95]
	v_mfma_f32_32x32x16_bf16 v[64:79], v[238:241], v[186:189], v[64:79]
	v_mfma_f32_32x32x16_bf16 v[48:63], v[230:233], v[194:197], v[48:63]
	v_mfma_f32_32x32x16_bf16 v[32:47], v[238:241], v[194:197], v[32:47]
	v_mfma_f32_32x32x16_bf16 v[16:31], v[230:233], v[222:225], v[16:31]
	v_mfma_f32_32x32x16_bf16 v[0:15], v[238:241], v[222:225], v[0:15]
	s_waitcnt vmcnt(0)
	s_barrier
	s_cmp_eq_u32 s17, 7
	s_cbranch_scc1 .Lff1_skipdma
	s_add_u32 m0, s13, 0x0
	s_nop 0
	global_load_lds_dwordx4 v128, s[22:23]
	s_add_u32 m0, m0, 0x400
	s_nop 0
	global_load_lds_dwordx4 v129, s[22:23]
	s_add_u32 m0, m0, 0x400
	s_nop 0
	global_load_lds_dwordx4 v130, s[22:23]
	s_add_u32 m0, m0, 0x400
	s_nop 0
	global_load_lds_dwordx4 v131, s[22:23]
	s_add_u32 m0, s13, 0x10000
	s_nop 0
	global_load_lds_dwordx4 v132, s[14:15]
	s_add_u32 m0, m0, 0x400
	s_nop 0
	global_load_lds_dwordx4 v133, s[14:15]
	s_add_u32 m0, m0, 0x400
	s_nop 0
	global_load_lds_dwordx4 v134, s[14:15]
	s_add_u32 m0, m0, 0x400
	s_nop 0
	global_load_lds_dwordx4 v135, s[14:15]
	s_add_u32 s22, s22, 0x80
	s_addc_u32 s23, s23, 0
	s_add_u32 s14, s14, 0x80
	s_addc_u32 s15, s15, 0
; template <class AL, class BL>
; DEV void gemm_ktile(Acc& acc, const char* A, const char* B, int wm, int wn, int lr, int lh, const AL& al, const BL& bl,
;                     int tid, int m0, int n0, int knext, char* nxt, R4& ra, R4& rb) {
;   bf16x8 a[2][4], b[2][2];
;   const char* pa = A + (wm + lr) * LDSROW + lh * 16;
;   const char* pb = B + (wn + lr) * LDSROW + lh * 16;
; #pragma unroll
;   for (int i = 0; i < 4; ++i) a[0][i] = *(const bf16x8*)(pa + 32 * i * LDSROW);
; #pragma unroll
;   for (int j = 0; j < 2; ++j) b[0][j] = *(const bf16x8*)(pb + 32 * j * LDSROW);
; #pragma unroll
;   for (int ks = 0; ks < 4; ++ks) {
;     const int cur = ks & 1, nx = cur ^ 1;
;     if (ks < 3) {
; #pragma unroll
;       for (int i = 0; i < 4; ++i) a[nx][i] = *(const bf16x8*)(pa + 32 * i * LDSROW + (ks + 1) * 32);
; #pragma unroll
;       for (int j = 0; j < 2; ++j) b[nx][j] = *(const bf16x8*)(pb + 32 * j * LDSROW + (ks + 1) * 32);
;     }
;     __builtin_amdgcn_sched_barrier(0);
; #pragma unroll
;     for (int i = 0; i < 4; ++i)
; #pragma unroll
;       for (int j = 0; j < 2; ++j)
;         acc[i][j] = __builtin_amdgcn_mfma_f32_32x32x16_bf16(a[cur][i], b[cur][j], acc[i][j], 0, 0, 0);
;     __builtin_amdgcn_sched_barrier(0);
;     if (ks == 1) {
;       al.store(tid, nxt, ra);
;       bl.store(tid, nxt + TILE_BYTES, rb);
;       __builtin_amdgcn_sched_barrier(0);
;       ra = al.load(tid, m0, knext);
;       rb = bl.load(tid, n0, knext);
;       __builtin_amdgcn_sched_barrier(0);
;     }
;   }
; DEV void phase_ff1(const Params& p, int g, char* smem) {
;     ...
;   for (int iter = 0;; ++iter) {
;     int mt, nt, mtn, ntn;
;     if (!tile_map(iter, 128, 16, mt, nt)) break;
;     const bool more = tile_map(iter + 1, 128, 16, mtn, ntn);
;     if (!more) { mtn = mt; ntn = nt; }
;     const int m0 = mt * 256, n0 = nt * 256;
;     Acc acc;
;     acc_zero(acc);
;     RowLoader al{H2, 1024}, bl{W, 1024};
;     gemm_mainloop_p(acc, al, bl, m0, n0, mtn * 256, ntn * 256, 1024, smem, gp);
;     gp.primed = more;
.Lff1_skipdma:
	ds_read_b128 v[174:177], v136 offset:32768
	ds_read_b128 v[178:181], v137 offset:32768
	ds_read_b128 v[182:185], v136 offset:36864
	ds_read_b128 v[186:189], v137 offset:36864
	ds_read_b128 v[190:193], v136 offset:40960
	ds_read_b128 v[194:197], v137 offset:40960
	ds_read_b128 v[198:201], v136 offset:45056
	ds_read_b128 v[222:225], v137 offset:45056
	ds_read_b128 v[226:229], v140 offset:32768
	ds_read_b128 v[230:233], v141 offset:32768
	ds_read_b128 v[234:237], v140 offset:36864
	ds_read_b128 v[238:241], v141 offset:36864
	s_waitcnt lgkmcnt(3)
	v_mfma_f32_32x32x16_bf16 v[112:127], v[226:229], v[174:177], v[112:127]
	s_waitcnt lgkmcnt(1)
	v_mfma_f32_32x32x16_bf16 v[96:111], v[234:237], v[174:177], v[96:111]
	v_mfma_f32_32x32x16_bf16 v[80:95], v[226:229], v[182:185], v[80:95]
	v_mfma_f32_32x32x16_bf16 v[64:79], v[234:237], v[182:185], v[64:79]
	v_mfma_f32_32x32x16_bf16 v[48:63], v[226:229], v[190:193], v[48:63]
	v_mfma_f32_32x32x16_bf16 v[32:47], v[234:237], v[190:193], v[32:47]
	v_mfma_f32_32x32x16_bf16 v[16:31], v[226:229], v[198:201], v[16:31]
	v_mfma_f32_32x32x16_bf16 v[0:15], v[234:237], v[198:201], v[0:15]
	ds_read_b128 v[174:177], v138 offset:32768
	ds_read_b128 v[182:185], v138 offset:36864
	ds_read_b128 v[190:193], v138 offset:40960
	ds_read_b128 v[198:201], v138 offset:45056
	ds_read_b128 v[226:229], v142 offset:32768
	ds_read_b128 v[234:237], v142 offset:36864
	v_mfma_f32_32x32x16_bf16 v[112:127], v[230:233], v[178:181], v[112:127]
	s_waitcnt lgkmcnt(6)
	v_mfma_f32_32x32x16_bf16 v[96:111], v[238:241], v[178:181], v[96:111]
	v_mfma_f32_32x32x16_bf16 v[80:95], v[230:233], v[186:189], v[80:95]
	v_mfma_f32_32x32x16_bf16 v[64:79], v[238:241], v[186:189], v[64:79]
	v_mfma_f32_32x32x16_bf16 v[48:63], v[230:233], v[194:197], v[48:63]
	v_mfma_f32_32x32x16_bf16 v[32:47], v[238:241], v[194:197], v[32:47]
	v_mfma_f32_32x32x16_bf16 v[16:31], v[230:233], v[222:225], v[16:31]
	v_mfma_f32_32x32x16_bf16 v[0:15], v[238:241], v[222:225], v[0:15]
	ds_read_b128 v[178:181], v139 offset:32768
	ds_read_b128 v[186:189], v139 offset:36864
	ds_read_b128 v[194:197], v139 offset:40960
	ds_read_b128 v[222:225], v139 offset:45056
	ds_read_b128 v[230:233], v143 offset:32768
	ds_read_b128 v[238:241], v143 offset:36864
	s_waitcnt lgkmcnt(6)
	v_mfma_f32_32x32x16_bf16 v[112:127], v[226:229], v[174:177], v[112:127]
	v_mfma_f32_32x32x16_bf16 v[96:111], v[234:237], v[174:177], v[96:111]
	v_mfma_f32_32x32x16_bf16 v[80:95], v[226:229], v[182:185], v[80:95]
	v_mfma_f32_32x32x16_bf16 v[64:79], v[234:237], v[182:185], v[64:79]
	v_mfma_f32_32x32x16_bf16 v[48:63], v[226:229], v[190:193], v[48:63]
	v_mfma_f32_32x32x16_bf16 v[32:47], v[234:237], v[190:193], v[32:47]
	v_mfma_f32_32x32x16_bf16 v[16:31], v[226:229], v[198:201], v[16:31]
	v_mfma_f32_32x32x16_bf16 v[0:15], v[234:237], v[198:201], v[0:15]
	s_waitcnt lgkmcnt(1)
	v_mfma_f32_32x32x16_bf16 v[112:127], v[230:233], v[178:181], v[112:127]
	s_waitcnt lgkmcnt(0)
	v_mfma_f32_32x32x16_bf16 v[96:111], v[238:241], v[178:181], v[96:111]
	v_mfma_f32_32x32x16_bf16 v[80:95], v[230:233], v[186:189], v[80:95]
	v_mfma_f32_32x32x16_bf16 v[64:79], v[238:241], v[186:189], v[64:79]
	v_mfma_f32_32x32x16_bf16 v[48:63], v[230:233], v[194:197], v[48:63]
	v_mfma_f32_32x32x16_bf16 v[32:47], v[238:241], v[194:197], v[32:47]
	v_mfma_f32_32x32x16_bf16 v[16:31], v[230:233], v[222:225], v[16:31]
	v_mfma_f32_32x32x16_bf16 v[0:15], v[238:241], v[222:225], v[0:15]
	s_add_i32 s17, s17, 1
	s_waitcnt vmcnt(0)
	s_cmp_lg_u32 s17, 8
	s_barrier
	s_cbranch_scc1 .Lff1_kloop
	s_and_b64 vcc, exec, s[0:1]
	s_cbranch_vccz .Lff1_nomore
	s_lshl_b32 s7, s11, 8
	s_lshl_b32 s8, s12, 8
	v_add_u32_e32 v128, s7, v150
	v_lshlrev_b32_e32 v128, 11, v128
	v_add_u32_e32 v128, v128, v151
	v_add_u32_e32 v129, 0x4000, v128
	v_add_u32_e32 v130, 0x8000, v128
	v_add_u32_e32 v131, 0xc000, v128
	v_xor_b32_e32 v129, 0x40, v129
	v_xor_b32_e32 v131, 0x40, v131
	v_add_u32_e32 v132, s8, v150
	v_lshlrev_b32_e32 v132, 11, v132
	v_add_u32_e32 v132, v132, v151
	v_add_u32_e32 v133, 0x4000, v132
	v_add_u32_e32 v134, 0x8000, v132
	v_add_u32_e32 v135, 0xc000, v132
	v_xor_b32_e32 v133, 0x40, v133
	v_xor_b32_e32 v135, 0x40, v135
	s_mov_b64 s[22:23], s[18:19]
	s_mov_b64 s[14:15], s[20:21]
	s_add_u32 m0, s13, 0x0
	s_nop 0
	global_load_lds_dwordx4 v128, s[22:23]
	s_add_u32 m0, m0, 0x400
	s_nop 0
	global_load_lds_dwordx4 v129, s[22:23]
	s_add_u32 m0, m0, 0x400
	s_nop 0
	global_load_lds_dwordx4 v130, s[22:23]
	s_add_u32 m0, m0, 0x400
	s_nop 0
	global_load_lds_dwordx4 v131, s[22:23]
	s_add_u32 m0, s13, 0x10000
	s_nop 0
	global_load_lds_dwordx4 v132, s[14:15]
	s_add_u32 m0, m0, 0x400
	s_nop 0
	global_load_lds_dwordx4 v133, s[14:15]
	s_add_u32 m0, m0, 0x400
	s_nop 0
	global_load_lds_dwordx4 v134, s[14:15]
	s_add_u32 m0, m0, 0x400
	s_nop 0
	global_load_lds_dwordx4 v135, s[14:15]
; DEV u16 f2bf(float f) { return (u16)(pack2(f, f) & 0xffffu); }
; template <class F>
; DEV void acc_foreach(Acc& acc, int m0, int n0, F f) {
;   asm volatile("s_nop 7\n\ts_nop 7\n\ts_nop 3" ::: "memory");
;   const int tid = tidx_full();
;   const int wave = tid >> 6, lane = tid & 63;
;   const int wm = (wave >> 2) * 128, wn = (wave & 3) * 64;
;   const int lr = lane & 31, lh = lane >> 5;
; #pragma unroll
;   for (int i = 0; i < 4; ++i)
; #pragma unroll
;     for (int j = 0; j < 2; ++j)
; #pragma unroll
;       for (int r = 0; r < 16; ++r) {
;         const int m = m0 + wm + 32 * i + (r & 3) + 8 * (r >> 2) + 4 * lh;
;         const int n = n0 + wn + 32 * j + lr;
;         float v = acc[i][j][r];
;         f(m, n, v);
;         acc[i][j][r] = v;
;       }
; DEV void phase_ff1(const Params& p, int g, char* smem) {
;     ...
;     acc_foreach(acc, m0, n0, [&](int m, int n, float& v) {
;       const float r = fmaxf(v, 0.f);
;       AB[(size_t)m * 4096 + n] = f2bf(r * r);
;     });
.Lff1_nomore:
	s_nop 7
	s_nop 7
	s_nop 3
	v_and_b32_e32 v160, 63, v202
	v_lshrrev_b32_e32 v161, 6, v202
	v_and_b32_e32 v164, 3, v161
	v_lshlrev_b32_e32 v164, 13, v164
	v_add_u32_e32 v164, 0x8000, v164
	v_lshrrev_b32_e32 v160, 2, v161
	v_lshl_add_u32 v164, v160, 16, v164
	v_and_b32_e32 v160, 63, v202
	v_and_b32_e32 v166, 31, v160
	v_lshrrev_b32_e32 v167, 5, v160
	v_lshlrev_b32_e32 v168, 7, v166
	v_lshl_add_u32 v168, v167, 3, v168
	v_add_u32_e32 v168, v164, v168
	v_and_b32_e32 v166, 7, v166
	v_lshlrev_b32_e32 v166, 4, v166
	v_add_u32_e32 v170, v168, v166
	v_xor_b32_e32 v167, 0x10, v166
	v_add_u32_e32 v171, v168, v167
	v_xor_b32_e32 v167, 0x20, v166
	v_add_u32_e32 v172, v168, v167
	v_xor_b32_e32 v167, 0x30, v166
	v_add_u32_e32 v173, v168, v167
	v_xor_b32_e32 v167, 0x40, v166
	v_add_u32_e32 v174, v168, v167
	v_xor_b32_e32 v167, 0x50, v166
	v_add_u32_e32 v175, v168, v167
	v_xor_b32_e32 v167, 0x60, v166
	v_add_u32_e32 v176, v168, v167
	v_xor_b32_e32 v167, 0x70, v166
	v_add_u32_e32 v177, v168, v167
	v_lshrrev_b32_e32 v166, 3, v160
	v_and_b32_e32 v167, 7, v160
	v_lshrrev_b32_e32 v169, 2, v161
	v_lshl_add_u32 v169, v169, 7, v166
	v_add_u32_e32 v169, s5, v169
	v_mul_u32_u24_e32 v169, 0x2000, v169
	v_and_b32_e32 v168, 3, v161
	v_lshlrev_b32_e32 v168, 3, v168
	v_add_u32_e32 v168, v168, v167
	v_lshl_add_u32 v169, v168, 4, v169
	s_lshl_b32 s100, s4, 1
	v_add_u32_e32 v169, s100, v169
	v_xor_b32_e32 v167, v166, v167
	v_lshlrev_b32_e32 v167, 4, v167
	v_lshl_add_u32 v168, v166, 7, v167
	v_add_u32_e32 v168, v164, v168
	v_max_f32_e32 v112, 0, v112
	v_max_f32_e32 v113, 0, v113
	v_max_f32_e32 v114, 0, v114
	v_max_f32_e32 v115, 0, v115
	v_mul_f32_e32 v112, v112, v112
	v_mul_f32_e32 v113, v113, v113
	v_mul_f32_e32 v114, v114, v114
	v_mul_f32_e32 v115, v115, v115
	v_cvt_pk_bf16_f32 v112, v112, v113
	v_cvt_pk_bf16_f32 v113, v114, v115
	ds_write_b64 v170, v[112:113]
	v_max_f32_e32 v116, 0, v116
	v_max_f32_e32 v117, 0, v117
	v_max_f32_e32 v118, 0, v118
	v_max_f32_e32 v119, 0, v119
	v_mul_f32_e32 v116, v116, v116
	v_mul_f32_e32 v117, v117, v117
	v_mul_f32_e32 v118, v118, v118
	v_mul_f32_e32 v119, v119, v119
	v_cvt_pk_bf16_f32 v116, v116, v117
	v_cvt_pk_bf16_f32 v117, v118, v119
	ds_write_b64 v171, v[116:117]
	v_max_f32_e32 v120, 0, v120
	v_max_f32_e32 v121, 0, v121
	v_max_f32_e32 v122, 0, v122
	v_max_f32_e32 v123, 0, v123
	v_mul_f32_e32 v120, v120, v120
	v_mul_f32_e32 v121, v121, v121
	v_mul_f32_e32 v122, v122, v122
	v_mul_f32_e32 v123, v123, v123
	v_cvt_pk_bf16_f32 v120, v120, v121
	v_cvt_pk_bf16_f32 v121, v122, v123
	ds_write_b64 v172, v[120:121]
	v_max_f32_e32 v124, 0, v124
	v_max_f32_e32 v125, 0, v125
	v_max_f32_e32 v126, 0, v126
	v_max_f32_e32 v127, 0, v127
	v_mul_f32_e32 v124, v124, v124
	v_mul_f32_e32 v125, v125, v125
	v_mul_f32_e32 v126, v126, v126
	v_mul_f32_e32 v127, v127, v127
	v_cvt_pk_bf16_f32 v124, v124, v125
	v_cvt_pk_bf16_f32 v125, v126, v127
	ds_write_b64 v173, v[124:125]
	v_max_f32_e32 v96, 0, v96
	v_max_f32_e32 v97, 0, v97
	v_max_f32_e32 v98, 0, v98
	v_max_f32_e32 v99, 0, v99
	v_mul_f32_e32 v96, v96, v96
	v_mul_f32_e32 v97, v97, v97
	v_mul_f32_e32 v98, v98, v98
	v_mul_f32_e32 v99, v99, v99
	v_cvt_pk_bf16_f32 v96, v96, v97
	v_cvt_pk_bf16_f32 v97, v98, v99
	ds_write_b64 v174, v[96:97]
	v_max_f32_e32 v100, 0, v100
	v_max_f32_e32 v101, 0, v101
	v_max_f32_e32 v102, 0, v102
	v_max_f32_e32 v103, 0, v103
	v_mul_f32_e32 v100, v100, v100
	v_mul_f32_e32 v101, v101, v101
	v_mul_f32_e32 v102, v102, v102
	v_mul_f32_e32 v103, v103, v103
	v_cvt_pk_bf16_f32 v100, v100, v101
	v_cvt_pk_bf16_f32 v101, v102, v103
	ds_write_b64 v175, v[100:101]
	v_max_f32_e32 v104, 0, v104
	v_max_f32_e32 v105, 0, v105
	v_max_f32_e32 v106, 0, v106
	v_max_f32_e32 v107, 0, v107
	v_mul_f32_e32 v104, v104, v104
	v_mul_f32_e32 v105, v105, v105
	v_mul_f32_e32 v106, v106, v106
	v_mul_f32_e32 v107, v107, v107
	v_cvt_pk_bf16_f32 v104, v104, v105
	v_cvt_pk_bf16_f32 v105, v106, v107
	ds_write_b64 v176, v[104:105]
	v_max_f32_e32 v108, 0, v108
	v_max_f32_e32 v109, 0, v109
	v_max_f32_e32 v110, 0, v110
	v_max_f32_e32 v111, 0, v111
	v_mul_f32_e32 v108, v108, v108
	v_mul_f32_e32 v109, v109, v109
	v_mul_f32_e32 v110, v110, v110
	v_mul_f32_e32 v111, v111, v111
	v_cvt_pk_bf16_f32 v108, v108, v109
	v_cvt_pk_bf16_f32 v109, v110, v111
	ds_write_b64 v177, v[108:109]
	v_max_f32_e32 v80, 0, v80
	v_max_f32_e32 v81, 0, v81
	v_max_f32_e32 v82, 0, v82
	v_max_f32_e32 v83, 0, v83
	v_mul_f32_e32 v80, v80, v80
	v_mul_f32_e32 v81, v81, v81
	v_mul_f32_e32 v82, v82, v82
	v_mul_f32_e32 v83, v83, v83
	v_cvt_pk_bf16_f32 v80, v80, v81
	v_cvt_pk_bf16_f32 v81, v82, v83
	ds_write_b64 v170, v[80:81] offset:4096
	v_max_f32_e32 v84, 0, v84
	v_max_f32_e32 v85, 0, v85
	v_max_f32_e32 v86, 0, v86
	v_max_f32_e32 v87, 0, v87
	v_mul_f32_e32 v84, v84, v84
	v_mul_f32_e32 v85, v85, v85
	v_mul_f32_e32 v86, v86, v86
	v_mul_f32_e32 v87, v87, v87
	v_cvt_pk_bf16_f32 v84, v84, v85
	v_cvt_pk_bf16_f32 v85, v86, v87
	ds_write_b64 v171, v[84:85] offset:4096
	v_max_f32_e32 v88, 0, v88
	v_max_f32_e32 v89, 0, v89
	v_max_f32_e32 v90, 0, v90
	v_max_f32_e32 v91, 0, v91
	v_mul_f32_e32 v88, v88, v88
	v_mul_f32_e32 v89, v89, v89
	v_mul_f32_e32 v90, v90, v90
	v_mul_f32_e32 v91, v91, v91
	v_cvt_pk_bf16_f32 v88, v88, v89
	v_cvt_pk_bf16_f32 v89, v90, v91
	ds_write_b64 v172, v[88:89] offset:4096
	v_max_f32_e32 v92, 0, v92
	v_max_f32_e32 v93, 0, v93
	v_max_f32_e32 v94, 0, v94
	v_max_f32_e32 v95, 0, v95
	v_mul_f32_e32 v92, v92, v92
	v_mul_f32_e32 v93, v93, v93
	v_mul_f32_e32 v94, v94, v94
	v_mul_f32_e32 v95, v95, v95
	v_cvt_pk_bf16_f32 v92, v92, v93
	v_cvt_pk_bf16_f32 v93, v94, v95
	ds_write_b64 v173, v[92:93] offset:4096
	v_max_f32_e32 v64, 0, v64
	v_max_f32_e32 v65, 0, v65
	v_max_f32_e32 v66, 0, v66
	v_max_f32_e32 v67, 0, v67
	v_mul_f32_e32 v64, v64, v64
	v_mul_f32_e32 v65, v65, v65
	v_mul_f32_e32 v66, v66, v66
	v_mul_f32_e32 v67, v67, v67
	v_cvt_pk_bf16_f32 v64, v64, v65
	v_cvt_pk_bf16_f32 v65, v66, v67
	ds_write_b64 v174, v[64:65] offset:4096
	v_max_f32_e32 v68, 0, v68
	v_max_f32_e32 v69, 0, v69
	v_max_f32_e32 v70, 0, v70
	v_max_f32_e32 v71, 0, v71
	v_mul_f32_e32 v68, v68, v68
	v_mul_f32_e32 v69, v69, v69
	v_mul_f32_e32 v70, v70, v70
	v_mul_f32_e32 v71, v71, v71
	v_cvt_pk_bf16_f32 v68, v68, v69
	v_cvt_pk_bf16_f32 v69, v70, v71
	ds_write_b64 v175, v[68:69] offset:4096
	v_max_f32_e32 v72, 0, v72
	v_max_f32_e32 v73, 0, v73
	v_max_f32_e32 v74, 0, v74
	v_max_f32_e32 v75, 0, v75
	v_mul_f32_e32 v72, v72, v72
	v_mul_f32_e32 v73, v73, v73
	v_mul_f32_e32 v74, v74, v74
	v_mul_f32_e32 v75, v75, v75
	v_cvt_pk_bf16_f32 v72, v72, v73
	v_cvt_pk_bf16_f32 v73, v74, v75
	ds_write_b64 v176, v[72:73] offset:4096
	v_max_f32_e32 v76, 0, v76
	v_max_f32_e32 v77, 0, v77
	v_max_f32_e32 v78, 0, v78
	v_max_f32_e32 v79, 0, v79
	v_mul_f32_e32 v76, v76, v76
	v_mul_f32_e32 v77, v77, v77
	v_mul_f32_e32 v78, v78, v78
	v_mul_f32_e32 v79, v79, v79
	v_cvt_pk_bf16_f32 v76, v76, v77
	v_cvt_pk_bf16_f32 v77, v78, v79
	ds_write_b64 v177, v[76:77] offset:4096
	s_waitcnt lgkmcnt(0)
; DEV u16 f2bf(float f) { return (u16)(pack2(f, f) & 0xffffu); }
; DEV void phase_ff1(const Params& p, int g, char* smem) {
;     ...
;     acc_foreach(acc, m0, n0, [&](int m, int n, float& v) {
;       const float r = fmaxf(v, 0.f);
;       AB[(size_t)m * 4096 + n] = f2bf(r * r);
;     });
	ds_read_b128 v[96:99], v168
	ds_read_b128 v[100:103], v168 offset:1024
	ds_read_b128 v[104:107], v168 offset:2048
	ds_read_b128 v[108:111], v168 offset:3072
	ds_read_b128 v[112:115], v168 offset:4096
	ds_read_b128 v[116:119], v168 offset:5120
	ds_read_b128 v[120:123], v168 offset:6144
	ds_read_b128 v[124:127], v168 offset:7168
	s_waitcnt lgkmcnt(7)
	global_store_dwordx4 v169, v[96:99], s[74:75]
	v_add_u32_e32 v169, 0x10000, v169
	s_waitcnt lgkmcnt(6)
	global_store_dwordx4 v169, v[100:103], s[74:75]
	v_add_u32_e32 v169, 0x10000, v169
	s_waitcnt lgkmcnt(5)
	global_store_dwordx4 v169, v[104:107], s[74:75]
	v_add_u32_e32 v169, 0x10000, v169
	s_waitcnt lgkmcnt(4)
	global_store_dwordx4 v169, v[108:111], s[74:75]
	v_add_u32_e32 v169, 0x10000, v169
	s_waitcnt lgkmcnt(3)
	global_store_dwordx4 v169, v[112:115], s[74:75]
	v_add_u32_e32 v169, 0x10000, v169
	s_waitcnt lgkmcnt(2)
	global_store_dwordx4 v169, v[116:119], s[74:75]
	v_add_u32_e32 v169, 0x10000, v169
	s_waitcnt lgkmcnt(1)
	global_store_dwordx4 v169, v[120:123], s[74:75]
	v_add_u32_e32 v169, 0x10000, v169
	s_waitcnt lgkmcnt(0)
	global_store_dwordx4 v169, v[124:127], s[74:75]
	v_add_u32_e32 v169, 0x10000, v169
	v_max_f32_e32 v48, 0, v48
	v_max_f32_e32 v49, 0, v49
	v_max_f32_e32 v50, 0, v50
	v_max_f32_e32 v51, 0, v51
	v_mul_f32_e32 v48, v48, v48
	v_mul_f32_e32 v49, v49, v49
	v_mul_f32_e32 v50, v50, v50
	v_mul_f32_e32 v51, v51, v51
	v_cvt_pk_bf16_f32 v48, v48, v49
	v_cvt_pk_bf16_f32 v49, v50, v51
	ds_write_b64 v170, v[48:49]
	v_max_f32_e32 v52, 0, v52
	v_max_f32_e32 v53, 0, v53
	v_max_f32_e32 v54, 0, v54
	v_max_f32_e32 v55, 0, v55
	v_mul_f32_e32 v52, v52, v52
	v_mul_f32_e32 v53, v53, v53
	v_mul_f32_e32 v54, v54, v54
	v_mul_f32_e32 v55, v55, v55
	v_cvt_pk_bf16_f32 v52, v52, v53
	v_cvt_pk_bf16_f32 v53, v54, v55
	ds_write_b64 v171, v[52:53]
	v_max_f32_e32 v56, 0, v56
	v_max_f32_e32 v57, 0, v57
	v_max_f32_e32 v58, 0, v58
	v_max_f32_e32 v59, 0, v59
	v_mul_f32_e32 v56, v56, v56
	v_mul_f32_e32 v57, v57, v57
	v_mul_f32_e32 v58, v58, v58
	v_mul_f32_e32 v59, v59, v59
	v_cvt_pk_bf16_f32 v56, v56, v57
	v_cvt_pk_bf16_f32 v57, v58, v59
	ds_write_b64 v172, v[56:57]
	v_max_f32_e32 v60, 0, v60
	v_max_f32_e32 v61, 0, v61
	v_max_f32_e32 v62, 0, v62
	v_max_f32_e32 v63, 0, v63
	v_mul_f32_e32 v60, v60, v60
	v_mul_f32_e32 v61, v61, v61
	v_mul_f32_e32 v62, v62, v62
	v_mul_f32_e32 v63, v63, v63
	v_cvt_pk_bf16_f32 v60, v60, v61
	v_cvt_pk_bf16_f32 v61, v62, v63
	ds_write_b64 v173, v[60:61]
	v_max_f32_e32 v32, 0, v32
	v_max_f32_e32 v33, 0, v33
	v_max_f32_e32 v34, 0, v34
	v_max_f32_e32 v35, 0, v35
	v_mul_f32_e32 v32, v32, v32
	v_mul_f32_e32 v33, v33, v33
	v_mul_f32_e32 v34, v34, v34
	v_mul_f32_e32 v35, v35, v35
	v_cvt_pk_bf16_f32 v32, v32, v33
	v_cvt_pk_bf16_f32 v33, v34, v35
	ds_write_b64 v174, v[32:33]
	v_max_f32_e32 v36, 0, v36
	v_max_f32_e32 v37, 0, v37
	v_max_f32_e32 v38, 0, v38
	v_max_f32_e32 v39, 0, v39
	v_mul_f32_e32 v36, v36, v36
	v_mul_f32_e32 v37, v37, v37
	v_mul_f32_e32 v38, v38, v38
	v_mul_f32_e32 v39, v39, v39
	v_cvt_pk_bf16_f32 v36, v36, v37
	v_cvt_pk_bf16_f32 v37, v38, v39
	ds_write_b64 v175, v[36:37]
	v_max_f32_e32 v40, 0, v40
	v_max_f32_e32 v41, 0, v41
	v_max_f32_e32 v42, 0, v42
	v_max_f32_e32 v43, 0, v43
	v_mul_f32_e32 v40, v40, v40
	v_mul_f32_e32 v41, v41, v41
	v_mul_f32_e32 v42, v42, v42
	v_mul_f32_e32 v43, v43, v43
	v_cvt_pk_bf16_f32 v40, v40, v41
	v_cvt_pk_bf16_f32 v41, v42, v43
	ds_write_b64 v176, v[40:41]
	v_max_f32_e32 v44, 0, v44
	v_max_f32_e32 v45, 0, v45
	v_max_f32_e32 v46, 0, v46
	v_max_f32_e32 v47, 0, v47
	v_mul_f32_e32 v44, v44, v44
	v_mul_f32_e32 v45, v45, v45
	v_mul_f32_e32 v46, v46, v46
	v_mul_f32_e32 v47, v47, v47
	v_cvt_pk_bf16_f32 v44, v44, v45
	v_cvt_pk_bf16_f32 v45, v46, v47
	ds_write_b64 v177, v[44:45]
	v_max_f32_e32 v16, 0, v16
	v_max_f32_e32 v17, 0, v17
	v_max_f32_e32 v18, 0, v18
	v_max_f32_e32 v19, 0, v19
	v_mul_f32_e32 v16, v16, v16
	v_mul_f32_e32 v17, v17, v17
	v_mul_f32_e32 v18, v18, v18
	v_mul_f32_e32 v19, v19, v19
	v_cvt_pk_bf16_f32 v16, v16, v17
	v_cvt_pk_bf16_f32 v17, v18, v19
	ds_write_b64 v170, v[16:17] offset:4096
	v_max_f32_e32 v20, 0, v20
	v_max_f32_e32 v21, 0, v21
	v_max_f32_e32 v22, 0, v22
	v_max_f32_e32 v23, 0, v23
	v_mul_f32_e32 v20, v20, v20
	v_mul_f32_e32 v21, v21, v21
	v_mul_f32_e32 v22, v22, v22
	v_mul_f32_e32 v23, v23, v23
	v_cvt_pk_bf16_f32 v20, v20, v21
	v_cvt_pk_bf16_f32 v21, v22, v23
	ds_write_b64 v171, v[20:21] offset:4096
	v_max_f32_e32 v24, 0, v24
	v_max_f32_e32 v25, 0, v25
	v_max_f32_e32 v26, 0, v26
	v_max_f32_e32 v27, 0, v27
	v_mul_f32_e32 v24, v24, v24
	v_mul_f32_e32 v25, v25, v25
	v_mul_f32_e32 v26, v26, v26
	v_mul_f32_e32 v27, v27, v27
	v_cvt_pk_bf16_f32 v24, v24, v25
	v_cvt_pk_bf16_f32 v25, v26, v27
	ds_write_b64 v172, v[24:25] offset:4096
	v_max_f32_e32 v28, 0, v28
	v_max_f32_e32 v29, 0, v29
	v_max_f32_e32 v30, 0, v30
	v_max_f32_e32 v31, 0, v31
	v_mul_f32_e32 v28, v28, v28
	v_mul_f32_e32 v29, v29, v29
	v_mul_f32_e32 v30, v30, v30
	v_mul_f32_e32 v31, v31, v31
	v_cvt_pk_bf16_f32 v28, v28, v29
	v_cvt_pk_bf16_f32 v29, v30, v31
	ds_write_b64 v173, v[28:29] offset:4096
	v_max_f32_e32 v0, 0, v0
	v_max_f32_e32 v1, 0, v1
	v_max_f32_e32 v2, 0, v2
	v_max_f32_e32 v3, 0, v3
	v_mul_f32_e32 v0, v0, v0
	v_mul_f32_e32 v1, v1, v1
	v_mul_f32_e32 v2, v2, v2
	v_mul_f32_e32 v3, v3, v3
	v_cvt_pk_bf16_f32 v0, v0, v1
	v_cvt_pk_bf16_f32 v1, v2, v3
	ds_write_b64 v174, v[0:1] offset:4096
	v_max_f32_e32 v4, 0, v4
	v_max_f32_e32 v5, 0, v5
	v_max_f32_e32 v6, 0, v6
	v_max_f32_e32 v7, 0, v7
	v_mul_f32_e32 v4, v4, v4
	v_mul_f32_e32 v5, v5, v5
	v_mul_f32_e32 v6, v6, v6
	v_mul_f32_e32 v7, v7, v7
	v_cvt_pk_bf16_f32 v4, v4, v5
	v_cvt_pk_bf16_f32 v5, v6, v7
	ds_write_b64 v175, v[4:5] offset:4096
	v_max_f32_e32 v8, 0, v8
	v_max_f32_e32 v9, 0, v9
	v_max_f32_e32 v10, 0, v10
	v_max_f32_e32 v11, 0, v11
	v_mul_f32_e32 v8, v8, v8
	v_mul_f32_e32 v9, v9, v9
	v_mul_f32_e32 v10, v10, v10
	v_mul_f32_e32 v11, v11, v11
	v_cvt_pk_bf16_f32 v8, v8, v9
	v_cvt_pk_bf16_f32 v9, v10, v11
	ds_write_b64 v176, v[8:9] offset:4096
	v_max_f32_e32 v12, 0, v12
	v_max_f32_e32 v13, 0, v13
	v_max_f32_e32 v14, 0, v14
	v_max_f32_e32 v15, 0, v15
	v_mul_f32_e32 v12, v12, v12
	v_mul_f32_e32 v13, v13, v13
	v_mul_f32_e32 v14, v14, v14
	v_mul_f32_e32 v15, v15, v15
	v_cvt_pk_bf16_f32 v12, v12, v13
	v_cvt_pk_bf16_f32 v13, v14, v15
	ds_write_b64 v177, v[12:13] offset:4096
	s_waitcnt lgkmcnt(0)
; DEV u16 f2bf(float f) { return (u16)(pack2(f, f) & 0xffffu); }
; DEV void phase_ff1(const Params& p, int g, char* smem) {
;     ...
;     acc_foreach(acc, m0, n0, [&](int m, int n, float& v) {
;       const float r = fmaxf(v, 0.f);
;       AB[(size_t)m * 4096 + n] = f2bf(r * r);
;     });
;   }
	ds_read_b128 v[64:67], v168
	ds_read_b128 v[68:71], v168 offset:1024
	ds_read_b128 v[72:75], v168 offset:2048
	ds_read_b128 v[76:79], v168 offset:3072
	ds_read_b128 v[80:83], v168 offset:4096
	ds_read_b128 v[84:87], v168 offset:5120
	ds_read_b128 v[88:91], v168 offset:6144
	ds_read_b128 v[92:95], v168 offset:7168
	s_waitcnt lgkmcnt(7)
	global_store_dwordx4 v169, v[64:67], s[74:75]
	v_add_u32_e32 v169, 0x10000, v169
	s_waitcnt lgkmcnt(6)
	global_store_dwordx4 v169, v[68:71], s[74:75]
	v_add_u32_e32 v169, 0x10000, v169
	s_waitcnt lgkmcnt(5)
	global_store_dwordx4 v169, v[72:75], s[74:75]
	v_add_u32_e32 v169, 0x10000, v169
	s_waitcnt lgkmcnt(4)
	global_store_dwordx4 v169, v[76:79], s[74:75]
	v_add_u32_e32 v169, 0x10000, v169
	s_waitcnt lgkmcnt(3)
	global_store_dwordx4 v169, v[80:83], s[74:75]
	v_add_u32_e32 v169, 0x10000, v169
	s_waitcnt lgkmcnt(2)
	global_store_dwordx4 v169, v[84:87], s[74:75]
	v_add_u32_e32 v169, 0x10000, v169
	s_waitcnt lgkmcnt(1)
	global_store_dwordx4 v169, v[88:91], s[74:75]
	v_add_u32_e32 v169, 0x10000, v169
	s_waitcnt lgkmcnt(0)
	s_barrier
	global_store_dwordx4 v169, v[92:95], s[74:75]
	v_add_u32_e32 v169, 0x10000, v169
	s_mov_b64 s[4:5], 0
	s_branch .LBB0_1110
